# baseline (speedup 1.0000x reference)
; #define PG8_STAGE(bufoff, gbase, voff) do { _Pragma("unroll") for (int _i = 0; _i < 2; ++_i) \
;         __builtin_amdgcn_global_load_lds((const unsigned*)((const char*)(gbase) + (voff)[_i]), (PG8_LAS unsigned*)(lds + (bufoff) + ldsw + _i * 8192), 16, 0, 0); } while (0)
; #define PG8_LDA(dst, b, h) do { _Pragma("unroll") for (int m = 0; m < 4; ++m) _Pragma("unroll") for (int k = 0; k < 2; ++k) dst[m][k] = *(const PG8_LAS bf16x8*)(lds + PG8_SA(b, h) + aoff + m * 2048 + k * 1024); } while (0)
; #define PG8_LDB(dst, b, h) do { _Pragma("unroll") for (int n = 0; n < 2; ++n) _Pragma("unroll") for (int k = 0; k < 2; ++k) dst[n][k] = *(const PG8_LAS bf16x8*)(lds + PG8_SB(b, h) + boff + n * 2048 + k * 1024); } while (0)
; #define PG8_MMA(ai, bj, At, Bt) do { __builtin_amdgcn_s_setprio(1); _Pragma("unroll") for (int m = 0; m < 4; ++m) _Pragma("unroll") for (int n = 0; n < 2; ++n) _Pragma("unroll") for (int k = 0; k < 2; ++k) \
;         acc[ai][bj][m][n] = __builtin_amdgcn_mfma_f32_16x16x32_bf16(Bt[n][k], At[m][k], acc[ai][bj][m][n], 0, 0, 0); __builtin_amdgcn_s_setprio(0); } while (0)
; #define PG8_WAIT_V(n) asm volatile("s_waitcnt vmcnt(" #n ")" ::: "memory")
; #define PG8_WAIT_L(n) asm volatile("s_waitcnt lgkmcnt(" #n ")" ::: "memory")
; #define PG8_BAR __builtin_amdgcn_s_barrier()
; #define PG8_SCHED __builtin_amdgcn_sched_barrier(0)
; template <class Epi, class Sched, bool ALIGN_EPI = false, bool SP2 = false>
; __device__ __forceinline__ void gemm_phase(PG8_LAS unsigned char* lds, const Gemm g, const Sched& S, const Epi& E, const int tid) {
;     ...
;             PG8_WAIT_V(8); PG8_WAIT_L(0); PG8_BAR; PG8_MMA(1, 0, At, B0); PG8_MMA(1, 1, At, B1); PG8_BAR; PG8_SCHED;
;             PG8_LDB(B0, 1, 0); PG8_LDB(B1, 1, 1); PG8_SCHED; PG8_LDA(At, 1, 0); PG8_STAGE(PG8_SA(0, 1), a2 + hstep, voffA);
;             PG8_WAIT_V(8); PG8_WAIT_L(0); PG8_BAR; PG8_MMA(0, 0, At, B0); PG8_MMA(0, 1, At, B1); PG8_BAR; PG8_SCHED;
.Lmy_wj_0:
	s_waitcnt lgkmcnt(0)
	s_barrier
	s_setprio 1
	s_waitcnt lgkmcnt(0)
	v_mfma_f32_16x16x32_bf16 v[60:63], v[138:141], v[188:191], 0
	v_mfma_f32_16x16x32_bf16 v[56:59], v[150:153], v[188:191], 0
	v_mfma_f32_16x16x32_bf16 v[44:47], v[138:141], v[208:211], 0
	v_mfma_f32_16x16x32_bf16 v[40:43], v[150:153], v[208:211], 0
	v_mfma_f32_16x16x32_bf16 v[28:31], v[138:141], v[218:221], 0
	v_mfma_f32_16x16x32_bf16 v[24:27], v[150:153], v[218:221], 0
	v_mfma_f32_16x16x32_bf16 v[12:15], v[138:141], v[226:229], 0
	v_mfma_f32_16x16x32_bf16 v[8:11], v[150:153], v[226:229], 0
	v_mfma_f32_16x16x32_bf16 v[60:63], v[146:149], v[192:195], v[60:63]
	v_mfma_f32_16x16x32_bf16 v[56:59], v[154:157], v[192:195], v[56:59]
	v_mfma_f32_16x16x32_bf16 v[44:47], v[146:149], v[214:217], v[44:47]
	v_mfma_f32_16x16x32_bf16 v[40:43], v[154:157], v[214:217], v[40:43]
	v_mfma_f32_16x16x32_bf16 v[28:31], v[146:149], v[222:225], v[28:31]
	v_mfma_f32_16x16x32_bf16 v[24:27], v[154:157], v[222:225], v[24:27]
	v_mfma_f32_16x16x32_bf16 v[12:15], v[146:149], v[230:233], v[12:15]
	v_mfma_f32_16x16x32_bf16 v[8:11], v[154:157], v[230:233], v[8:11]
	s_setprio 0
	s_setprio 1
	v_mfma_f32_16x16x32_bf16 v[52:55], v[162:165], v[188:191], 0
	v_mfma_f32_16x16x32_bf16 v[48:51], v[170:173], v[188:191], 0
	v_mfma_f32_16x16x32_bf16 v[36:39], v[162:165], v[208:211], 0
	v_mfma_f32_16x16x32_bf16 v[32:35], v[170:173], v[208:211], 0
	v_mfma_f32_16x16x32_bf16 v[20:23], v[162:165], v[218:221], 0
	v_mfma_f32_16x16x32_bf16 v[16:19], v[170:173], v[218:221], 0
	v_mfma_f32_16x16x32_bf16 v[4:7], v[162:165], v[226:229], 0
	v_mfma_f32_16x16x32_bf16 v[0:3], v[170:173], v[226:229], 0
	v_mfma_f32_16x16x32_bf16 v[52:55], v[166:169], v[192:195], v[52:55]
	v_mfma_f32_16x16x32_bf16 v[48:51], v[184:187], v[192:195], v[48:51]
	v_mfma_f32_16x16x32_bf16 v[36:39], v[166:169], v[214:217], v[36:39]
	v_mfma_f32_16x16x32_bf16 v[32:35], v[184:187], v[214:217], v[32:35]
	v_mfma_f32_16x16x32_bf16 v[20:23], v[166:169], v[222:225], v[20:23]
	v_mfma_f32_16x16x32_bf16 v[16:19], v[184:187], v[222:225], v[16:19]
	v_mfma_f32_16x16x32_bf16 v[4:7], v[166:169], v[230:233], v[4:7]
	v_mfma_f32_16x16x32_bf16 v[0:3], v[184:187], v[230:233], v[0:3]
	s_setprio 0
	s_barrier
	s_add_i32 s45, 0, 0x18000
	s_add_i32 s63, 0, 0x1c000
	v_add_u32_e32 v154, s45, v143
	v_add_u32_e32 v183, s63, v143
	ds_read_b128 v[138:141], v154
	ds_read_b128 v[146:149], v154 offset:1024
	ds_read_b128 v[150:153], v154 offset:2048
	ds_read_b128 v[154:157], v154 offset:3072
	ds_read_b128 v[162:165], v183
	ds_read_b128 v[166:169], v183 offset:1024
	ds_read_b128 v[170:173], v183 offset:2048
	ds_read_b128 v[184:187], v183 offset:3072
	s_add_u32 s30, s30, s12
	s_addc_u32 s31, s31, 0
	s_mov_b32 m0, s49
	v_lshl_add_u64 v[204:205], s[30:31], 0, v[128:129]
	ds_read_b128 v[188:191], v145 offset:32768
	ds_read_b128 v[192:195], v145 offset:33792
	ds_read_b128 v[208:211], v145 offset:34816
	ds_read_b128 v[214:217], v145 offset:35840
	ds_read_b128 v[218:221], v145 offset:36864
	ds_read_b128 v[222:225], v145 offset:37888
	ds_read_b128 v[226:229], v145 offset:38912
	ds_read_b128 v[230:233], v145 offset:39936
	global_load_lds_dwordx4 v[204:205], off
	v_lshl_add_u64 v[204:205], s[30:31], 0, v[130:131]
	s_mov_b32 m0, s50
	s_nop 0
	global_load_lds_dwordx4 v[204:205], off
	s_waitcnt vmcnt(8)
	s_waitcnt lgkmcnt(0)
	s_barrier
	s_setprio 1
	s_waitcnt lgkmcnt(0)
	v_mfma_f32_16x16x32_bf16 v[124:127], v[138:141], v[188:191], v[124:127]
	v_mfma_f32_16x16x32_bf16 v[120:123], v[150:153], v[188:191], v[120:123]
	v_mfma_f32_16x16x32_bf16 v[108:111], v[138:141], v[208:211], v[108:111]
	v_mfma_f32_16x16x32_bf16 v[104:107], v[150:153], v[208:211], v[104:107]
	v_mfma_f32_16x16x32_bf16 v[92:95], v[138:141], v[218:221], v[92:95]
	v_mfma_f32_16x16x32_bf16 v[88:91], v[150:153], v[218:221], v[88:91]
	v_mfma_f32_16x16x32_bf16 v[76:79], v[138:141], v[226:229], v[76:79]
	v_mfma_f32_16x16x32_bf16 v[72:75], v[150:153], v[226:229], v[72:75]
	v_mfma_f32_16x16x32_bf16 v[124:127], v[146:149], v[192:195], v[124:127]
	v_mfma_f32_16x16x32_bf16 v[120:123], v[154:157], v[192:195], v[120:123]
	v_mfma_f32_16x16x32_bf16 v[108:111], v[146:149], v[214:217], v[108:111]
	v_mfma_f32_16x16x32_bf16 v[104:107], v[154:157], v[214:217], v[104:107]
	v_mfma_f32_16x16x32_bf16 v[92:95], v[146:149], v[222:225], v[92:95]
	v_mfma_f32_16x16x32_bf16 v[88:91], v[154:157], v[222:225], v[88:91]
	v_mfma_f32_16x16x32_bf16 v[76:79], v[146:149], v[230:233], v[76:79]
	v_mfma_f32_16x16x32_bf16 v[72:75], v[154:157], v[230:233], v[72:75]
	s_setprio 0
	s_setprio 1
	v_mfma_f32_16x16x32_bf16 v[116:119], v[162:165], v[188:191], v[116:119]
	v_mfma_f32_16x16x32_bf16 v[112:115], v[170:173], v[188:191], v[112:115]
	v_mfma_f32_16x16x32_bf16 v[100:103], v[162:165], v[208:211], v[100:103]
	v_mfma_f32_16x16x32_bf16 v[96:99], v[170:173], v[208:211], v[96:99]
	v_mfma_f32_16x16x32_bf16 v[84:87], v[162:165], v[218:221], v[84:87]
	v_mfma_f32_16x16x32_bf16 v[80:83], v[170:173], v[218:221], v[80:83]
	v_mfma_f32_16x16x32_bf16 v[68:71], v[162:165], v[226:229], v[68:71]
	v_mfma_f32_16x16x32_bf16 v[64:67], v[170:173], v[226:229], v[64:67]
	v_mfma_f32_16x16x32_bf16 v[116:119], v[166:169], v[192:195], v[116:119]
	v_mfma_f32_16x16x32_bf16 v[112:115], v[184:187], v[192:195], v[112:115]
	v_mfma_f32_16x16x32_bf16 v[100:103], v[166:169], v[214:217], v[100:103]
	v_mfma_f32_16x16x32_bf16 v[96:99], v[184:187], v[214:217], v[96:99]
	v_mfma_f32_16x16x32_bf16 v[84:87], v[166:169], v[222:225], v[84:87]
	v_mfma_f32_16x16x32_bf16 v[80:83], v[184:187], v[222:225], v[80:83]
	v_mfma_f32_16x16x32_bf16 v[68:71], v[166:169], v[230:233], v[68:71]
	v_mfma_f32_16x16x32_bf16 v[64:67], v[184:187], v[230:233], v[64:67]
	s_setprio 0
	s_barrier
; #define PG8_STAGE(bufoff, gbase, voff) do { _Pragma("unroll") for (int _i = 0; _i < 2; ++_i) \
;         __builtin_amdgcn_global_load_lds((const unsigned*)((const char*)(gbase) + (voff)[_i]), (PG8_LAS unsigned*)(lds + (bufoff) + ldsw + _i * 8192), 16, 0, 0); } while (0)
; #define PG8_LDA(dst, b, h) do { _Pragma("unroll") for (int m = 0; m < 4; ++m) _Pragma("unroll") for (int k = 0; k < 2; ++k) dst[m][k] = *(const PG8_LAS bf16x8*)(lds + PG8_SA(b, h) + aoff + m * 2048 + k * 1024); } while (0)
; #define PG8_WAIT_V(n) asm volatile("s_waitcnt vmcnt(" #n ")" ::: "memory")
; #define PG8_WAIT_L(n) asm volatile("s_waitcnt lgkmcnt(" #n ")" ::: "memory")
; #define PG8_BAR __builtin_amdgcn_s_barrier()
; template <class Epi, class Sched, bool ALIGN_EPI = false, bool SP2 = false>
; __device__ __forceinline__ void gemm_phase(PG8_LAS unsigned char* lds, const Gemm g, const Sched& S, const Epi& E, const int tid) {
;     ...
;         for (int t = 0; t < nt; t += 2) {
;             const bool last = (t == nt - 2);
;             const char* a1 = cA + (size_t)(t + 1) * kstep;
;             const char* a2 = last ? nA : cA + (size_t)(t + 2) * kstep; const char* b2 = last ? nB : cB + (size_t)(t + 2) * kstep;
;             const char* a3 = a2 + kstep; const char* b3 = b2 + kstep;
;             if (last && has_next) S.a_ready(nxt);
;             if constexpr (SP2) {
;             PG8_LDB(B0, 0, 0); PG8_LDB(B1, 0, 1); PG8_SCHED; PG8_LDA(At, 0, 0); PG8_STAGE(PG8_SA(1, 1), a1 + hstep, voffA);
;             PG8_WAIT_V(8); PG8_WAIT_L(0); PG8_BAR; PG8_MMA(0, 0, At, B0); PG8_MMA(0, 1, At, B1); PG8_BAR; PG8_SCHED;
;             PG8_LDA(At, 0, 1); PG8_STAGE(PG8_SB(0, 0), b2, voffB); PG8_STAGE(PG8_SB(0, 1), b2 + hstep, voffB); PG8_STAGE(PG8_SA(0, 0), a2, voffA);
;             PG8_WAIT_V(8); PG8_WAIT_L(0); PG8_BAR; PG8_MMA(1, 0, At, B0); PG8_MMA(1, 1, At, B1); PG8_BAR; PG8_SCHED;
;             PG8_LDB(B0, 1, 0); PG8_LDB(B1, 1, 1); PG8_SCHED; PG8_LDA(At, 1, 0); PG8_STAGE(PG8_SA(0, 1), a2 + hstep, voffA);
;             PG8_WAIT_V(8); PG8_WAIT_L(0); PG8_BAR; PG8_MMA(0, 0, At, B0); PG8_MMA(0, 1, At, B1); PG8_BAR; PG8_SCHED;
;             PG8_LDA(At, 1, 1); PG8_STAGE(PG8_SB(1, 0), b3, voffB); PG8_STAGE(PG8_SB(1, 1), b3 + hstep, voffB); PG8_STAGE(PG8_SA(1, 0), a3, voffA);
;             PG8_WAIT_V(8); PG8_WAIT_L(0); PG8_BAR; PG8_MMA(1, 0, At, B0); PG8_MMA(1, 1, At, B1); PG8_BAR; PG8_SCHED;
	s_add_i32 s30, s45, s46
	v_lshl_add_u64 v[158:159], v[158:159], 0, s[28:29]
	s_mov_b32 m0, s30
	ds_read_b128 v[188:191], v145 offset:49152
	ds_read_b128 v[192:195], v145 offset:50176
	ds_read_b128 v[208:211], v145 offset:51200
	ds_read_b128 v[214:217], v145 offset:52224
	ds_read_b128 v[218:221], v145 offset:53248
	ds_read_b128 v[222:225], v145 offset:54272
	ds_read_b128 v[226:229], v145 offset:55296
	ds_read_b128 v[230:233], v145 offset:56320
	global_load_lds_dwordx4 v[158:159], off
	v_lshl_add_u64 v[158:159], v[174:175], 0, s[28:29]
	s_add_i32 m0, s30, 0x2000
	s_add_i32 s30, s63, s46
	global_load_lds_dwordx4 v[158:159], off
	v_lshl_add_u64 v[158:159], v[178:179], 0, s[28:29]
	s_mov_b32 m0, s30
	s_nop 0
	global_load_lds_dwordx4 v[158:159], off
	v_lshl_add_u64 v[158:159], v[180:181], 0, s[28:29]
	s_add_i32 m0, s30, 0x2000
	s_nop 0
	global_load_lds_dwordx4 v[158:159], off
	v_lshl_add_u64 v[158:159], v[196:197], 0, s[28:29]
	s_mov_b32 m0, s51
	s_nop 0
	global_load_lds_dwordx4 v[158:159], off
	v_lshl_add_u64 v[158:159], v[198:199], 0, s[28:29]
	s_mov_b32 m0, s52
	s_nop 0
	global_load_lds_dwordx4 v[158:159], off
	s_waitcnt vmcnt(8)
	s_waitcnt lgkmcnt(0)
	s_barrier
	s_setprio 1
	s_waitcnt lgkmcnt(0)
	v_mfma_f32_16x16x32_bf16 v[60:63], v[138:141], v[188:191], v[60:63]
	v_mfma_f32_16x16x32_bf16 v[56:59], v[150:153], v[188:191], v[56:59]
	v_mfma_f32_16x16x32_bf16 v[44:47], v[138:141], v[208:211], v[44:47]
	v_mfma_f32_16x16x32_bf16 v[40:43], v[150:153], v[208:211], v[40:43]
	v_mfma_f32_16x16x32_bf16 v[28:31], v[138:141], v[218:221], v[28:31]
	v_mfma_f32_16x16x32_bf16 v[24:27], v[150:153], v[218:221], v[24:27]
	v_mfma_f32_16x16x32_bf16 v[12:15], v[138:141], v[226:229], v[12:15]
	v_mfma_f32_16x16x32_bf16 v[8:11], v[150:153], v[226:229], v[8:11]
	v_mfma_f32_16x16x32_bf16 v[60:63], v[146:149], v[192:195], v[60:63]
	v_mfma_f32_16x16x32_bf16 v[56:59], v[154:157], v[192:195], v[56:59]
	v_mfma_f32_16x16x32_bf16 v[44:47], v[146:149], v[214:217], v[44:47]
	v_mfma_f32_16x16x32_bf16 v[40:43], v[154:157], v[214:217], v[40:43]
	v_mfma_f32_16x16x32_bf16 v[28:31], v[146:149], v[222:225], v[28:31]
	v_mfma_f32_16x16x32_bf16 v[24:27], v[154:157], v[222:225], v[24:27]
	v_mfma_f32_16x16x32_bf16 v[12:15], v[146:149], v[230:233], v[12:15]
	v_mfma_f32_16x16x32_bf16 v[8:11], v[154:157], v[230:233], v[8:11]
	s_setprio 0
	s_setprio 1
	v_mfma_f32_16x16x32_bf16 v[52:55], v[162:165], v[188:191], v[52:55]
	s_add_u32 s26, s26, 0x100
	v_mfma_f32_16x16x32_bf16 v[48:51], v[170:173], v[188:191], v[48:51]
	s_addc_u32 s27, s27, 0
	v_mfma_f32_16x16x32_bf16 v[36:39], v[162:165], v[208:211], v[36:39]
	s_add_u32 s36, s36, 0x100
	v_mfma_f32_16x16x32_bf16 v[32:35], v[170:173], v[208:211], v[32:35]
	s_addc_u32 s37, s37, 0
	v_mfma_f32_16x16x32_bf16 v[20:23], v[162:165], v[218:221], v[20:23]
	s_cmp_ge_u32 s44, s57
	v_mfma_f32_16x16x32_bf16 v[16:19], v[170:173], v[218:221], v[16:19]
	s_mov_b32 s30, s44
	v_mfma_f32_16x16x32_bf16 v[4:7], v[162:165], v[226:229], v[4:7]
	v_mfma_f32_16x16x32_bf16 v[0:3], v[170:173], v[226:229], v[0:3]
	v_mfma_f32_16x16x32_bf16 v[52:55], v[166:169], v[192:195], v[52:55]
	v_mfma_f32_16x16x32_bf16 v[48:51], v[184:187], v[192:195], v[48:51]
	v_mfma_f32_16x16x32_bf16 v[36:39], v[166:169], v[214:217], v[36:39]
	v_mfma_f32_16x16x32_bf16 v[32:35], v[184:187], v[214:217], v[32:35]
	v_mfma_f32_16x16x32_bf16 v[20:23], v[166:169], v[222:225], v[20:23]
	v_mfma_f32_16x16x32_bf16 v[16:19], v[184:187], v[222:225], v[16:19]
	v_mfma_f32_16x16x32_bf16 v[4:7], v[166:169], v[230:233], v[4:7]
	v_mfma_f32_16x16x32_bf16 v[0:3], v[184:187], v[230:233], v[0:3]
	s_setprio 0
	s_barrier
	s_cbranch_scc1 .Lmy_kdone_0
.LBB0_60:
	s_add_i32 s44, s30, 2
	s_add_u32 s45, s26, 0x80
	s_addc_u32 s31, s27, 0
	s_add_i32 s63, 0, 0x10000
	s_cmp_eq_u32 s58, s30
	s_cselect_b32 s31, s21, s31
	s_cselect_b32 s30, s20, s45
	s_cselect_b32 s65, s23, s37
	s_cselect_b32 s64, s22, s36
	s_add_i32 s45, 0, 0x14000
	v_add_u32_e32 v154, s63, v143
	v_add_u32_e32 v158, s45, v143
	ds_read_b128 v[138:141], v154
	ds_read_b128 v[146:149], v154 offset:1024
	ds_read_b128 v[150:153], v154 offset:2048
	ds_read_b128 v[154:157], v154 offset:3072
	ds_read_b128 v[162:165], v158
	ds_read_b128 v[166:169], v158 offset:1024
	ds_read_b128 v[170:173], v158 offset:2048
	ds_read_b128 v[184:187], v158 offset:3072
	v_lshl_add_u64 v[158:159], s[26:27], 0, v[134:135]
	s_add_i32 m0, s47, 0xc000
	ds_read_b128 v[188:191], v145
	ds_read_b128 v[192:195], v145 offset:1024
	ds_read_b128 v[208:211], v145 offset:2048
	ds_read_b128 v[214:217], v145 offset:3072
	ds_read_b128 v[218:221], v145 offset:4096
	ds_read_b128 v[222:225], v145 offset:5120
	ds_read_b128 v[226:229], v145 offset:6144
	ds_read_b128 v[230:233], v145 offset:7168
	global_load_lds_dwordx4 v[158:159], off
	v_lshl_add_u64 v[158:159], s[26:27], 0, v[136:137]
	s_add_i32 m0, s47, 0xe000
	s_nop 0
	global_load_lds_dwordx4 v[158:159], off
	s_waitcnt vmcnt(8)
	s_waitcnt lgkmcnt(0)
	s_barrier
; #define PG8_STAGE(bufoff, gbase, voff) do { _Pragma("unroll") for (int _i = 0; _i < 2; ++_i) \
;         __builtin_amdgcn_global_load_lds((const unsigned*)((const char*)(gbase) + (voff)[_i]), (PG8_LAS unsigned*)(lds + (bufoff) + ldsw + _i * 8192), 16, 0, 0); } while (0)
; #define PG8_LDA(dst, b, h) do { _Pragma("unroll") for (int m = 0; m < 4; ++m) _Pragma("unroll") for (int k = 0; k < 2; ++k) dst[m][k] = *(const PG8_LAS bf16x8*)(lds + PG8_SA(b, h) + aoff + m * 2048 + k * 1024); } while (0)
; #define PG8_MMA(ai, bj, At, Bt) do { __builtin_amdgcn_s_setprio(1); _Pragma("unroll") for (int m = 0; m < 4; ++m) _Pragma("unroll") for (int n = 0; n < 2; ++n) _Pragma("unroll") for (int k = 0; k < 2; ++k) \
;         acc[ai][bj][m][n] = __builtin_amdgcn_mfma_f32_16x16x32_bf16(Bt[n][k], At[m][k], acc[ai][bj][m][n], 0, 0, 0); __builtin_amdgcn_s_setprio(0); } while (0)
; #define PG8_WAIT_V(n) asm volatile("s_waitcnt vmcnt(" #n ")" ::: "memory")
; #define PG8_WAIT_L(n) asm volatile("s_waitcnt lgkmcnt(" #n ")" ::: "memory")
; #define PG8_BAR __builtin_amdgcn_s_barrier()
; #define PG8_SCHED __builtin_amdgcn_sched_barrier(0)
; template <class Epi, class Sched, bool ALIGN_EPI = false, bool SP2 = false>
; __device__ __forceinline__ void gemm_phase(PG8_LAS unsigned char* lds, const Gemm g, const Sched& S, const Epi& E, const int tid) {
;     ...
;             PG8_WAIT_V(8); PG8_WAIT_L(0); PG8_BAR; PG8_MMA(0, 0, At, B0); PG8_MMA(0, 1, At, B1); PG8_BAR; PG8_SCHED;
;             PG8_LDA(At, 0, 1); PG8_STAGE(PG8_SB(0, 0), b2, voffB); PG8_STAGE(PG8_SB(0, 1), b2 + hstep, voffB); PG8_STAGE(PG8_SA(0, 0), a2, voffA);
;             PG8_WAIT_V(8); PG8_WAIT_L(0); PG8_BAR; PG8_MMA(1, 0, At, B0); PG8_MMA(1, 1, At, B1); PG8_BAR; PG8_SCHED;
	s_setprio 1
	s_waitcnt lgkmcnt(0)
	v_mfma_f32_16x16x32_bf16 v[124:127], v[138:141], v[188:191], v[124:127]
	v_mfma_f32_16x16x32_bf16 v[120:123], v[150:153], v[188:191], v[120:123]
	v_mfma_f32_16x16x32_bf16 v[108:111], v[138:141], v[208:211], v[108:111]
	v_mfma_f32_16x16x32_bf16 v[104:107], v[150:153], v[208:211], v[104:107]
	v_mfma_f32_16x16x32_bf16 v[92:95], v[138:141], v[218:221], v[92:95]
	v_mfma_f32_16x16x32_bf16 v[88:91], v[150:153], v[218:221], v[88:91]
	v_mfma_f32_16x16x32_bf16 v[76:79], v[138:141], v[226:229], v[76:79]
	v_mfma_f32_16x16x32_bf16 v[72:75], v[150:153], v[226:229], v[72:75]
	v_mfma_f32_16x16x32_bf16 v[124:127], v[146:149], v[192:195], v[124:127]
	v_mfma_f32_16x16x32_bf16 v[120:123], v[154:157], v[192:195], v[120:123]
	v_mfma_f32_16x16x32_bf16 v[108:111], v[146:149], v[214:217], v[108:111]
	v_mfma_f32_16x16x32_bf16 v[104:107], v[154:157], v[214:217], v[104:107]
	v_mfma_f32_16x16x32_bf16 v[92:95], v[146:149], v[222:225], v[92:95]
	v_mfma_f32_16x16x32_bf16 v[88:91], v[154:157], v[222:225], v[88:91]
	v_mfma_f32_16x16x32_bf16 v[76:79], v[146:149], v[230:233], v[76:79]
	v_mfma_f32_16x16x32_bf16 v[72:75], v[154:157], v[230:233], v[72:75]
	s_setprio 0
	s_setprio 1
	v_mfma_f32_16x16x32_bf16 v[116:119], v[162:165], v[188:191], v[116:119]
	v_mfma_f32_16x16x32_bf16 v[112:115], v[170:173], v[188:191], v[112:115]
	v_mfma_f32_16x16x32_bf16 v[100:103], v[162:165], v[208:211], v[100:103]
	v_mfma_f32_16x16x32_bf16 v[96:99], v[170:173], v[208:211], v[96:99]
	v_mfma_f32_16x16x32_bf16 v[84:87], v[162:165], v[218:221], v[84:87]
	v_mfma_f32_16x16x32_bf16 v[80:83], v[170:173], v[218:221], v[80:83]
	v_mfma_f32_16x16x32_bf16 v[68:71], v[162:165], v[226:229], v[68:71]
	v_mfma_f32_16x16x32_bf16 v[64:67], v[170:173], v[226:229], v[64:67]
	v_mfma_f32_16x16x32_bf16 v[116:119], v[166:169], v[192:195], v[116:119]
	v_mfma_f32_16x16x32_bf16 v[112:115], v[184:187], v[192:195], v[112:115]
	v_mfma_f32_16x16x32_bf16 v[100:103], v[166:169], v[214:217], v[100:103]
	v_mfma_f32_16x16x32_bf16 v[96:99], v[184:187], v[214:217], v[96:99]
	v_mfma_f32_16x16x32_bf16 v[84:87], v[166:169], v[222:225], v[84:87]
	v_mfma_f32_16x16x32_bf16 v[80:83], v[184:187], v[222:225], v[80:83]
	v_mfma_f32_16x16x32_bf16 v[68:71], v[166:169], v[230:233], v[68:71]
	v_mfma_f32_16x16x32_bf16 v[64:67], v[184:187], v[230:233], v[64:67]
	s_setprio 0
	s_barrier
	s_add_i32 s63, s63, s46
	v_lshl_add_u64 v[158:159], s[64:65], 0, v[160:161]
	s_mov_b32 m0, s63
	ds_read_b128 v[188:191], v145 offset:16384
	ds_read_b128 v[192:195], v145 offset:17408
	ds_read_b128 v[208:211], v145 offset:18432
	ds_read_b128 v[214:217], v145 offset:19456
	ds_read_b128 v[218:221], v145 offset:20480
	ds_read_b128 v[222:225], v145 offset:21504
	ds_read_b128 v[226:229], v145 offset:22528
	ds_read_b128 v[230:233], v145 offset:23552
	global_load_lds_dwordx4 v[158:159], off
	s_add_i32 m0, s63, 0x2000
	v_lshl_add_u64 v[174:175], s[64:65], 0, v[132:133]
	s_add_u32 s64, s64, s12
	s_addc_u32 s65, s65, 0
	s_add_i32 s45, s45, s46
	global_load_lds_dwordx4 v[174:175], off
	v_lshl_add_u64 v[178:179], s[64:65], 0, v[160:161]
	s_mov_b32 m0, s45
	v_lshl_add_u64 v[180:181], s[64:65], 0, v[132:133]
	global_load_lds_dwordx4 v[178:179], off
	s_add_i32 m0, s45, 0x2000
	v_lshl_add_u64 v[196:197], s[30:31], 0, v[128:129]
	global_load_lds_dwordx4 v[180:181], off
	s_mov_b32 m0, s47
	v_lshl_add_u64 v[198:199], s[30:31], 0, v[130:131]
	global_load_lds_dwordx4 v[196:197], off
	s_mov_b32 m0, s48
	s_nop 0
	global_load_lds_dwordx4 v[198:199], off
	s_waitcnt vmcnt(8)
	s_waitcnt lgkmcnt(0)
	s_barrier
	s_setprio 1
	s_waitcnt lgkmcnt(0)
	v_mfma_f32_16x16x32_bf16 v[60:63], v[138:141], v[188:191], v[60:63]
	v_mfma_f32_16x16x32_bf16 v[56:59], v[150:153], v[188:191], v[56:59]
	v_mfma_f32_16x16x32_bf16 v[44:47], v[138:141], v[208:211], v[44:47]
	v_mfma_f32_16x16x32_bf16 v[40:43], v[150:153], v[208:211], v[40:43]
	v_mfma_f32_16x16x32_bf16 v[28:31], v[138:141], v[218:221], v[28:31]
	v_mfma_f32_16x16x32_bf16 v[24:27], v[150:153], v[218:221], v[24:27]
	v_mfma_f32_16x16x32_bf16 v[12:15], v[138:141], v[226:229], v[12:15]
	v_mfma_f32_16x16x32_bf16 v[8:11], v[150:153], v[226:229], v[8:11]
	v_mfma_f32_16x16x32_bf16 v[60:63], v[146:149], v[192:195], v[60:63]
	v_mfma_f32_16x16x32_bf16 v[56:59], v[154:157], v[192:195], v[56:59]
	v_mfma_f32_16x16x32_bf16 v[44:47], v[146:149], v[214:217], v[44:47]
	v_mfma_f32_16x16x32_bf16 v[40:43], v[154:157], v[214:217], v[40:43]
	v_mfma_f32_16x16x32_bf16 v[28:31], v[146:149], v[222:225], v[28:31]
	v_mfma_f32_16x16x32_bf16 v[24:27], v[154:157], v[222:225], v[24:27]
	v_mfma_f32_16x16x32_bf16 v[12:15], v[146:149], v[230:233], v[12:15]
	v_mfma_f32_16x16x32_bf16 v[8:11], v[154:157], v[230:233], v[8:11]
	s_setprio 0
	s_setprio 1
	v_mfma_f32_16x16x32_bf16 v[52:55], v[162:165], v[188:191], v[52:55]
	v_mfma_f32_16x16x32_bf16 v[48:51], v[170:173], v[188:191], v[48:51]
	v_mfma_f32_16x16x32_bf16 v[36:39], v[162:165], v[208:211], v[36:39]
	v_mfma_f32_16x16x32_bf16 v[32:35], v[170:173], v[208:211], v[32:35]
	v_mfma_f32_16x16x32_bf16 v[20:23], v[162:165], v[218:221], v[20:23]
	v_mfma_f32_16x16x32_bf16 v[16:19], v[170:173], v[218:221], v[16:19]
	v_mfma_f32_16x16x32_bf16 v[4:7], v[162:165], v[226:229], v[4:7]
	v_mfma_f32_16x16x32_bf16 v[0:3], v[170:173], v[226:229], v[0:3]
	v_mfma_f32_16x16x32_bf16 v[52:55], v[166:169], v[192:195], v[52:55]
	v_mfma_f32_16x16x32_bf16 v[48:51], v[184:187], v[192:195], v[48:51]
	v_mfma_f32_16x16x32_bf16 v[36:39], v[166:169], v[214:217], v[36:39]
	v_mfma_f32_16x16x32_bf16 v[32:35], v[184:187], v[214:217], v[32:35]
	v_mfma_f32_16x16x32_bf16 v[20:23], v[166:169], v[222:225], v[20:23]
	v_mfma_f32_16x16x32_bf16 v[16:19], v[184:187], v[222:225], v[16:19]
	v_mfma_f32_16x16x32_bf16 v[4:7], v[166:169], v[230:233], v[4:7]
	v_mfma_f32_16x16x32_bf16 v[0:3], v[184:187], v[230:233], v[0:3]
	s_setprio 0
	s_barrier
; #define PG8_STAGE(bufoff, gbase, voff) do { _Pragma("unroll") for (int _i = 0; _i < 2; ++_i) \
;         __builtin_amdgcn_global_load_lds((const unsigned*)((const char*)(gbase) + (voff)[_i]), (PG8_LAS unsigned*)(lds + (bufoff) + ldsw + _i * 8192), 16, 0, 0); } while (0)
; #define PG8_LDA(dst, b, h) do { _Pragma("unroll") for (int m = 0; m < 4; ++m) _Pragma("unroll") for (int k = 0; k < 2; ++k) dst[m][k] = *(const PG8_LAS bf16x8*)(lds + PG8_SA(b, h) + aoff + m * 2048 + k * 1024); } while (0)
; #define PG8_LDB(dst, b, h) do { _Pragma("unroll") for (int n = 0; n < 2; ++n) _Pragma("unroll") for (int k = 0; k < 2; ++k) dst[n][k] = *(const PG8_LAS bf16x8*)(lds + PG8_SB(b, h) + boff + n * 2048 + k * 1024); } while (0)
; #define PG8_MMA(ai, bj, At, Bt) do { __builtin_amdgcn_s_setprio(1); _Pragma("unroll") for (int m = 0; m < 4; ++m) _Pragma("unroll") for (int n = 0; n < 2; ++n) _Pragma("unroll") for (int k = 0; k < 2; ++k) \
;         acc[ai][bj][m][n] = __builtin_amdgcn_mfma_f32_16x16x32_bf16(Bt[n][k], At[m][k], acc[ai][bj][m][n], 0, 0, 0); __builtin_amdgcn_s_setprio(0); } while (0)
; #define PG8_WAIT_V(n) asm volatile("s_waitcnt vmcnt(" #n ")" ::: "memory")
; #define PG8_WAIT_L(n) asm volatile("s_waitcnt lgkmcnt(" #n ")" ::: "memory")
; #define PG8_BAR __builtin_amdgcn_s_barrier()
; #define PG8_SCHED __builtin_amdgcn_sched_barrier(0)
; template <class Epi, class Sched, bool ALIGN_EPI = false, bool SP2 = false>
; __device__ __forceinline__ void gemm_phase(PG8_LAS unsigned char* lds, const Gemm g, const Sched& S, const Epi& E, const int tid) {
;     ...
;             PG8_LDB(B0, 1, 0); PG8_LDB(B1, 1, 1); PG8_SCHED; PG8_LDA(At, 1, 0); PG8_STAGE(PG8_SA(0, 1), a2 + hstep, voffA);
;             PG8_WAIT_V(8); PG8_WAIT_L(0); PG8_BAR; PG8_MMA(0, 0, At, B0); PG8_MMA(0, 1, At, B1); PG8_BAR; PG8_SCHED;
	s_add_i32 s45, 0, 0x18000
	s_add_i32 s63, 0, 0x1c000
	v_add_u32_e32 v154, s45, v143
	v_add_u32_e32 v183, s63, v143
	ds_read_b128 v[138:141], v154
	ds_read_b128 v[146:149], v154 offset:1024
	ds_read_b128 v[150:153], v154 offset:2048
	ds_read_b128 v[154:157], v154 offset:3072
	ds_read_b128 v[162:165], v183
	ds_read_b128 v[166:169], v183 offset:1024
	ds_read_b128 v[170:173], v183 offset:2048
	ds_read_b128 v[184:187], v183 offset:3072
	s_add_u32 s30, s30, s12
	s_addc_u32 s31, s31, 0
	s_mov_b32 m0, s49
	v_lshl_add_u64 v[204:205], s[30:31], 0, v[128:129]
	ds_read_b128 v[188:191], v145 offset:32768
	ds_read_b128 v[192:195], v145 offset:33792
	ds_read_b128 v[208:211], v145 offset:34816
	ds_read_b128 v[214:217], v145 offset:35840
	ds_read_b128 v[218:221], v145 offset:36864
	ds_read_b128 v[222:225], v145 offset:37888
	ds_read_b128 v[226:229], v145 offset:38912
	ds_read_b128 v[230:233], v145 offset:39936
	global_load_lds_dwordx4 v[204:205], off
	v_lshl_add_u64 v[204:205], s[30:31], 0, v[130:131]
	s_mov_b32 m0, s50
	s_nop 0
	global_load_lds_dwordx4 v[204:205], off
	s_waitcnt vmcnt(8)
	s_waitcnt lgkmcnt(0)
	s_barrier
	s_setprio 1
	s_waitcnt lgkmcnt(0)
	v_mfma_f32_16x16x32_bf16 v[124:127], v[138:141], v[188:191], v[124:127]
	v_mfma_f32_16x16x32_bf16 v[120:123], v[150:153], v[188:191], v[120:123]
	v_mfma_f32_16x16x32_bf16 v[108:111], v[138:141], v[208:211], v[108:111]
	v_mfma_f32_16x16x32_bf16 v[104:107], v[150:153], v[208:211], v[104:107]
	v_mfma_f32_16x16x32_bf16 v[92:95], v[138:141], v[218:221], v[92:95]
	v_mfma_f32_16x16x32_bf16 v[88:91], v[150:153], v[218:221], v[88:91]
	v_mfma_f32_16x16x32_bf16 v[76:79], v[138:141], v[226:229], v[76:79]
	v_mfma_f32_16x16x32_bf16 v[72:75], v[150:153], v[226:229], v[72:75]
	v_mfma_f32_16x16x32_bf16 v[124:127], v[146:149], v[192:195], v[124:127]
	v_mfma_f32_16x16x32_bf16 v[120:123], v[154:157], v[192:195], v[120:123]
	v_mfma_f32_16x16x32_bf16 v[108:111], v[146:149], v[214:217], v[108:111]
	v_mfma_f32_16x16x32_bf16 v[104:107], v[154:157], v[214:217], v[104:107]
	v_mfma_f32_16x16x32_bf16 v[92:95], v[146:149], v[222:225], v[92:95]
	v_mfma_f32_16x16x32_bf16 v[88:91], v[154:157], v[222:225], v[88:91]
	v_mfma_f32_16x16x32_bf16 v[76:79], v[146:149], v[230:233], v[76:79]
	v_mfma_f32_16x16x32_bf16 v[72:75], v[154:157], v[230:233], v[72:75]
	s_setprio 0
	s_setprio 1
	v_mfma_f32_16x16x32_bf16 v[116:119], v[162:165], v[188:191], v[116:119]
	v_mfma_f32_16x16x32_bf16 v[112:115], v[170:173], v[188:191], v[112:115]
	v_mfma_f32_16x16x32_bf16 v[100:103], v[162:165], v[208:211], v[100:103]
	v_mfma_f32_16x16x32_bf16 v[96:99], v[170:173], v[208:211], v[96:99]
	v_mfma_f32_16x16x32_bf16 v[84:87], v[162:165], v[218:221], v[84:87]
	v_mfma_f32_16x16x32_bf16 v[80:83], v[170:173], v[218:221], v[80:83]
	v_mfma_f32_16x16x32_bf16 v[68:71], v[162:165], v[226:229], v[68:71]
	v_mfma_f32_16x16x32_bf16 v[64:67], v[170:173], v[226:229], v[64:67]
	v_mfma_f32_16x16x32_bf16 v[116:119], v[166:169], v[192:195], v[116:119]
	v_mfma_f32_16x16x32_bf16 v[112:115], v[184:187], v[192:195], v[112:115]
	v_mfma_f32_16x16x32_bf16 v[100:103], v[166:169], v[214:217], v[100:103]
	v_mfma_f32_16x16x32_bf16 v[96:99], v[184:187], v[214:217], v[96:99]
	v_mfma_f32_16x16x32_bf16 v[84:87], v[166:169], v[222:225], v[84:87]
	v_mfma_f32_16x16x32_bf16 v[80:83], v[184:187], v[222:225], v[80:83]
	v_mfma_f32_16x16x32_bf16 v[68:71], v[166:169], v[230:233], v[68:71]
	v_mfma_f32_16x16x32_bf16 v[64:67], v[184:187], v[230:233], v[64:67]
	s_setprio 0
	s_barrier
; #define PG8_STAGE(bufoff, gbase, voff) do { _Pragma("unroll") for (int _i = 0; _i < 2; ++_i) \
;         __builtin_amdgcn_global_load_lds((const unsigned*)((const char*)(gbase) + (voff)[_i]), (PG8_LAS unsigned*)(lds + (bufoff) + ldsw + _i * 8192), 16, 0, 0); } while (0)
; #define PG8_LDA(dst, b, h) do { _Pragma("unroll") for (int m = 0; m < 4; ++m) _Pragma("unroll") for (int k = 0; k < 2; ++k) dst[m][k] = *(const PG8_LAS bf16x8*)(lds + PG8_SA(b, h) + aoff + m * 2048 + k * 1024); } while (0)
; #define PG8_MMA(ai, bj, At, Bt) do { __builtin_amdgcn_s_setprio(1); _Pragma("unroll") for (int m = 0; m < 4; ++m) _Pragma("unroll") for (int n = 0; n < 2; ++n) _Pragma("unroll") for (int k = 0; k < 2; ++k) \
;         acc[ai][bj][m][n] = __builtin_amdgcn_mfma_f32_16x16x32_bf16(Bt[n][k], At[m][k], acc[ai][bj][m][n], 0, 0, 0); __builtin_amdgcn_s_setprio(0); } while (0)
; #define PG8_WAIT_V(n) asm volatile("s_waitcnt vmcnt(" #n ")" ::: "memory")
; #define PG8_WAIT_L(n) asm volatile("s_waitcnt lgkmcnt(" #n ")" ::: "memory")
; #define PG8_BAR __builtin_amdgcn_s_barrier()
; #define PG8_SCHED __builtin_amdgcn_sched_barrier(0)
; template <class Epi, class Sched, bool ALIGN_EPI = false, bool SP2 = false>
; __device__ __forceinline__ void gemm_phase(PG8_LAS unsigned char* lds, const Gemm g, const Sched& S, const Epi& E, const int tid) {
;     ...
;             PG8_LDA(At, 1, 1); PG8_STAGE(PG8_SB(1, 0), b3, voffB); PG8_STAGE(PG8_SB(1, 1), b3 + hstep, voffB); PG8_STAGE(PG8_SA(1, 0), a3, voffA);
;             PG8_WAIT_V(8); PG8_WAIT_L(0); PG8_BAR; PG8_MMA(1, 0, At, B0); PG8_MMA(1, 1, At, B1); PG8_BAR; PG8_SCHED;
	s_add_i32 s30, s45, s46
	v_lshl_add_u64 v[158:159], v[158:159], 0, s[28:29]
	s_mov_b32 m0, s30
	ds_read_b128 v[188:191], v145 offset:49152
	ds_read_b128 v[192:195], v145 offset:50176
	ds_read_b128 v[208:211], v145 offset:51200
	ds_read_b128 v[214:217], v145 offset:52224
	ds_read_b128 v[218:221], v145 offset:53248
	ds_read_b128 v[222:225], v145 offset:54272
	ds_read_b128 v[226:229], v145 offset:55296
	ds_read_b128 v[230:233], v145 offset:56320
	global_load_lds_dwordx4 v[158:159], off
	v_lshl_add_u64 v[158:159], v[174:175], 0, s[28:29]
	s_add_i32 m0, s30, 0x2000
	s_add_i32 s30, s63, s46
	global_load_lds_dwordx4 v[158:159], off
	v_lshl_add_u64 v[158:159], v[178:179], 0, s[28:29]
	s_mov_b32 m0, s30
	s_nop 0
	global_load_lds_dwordx4 v[158:159], off
	v_lshl_add_u64 v[158:159], v[180:181], 0, s[28:29]
	s_add_i32 m0, s30, 0x2000
	s_nop 0
	global_load_lds_dwordx4 v[158:159], off
	v_lshl_add_u64 v[158:159], v[196:197], 0, s[28:29]
	s_mov_b32 m0, s51
	s_nop 0
	global_load_lds_dwordx4 v[158:159], off
	v_lshl_add_u64 v[158:159], v[198:199], 0, s[28:29]
	s_mov_b32 m0, s52
	s_nop 0
	global_load_lds_dwordx4 v[158:159], off
	s_waitcnt vmcnt(8)
	s_waitcnt lgkmcnt(0)
	s_barrier
	s_setprio 1
	s_waitcnt lgkmcnt(0)
	v_mfma_f32_16x16x32_bf16 v[60:63], v[138:141], v[188:191], v[60:63]
	v_mfma_f32_16x16x32_bf16 v[56:59], v[150:153], v[188:191], v[56:59]
	v_mfma_f32_16x16x32_bf16 v[44:47], v[138:141], v[208:211], v[44:47]
	v_mfma_f32_16x16x32_bf16 v[40:43], v[150:153], v[208:211], v[40:43]
	v_mfma_f32_16x16x32_bf16 v[28:31], v[138:141], v[218:221], v[28:31]
	v_mfma_f32_16x16x32_bf16 v[24:27], v[150:153], v[218:221], v[24:27]
	v_mfma_f32_16x16x32_bf16 v[12:15], v[138:141], v[226:229], v[12:15]
	v_mfma_f32_16x16x32_bf16 v[8:11], v[150:153], v[226:229], v[8:11]
	v_mfma_f32_16x16x32_bf16 v[60:63], v[146:149], v[192:195], v[60:63]
	v_mfma_f32_16x16x32_bf16 v[56:59], v[154:157], v[192:195], v[56:59]
	v_mfma_f32_16x16x32_bf16 v[44:47], v[146:149], v[214:217], v[44:47]
	v_mfma_f32_16x16x32_bf16 v[40:43], v[154:157], v[214:217], v[40:43]
	v_mfma_f32_16x16x32_bf16 v[28:31], v[146:149], v[222:225], v[28:31]
	v_mfma_f32_16x16x32_bf16 v[24:27], v[154:157], v[222:225], v[24:27]
	v_mfma_f32_16x16x32_bf16 v[12:15], v[146:149], v[230:233], v[12:15]
	v_mfma_f32_16x16x32_bf16 v[8:11], v[154:157], v[230:233], v[8:11]
	s_setprio 0
	s_setprio 1
	v_mfma_f32_16x16x32_bf16 v[52:55], v[162:165], v[188:191], v[52:55]
	s_add_u32 s26, s26, 0x100
	v_mfma_f32_16x16x32_bf16 v[48:51], v[170:173], v[188:191], v[48:51]
	s_addc_u32 s27, s27, 0
	v_mfma_f32_16x16x32_bf16 v[36:39], v[162:165], v[208:211], v[36:39]
	s_add_u32 s36, s36, 0x100
	v_mfma_f32_16x16x32_bf16 v[32:35], v[170:173], v[208:211], v[32:35]
	s_addc_u32 s37, s37, 0
	v_mfma_f32_16x16x32_bf16 v[20:23], v[162:165], v[218:221], v[20:23]
	s_cmp_ge_u32 s44, s57
	v_mfma_f32_16x16x32_bf16 v[16:19], v[170:173], v[218:221], v[16:19]
	s_mov_b32 s30, s44
	v_mfma_f32_16x16x32_bf16 v[4:7], v[162:165], v[226:229], v[4:7]
	v_mfma_f32_16x16x32_bf16 v[0:3], v[170:173], v[226:229], v[0:3]
	v_mfma_f32_16x16x32_bf16 v[52:55], v[166:169], v[192:195], v[52:55]
	v_mfma_f32_16x16x32_bf16 v[48:51], v[184:187], v[192:195], v[48:51]
	v_mfma_f32_16x16x32_bf16 v[36:39], v[166:169], v[214:217], v[36:39]
	v_mfma_f32_16x16x32_bf16 v[32:35], v[184:187], v[214:217], v[32:35]
	v_mfma_f32_16x16x32_bf16 v[20:23], v[166:169], v[222:225], v[20:23]
	v_mfma_f32_16x16x32_bf16 v[16:19], v[184:187], v[222:225], v[16:19]
	v_mfma_f32_16x16x32_bf16 v[4:7], v[166:169], v[230:233], v[4:7]
	v_mfma_f32_16x16x32_bf16 v[0:3], v[184:187], v[230:233], v[0:3]
	s_setprio 0
	s_barrier
	s_cbranch_scc0 .LBB0_60

; #define PG8_STAGE(bufoff, gbase, voff) do { _Pragma("unroll") for (int _i = 0; _i < 2; ++_i) \
;         __builtin_amdgcn_global_load_lds((const unsigned*)((const char*)(gbase) + (voff)[_i]), (PG8_LAS unsigned*)(lds + (bufoff) + ldsw + _i * 8192), 16, 0, 0); } while (0)
; #define PG8_LDA(dst, b, h) do { _Pragma("unroll") for (int m = 0; m < 4; ++m) _Pragma("unroll") for (int k = 0; k < 2; ++k) dst[m][k] = *(const PG8_LAS bf16x8*)(lds + PG8_SA(b, h) + aoff + m * 2048 + k * 1024); } while (0)
; #define PG8_LDB(dst, b, h) do { _Pragma("unroll") for (int n = 0; n < 2; ++n) _Pragma("unroll") for (int k = 0; k < 2; ++k) dst[n][k] = *(const PG8_LAS bf16x8*)(lds + PG8_SB(b, h) + boff + n * 2048 + k * 1024); } while (0)
; #define PG8_MMA(ai, bj, At, Bt) do { __builtin_amdgcn_s_setprio(1); _Pragma("unroll") for (int m = 0; m < 4; ++m) _Pragma("unroll") for (int n = 0; n < 2; ++n) _Pragma("unroll") for (int k = 0; k < 2; ++k) \
;         acc[ai][bj][m][n] = __builtin_amdgcn_mfma_f32_16x16x32_bf16(Bt[n][k], At[m][k], acc[ai][bj][m][n], 0, 0, 0); __builtin_amdgcn_s_setprio(0); } while (0)
; #define PG8_WAIT_V(n) asm volatile("s_waitcnt vmcnt(" #n ")" ::: "memory")
; #define PG8_WAIT_L(n) asm volatile("s_waitcnt lgkmcnt(" #n ")" ::: "memory")
; #define PG8_BAR __builtin_amdgcn_s_barrier()
; #define PG8_SCHED __builtin_amdgcn_sched_barrier(0)
; template <class Epi, class Sched, bool ALIGN_EPI = false, bool SP2 = false>
; __device__ __forceinline__ void gemm_phase(PG8_LAS unsigned char* lds, const Gemm g, const Sched& S, const Epi& E, const int tid) {
;     ...
;             PG8_WAIT_V(8); PG8_WAIT_L(0); PG8_BAR; PG8_MMA(1, 0, At, B0); PG8_MMA(1, 1, At, B1); PG8_BAR; PG8_SCHED;
;             PG8_LDB(B0, 1, 0); PG8_LDB(B1, 1, 1); PG8_SCHED; PG8_LDA(At, 1, 0); PG8_STAGE(PG8_SA(0, 1), a2 + hstep, voffA);
;             PG8_WAIT_V(8); PG8_WAIT_L(0); PG8_BAR; PG8_MMA(0, 0, At, B0); PG8_MMA(0, 1, At, B1); PG8_BAR; PG8_SCHED;
.Lmy_wj_1:
	s_waitcnt lgkmcnt(0)
	s_barrier
	s_setprio 1
	s_waitcnt lgkmcnt(0)
	v_mfma_f32_16x16x32_bf16 v[60:63], v[140:143], v[208:211], 0
	v_mfma_f32_16x16x32_bf16 v[56:59], v[162:165], v[208:211], 0
	v_mfma_f32_16x16x32_bf16 v[44:47], v[140:143], v[218:221], 0
	v_mfma_f32_16x16x32_bf16 v[40:43], v[162:165], v[218:221], 0
	v_mfma_f32_16x16x32_bf16 v[28:31], v[140:143], v[226:229], 0
	v_mfma_f32_16x16x32_bf16 v[24:27], v[162:165], v[226:229], 0
	v_mfma_f32_16x16x32_bf16 v[12:15], v[140:143], v[234:237], 0
	v_mfma_f32_16x16x32_bf16 v[8:11], v[162:165], v[234:237], 0
	v_mfma_f32_16x16x32_bf16 v[60:63], v[154:157], v[214:217], v[60:63]
	v_mfma_f32_16x16x32_bf16 v[56:59], v[166:169], v[214:217], v[56:59]
	v_mfma_f32_16x16x32_bf16 v[44:47], v[154:157], v[222:225], v[44:47]
	v_mfma_f32_16x16x32_bf16 v[40:43], v[166:169], v[222:225], v[40:43]
	v_mfma_f32_16x16x32_bf16 v[28:31], v[154:157], v[230:233], v[28:31]
	v_mfma_f32_16x16x32_bf16 v[24:27], v[166:169], v[230:233], v[24:27]
	v_mfma_f32_16x16x32_bf16 v[12:15], v[154:157], v[238:241], v[12:15]
	v_mfma_f32_16x16x32_bf16 v[8:11], v[166:169], v[238:241], v[8:11]
	s_setprio 0
	s_setprio 1
	v_mfma_f32_16x16x32_bf16 v[52:55], v[170:173], v[208:211], 0
	v_mfma_f32_16x16x32_bf16 v[48:51], v[188:191], v[208:211], 0
	v_mfma_f32_16x16x32_bf16 v[36:39], v[170:173], v[218:221], 0
	v_mfma_f32_16x16x32_bf16 v[32:35], v[188:191], v[218:221], 0
	v_mfma_f32_16x16x32_bf16 v[20:23], v[170:173], v[226:229], 0
	v_mfma_f32_16x16x32_bf16 v[16:19], v[188:191], v[226:229], 0
	v_mfma_f32_16x16x32_bf16 v[4:7], v[170:173], v[234:237], 0
	v_mfma_f32_16x16x32_bf16 v[0:3], v[188:191], v[234:237], 0
	v_mfma_f32_16x16x32_bf16 v[52:55], v[184:187], v[214:217], v[52:55]
	v_mfma_f32_16x16x32_bf16 v[48:51], v[192:195], v[214:217], v[48:51]
	v_mfma_f32_16x16x32_bf16 v[36:39], v[184:187], v[222:225], v[36:39]
	v_mfma_f32_16x16x32_bf16 v[32:35], v[192:195], v[222:225], v[32:35]
	v_mfma_f32_16x16x32_bf16 v[20:23], v[184:187], v[230:233], v[20:23]
	v_mfma_f32_16x16x32_bf16 v[16:19], v[192:195], v[230:233], v[16:19]
	v_mfma_f32_16x16x32_bf16 v[4:7], v[184:187], v[238:241], v[4:7]
	v_mfma_f32_16x16x32_bf16 v[0:3], v[192:195], v[238:241], v[0:3]
	s_setprio 0
	s_barrier
	s_add_i32 s56, 0, 0x18000
	v_add_u32_e32 v138, s56, v147
	s_add_i32 s57, 0, 0x1c000
	ds_read_b128 v[140:143], v138
	ds_read_b128 v[154:157], v138 offset:1024
	ds_read_b128 v[162:165], v138 offset:2048
	ds_read_b128 v[166:169], v138 offset:3072
	v_add_u32_e32 v138, s57, v147
	ds_read_b128 v[170:173], v138
	ds_read_b128 v[184:187], v138 offset:1024
	ds_read_b128 v[188:191], v138 offset:2048
	ds_read_b128 v[192:195], v138 offset:3072
	s_add_u32 s20, s20, 0x40000
	s_addc_u32 s21, s21, 0
	s_mov_b32 m0, s31
	v_lshl_add_u64 v[196:197], s[20:21], 0, v[128:129]
	ds_read_b128 v[208:211], v153 offset:32768
	ds_read_b128 v[214:217], v153 offset:33792
	ds_read_b128 v[218:221], v153 offset:34816
	ds_read_b128 v[222:225], v153 offset:35840
	ds_read_b128 v[226:229], v153 offset:36864
	ds_read_b128 v[230:233], v153 offset:37888
	ds_read_b128 v[234:237], v153 offset:38912
	ds_read_b128 v[238:241], v153 offset:39936
	global_load_lds_dwordx4 v[196:197], off
	v_lshl_add_u64 v[196:197], s[20:21], 0, v[130:131]
	s_mov_b32 m0, s34
	s_nop 0
	global_load_lds_dwordx4 v[196:197], off
	s_waitcnt vmcnt(8)
	s_waitcnt lgkmcnt(0)
	s_barrier
	s_setprio 1
	s_waitcnt lgkmcnt(0)
	v_mfma_f32_16x16x32_bf16 v[124:127], v[140:143], v[208:211], v[124:127]
	v_mfma_f32_16x16x32_bf16 v[120:123], v[162:165], v[208:211], v[120:123]
	v_mfma_f32_16x16x32_bf16 v[108:111], v[140:143], v[218:221], v[108:111]
	v_mfma_f32_16x16x32_bf16 v[104:107], v[162:165], v[218:221], v[104:107]
	v_mfma_f32_16x16x32_bf16 v[92:95], v[140:143], v[226:229], v[92:95]
	v_mfma_f32_16x16x32_bf16 v[88:91], v[162:165], v[226:229], v[88:91]
	v_mfma_f32_16x16x32_bf16 v[76:79], v[140:143], v[234:237], v[76:79]
	v_mfma_f32_16x16x32_bf16 v[72:75], v[162:165], v[234:237], v[72:75]
	v_mfma_f32_16x16x32_bf16 v[124:127], v[154:157], v[214:217], v[124:127]
	v_mfma_f32_16x16x32_bf16 v[120:123], v[166:169], v[214:217], v[120:123]
	v_mfma_f32_16x16x32_bf16 v[108:111], v[154:157], v[222:225], v[108:111]
	v_mfma_f32_16x16x32_bf16 v[104:107], v[166:169], v[222:225], v[104:107]
	v_mfma_f32_16x16x32_bf16 v[92:95], v[154:157], v[230:233], v[92:95]
	v_mfma_f32_16x16x32_bf16 v[88:91], v[166:169], v[230:233], v[88:91]
	v_mfma_f32_16x16x32_bf16 v[76:79], v[154:157], v[238:241], v[76:79]
	v_mfma_f32_16x16x32_bf16 v[72:75], v[166:169], v[238:241], v[72:75]
	s_setprio 0
	s_setprio 1
	v_mfma_f32_16x16x32_bf16 v[116:119], v[170:173], v[208:211], v[116:119]
	v_mfma_f32_16x16x32_bf16 v[112:115], v[188:191], v[208:211], v[112:115]
	v_mfma_f32_16x16x32_bf16 v[100:103], v[170:173], v[218:221], v[100:103]
	v_mfma_f32_16x16x32_bf16 v[96:99], v[188:191], v[218:221], v[96:99]
	v_mfma_f32_16x16x32_bf16 v[84:87], v[170:173], v[226:229], v[84:87]
	v_mfma_f32_16x16x32_bf16 v[80:83], v[188:191], v[226:229], v[80:83]
	v_mfma_f32_16x16x32_bf16 v[68:71], v[170:173], v[234:237], v[68:71]
	v_mfma_f32_16x16x32_bf16 v[64:67], v[188:191], v[234:237], v[64:67]
	v_mfma_f32_16x16x32_bf16 v[116:119], v[184:187], v[214:217], v[116:119]
	v_mfma_f32_16x16x32_bf16 v[112:115], v[192:195], v[214:217], v[112:115]
	v_mfma_f32_16x16x32_bf16 v[100:103], v[184:187], v[222:225], v[100:103]
	v_mfma_f32_16x16x32_bf16 v[96:99], v[192:195], v[222:225], v[96:99]
	v_mfma_f32_16x16x32_bf16 v[84:87], v[184:187], v[230:233], v[84:87]
	v_mfma_f32_16x16x32_bf16 v[80:83], v[192:195], v[230:233], v[80:83]
	v_mfma_f32_16x16x32_bf16 v[68:71], v[184:187], v[238:241], v[68:71]
	v_mfma_f32_16x16x32_bf16 v[64:67], v[192:195], v[238:241], v[64:67]
	s_setprio 0
	s_barrier
; #define PG8_STAGE(bufoff, gbase, voff) do { _Pragma("unroll") for (int _i = 0; _i < 2; ++_i) \
;         __builtin_amdgcn_global_load_lds((const unsigned*)((const char*)(gbase) + (voff)[_i]), (PG8_LAS unsigned*)(lds + (bufoff) + ldsw + _i * 8192), 16, 0, 0); } while (0)
; #define PG8_LDA(dst, b, h) do { _Pragma("unroll") for (int m = 0; m < 4; ++m) _Pragma("unroll") for (int k = 0; k < 2; ++k) dst[m][k] = *(const PG8_LAS bf16x8*)(lds + PG8_SA(b, h) + aoff + m * 2048 + k * 1024); } while (0)
; #define PG8_WAIT_V(n) asm volatile("s_waitcnt vmcnt(" #n ")" ::: "memory")
; #define PG8_WAIT_L(n) asm volatile("s_waitcnt lgkmcnt(" #n ")" ::: "memory")
; #define PG8_BAR __builtin_amdgcn_s_barrier()
; template <class Epi, class Sched, bool ALIGN_EPI = false, bool SP2 = false>
; __device__ __forceinline__ void gemm_phase(PG8_LAS unsigned char* lds, const Gemm g, const Sched& S, const Epi& E, const int tid) {
;     ...
;         for (int t = 0; t < nt; t += 2) {
;             const bool last = (t == nt - 2);
;             const char* a1 = cA + (size_t)(t + 1) * kstep;
;             const char* a2 = last ? nA : cA + (size_t)(t + 2) * kstep; const char* b2 = last ? nB : cB + (size_t)(t + 2) * kstep;
;             const char* a3 = a2 + kstep; const char* b3 = b2 + kstep;
;             if (last && has_next) S.a_ready(nxt);
;             if constexpr (SP2) {
;             PG8_LDB(B0, 0, 0); PG8_LDB(B1, 0, 1); PG8_SCHED; PG8_LDA(At, 0, 0); PG8_STAGE(PG8_SA(1, 1), a1 + hstep, voffA);
;             PG8_WAIT_V(8); PG8_WAIT_L(0); PG8_BAR; PG8_MMA(0, 0, At, B0); PG8_MMA(0, 1, At, B1); PG8_BAR; PG8_SCHED;
;             PG8_LDA(At, 0, 1); PG8_STAGE(PG8_SB(0, 0), b2, voffB); PG8_STAGE(PG8_SB(0, 1), b2 + hstep, voffB); PG8_STAGE(PG8_SA(0, 0), a2, voffA);
;             PG8_WAIT_V(8); PG8_WAIT_L(0); PG8_BAR; PG8_MMA(1, 0, At, B0); PG8_MMA(1, 1, At, B1); PG8_BAR; PG8_SCHED;
;             PG8_LDB(B0, 1, 0); PG8_LDB(B1, 1, 1); PG8_SCHED; PG8_LDA(At, 1, 0); PG8_STAGE(PG8_SA(0, 1), a2 + hstep, voffA);
;             PG8_WAIT_V(8); PG8_WAIT_L(0); PG8_BAR; PG8_MMA(0, 0, At, B0); PG8_MMA(0, 1, At, B1); PG8_BAR; PG8_SCHED;
;             PG8_LDA(At, 1, 1); PG8_STAGE(PG8_SB(1, 0), b3, voffB); PG8_STAGE(PG8_SB(1, 1), b3 + hstep, voffB); PG8_STAGE(PG8_SA(1, 0), a3, voffA);
;             PG8_WAIT_V(8); PG8_WAIT_L(0); PG8_BAR; PG8_MMA(1, 0, At, B0); PG8_MMA(1, 1, At, B1); PG8_BAR; PG8_SCHED;
	s_add_i32 s20, s56, s27
	v_lshl_add_u64 v[158:159], v[158:159], 0, s[28:29]
	s_mov_b32 m0, s20
	ds_read_b128 v[208:211], v153 offset:49152
	ds_read_b128 v[214:217], v153 offset:50176
	ds_read_b128 v[218:221], v153 offset:51200
	ds_read_b128 v[222:225], v153 offset:52224
	ds_read_b128 v[226:229], v153 offset:53248
	ds_read_b128 v[230:233], v153 offset:54272
	ds_read_b128 v[234:237], v153 offset:55296
	ds_read_b128 v[238:241], v153 offset:56320
	global_load_lds_dwordx4 v[158:159], off
	s_add_i32 m0, s20, 0x2000
	s_add_u32 s16, s16, 0x40080
	v_lshl_add_u64 v[158:159], v[174:175], 0, s[28:29]
	s_addc_u32 s17, s17, 0
	s_add_i32 s20, s57, s27
	global_load_lds_dwordx4 v[158:159], off
	v_lshl_add_u64 v[158:159], s[16:17], 0, v[160:161]
	s_mov_b32 m0, s20
	s_nop 0
	global_load_lds_dwordx4 v[158:159], off
	v_lshl_add_u64 v[158:159], s[16:17], 0, v[132:133]
	s_add_i32 m0, s20, 0x2000
	s_nop 0
	global_load_lds_dwordx4 v[158:159], off
	v_lshl_add_u64 v[158:159], v[178:179], 0, s[28:29]
	s_mov_b32 m0, s81
	s_nop 0
	global_load_lds_dwordx4 v[158:159], off
	v_lshl_add_u64 v[158:159], v[180:181], 0, s[28:29]
	s_mov_b32 m0, s82
	s_nop 0
	global_load_lds_dwordx4 v[158:159], off
	s_waitcnt vmcnt(8)
	s_waitcnt lgkmcnt(0)
	s_barrier
	s_setprio 1
	s_waitcnt lgkmcnt(0)
	v_mfma_f32_16x16x32_bf16 v[60:63], v[140:143], v[208:211], v[60:63]
	v_mfma_f32_16x16x32_bf16 v[56:59], v[162:165], v[208:211], v[56:59]
	v_mfma_f32_16x16x32_bf16 v[44:47], v[140:143], v[218:221], v[44:47]
	v_mfma_f32_16x16x32_bf16 v[40:43], v[162:165], v[218:221], v[40:43]
	v_mfma_f32_16x16x32_bf16 v[28:31], v[140:143], v[226:229], v[28:31]
	v_mfma_f32_16x16x32_bf16 v[24:27], v[162:165], v[226:229], v[24:27]
	v_mfma_f32_16x16x32_bf16 v[12:15], v[140:143], v[234:237], v[12:15]
	v_mfma_f32_16x16x32_bf16 v[8:11], v[162:165], v[234:237], v[8:11]
	v_mfma_f32_16x16x32_bf16 v[60:63], v[154:157], v[214:217], v[60:63]
	v_mfma_f32_16x16x32_bf16 v[56:59], v[166:169], v[214:217], v[56:59]
	v_mfma_f32_16x16x32_bf16 v[44:47], v[154:157], v[222:225], v[44:47]
	v_mfma_f32_16x16x32_bf16 v[40:43], v[166:169], v[222:225], v[40:43]
	v_mfma_f32_16x16x32_bf16 v[28:31], v[154:157], v[230:233], v[28:31]
	v_mfma_f32_16x16x32_bf16 v[24:27], v[166:169], v[230:233], v[24:27]
	v_mfma_f32_16x16x32_bf16 v[12:15], v[154:157], v[238:241], v[12:15]
	v_mfma_f32_16x16x32_bf16 v[8:11], v[166:169], v[238:241], v[8:11]
	s_setprio 0
	s_setprio 1
	v_mfma_f32_16x16x32_bf16 v[52:55], v[170:173], v[208:211], v[52:55]
	s_add_i32 s51, s51, 2
	v_mfma_f32_16x16x32_bf16 v[48:51], v[188:191], v[208:211], v[48:51]
	s_add_u32 s14, s14, 0x100
	v_mfma_f32_16x16x32_bf16 v[36:39], v[170:173], v[218:221], v[36:39]
	s_addc_u32 s15, s15, 0
	v_mfma_f32_16x16x32_bf16 v[32:35], v[188:191], v[218:221], v[32:35]
	s_add_u32 s43, s43, 0x100
	v_mfma_f32_16x16x32_bf16 v[20:23], v[170:173], v[226:229], v[20:23]
	s_addc_u32 s49, s49, 0
	v_mfma_f32_16x16x32_bf16 v[16:19], v[188:191], v[226:229], v[16:19]
	s_cmp_gt_u32 s51, 13
	v_mfma_f32_16x16x32_bf16 v[4:7], v[170:173], v[234:237], v[4:7]
	v_mfma_f32_16x16x32_bf16 v[0:3], v[188:191], v[234:237], v[0:3]
	v_mfma_f32_16x16x32_bf16 v[52:55], v[184:187], v[214:217], v[52:55]
	v_mfma_f32_16x16x32_bf16 v[48:51], v[192:195], v[214:217], v[48:51]
	v_mfma_f32_16x16x32_bf16 v[36:39], v[184:187], v[222:225], v[36:39]
	v_mfma_f32_16x16x32_bf16 v[32:35], v[192:195], v[222:225], v[32:35]
	v_mfma_f32_16x16x32_bf16 v[20:23], v[184:187], v[230:233], v[20:23]
	v_mfma_f32_16x16x32_bf16 v[16:19], v[192:195], v[230:233], v[16:19]
	v_mfma_f32_16x16x32_bf16 v[4:7], v[184:187], v[238:241], v[4:7]
	v_mfma_f32_16x16x32_bf16 v[0:3], v[192:195], v[238:241], v[0:3]
	s_setprio 0
	s_barrier
	s_cbranch_scc1 .Lmy_kdone_1
.LBB0_467:
	s_add_u32 s16, s14, 0xfffc0080
	s_addc_u32 s17, s15, -1
	s_add_i32 s56, 0, 0x10000
	s_cmp_eq_u32 s51, 12
	s_cselect_b32 s21, s1, s17
	s_cselect_b32 s20, s36, s16
	v_add_u32_e32 v138, s56, v147
	s_cselect_b32 s17, s37, s49
	s_cselect_b32 s16, s42, s43
	s_add_i32 s58, 0, 0x14000
	ds_read_b128 v[140:143], v138
	ds_read_b128 v[154:157], v138 offset:1024
	ds_read_b128 v[162:165], v138 offset:2048
	ds_read_b128 v[166:169], v138 offset:3072
	v_add_u32_e32 v138, s58, v147
	ds_read_b128 v[170:173], v138
	ds_read_b128 v[184:187], v138 offset:1024
	ds_read_b128 v[188:191], v138 offset:2048
	ds_read_b128 v[192:195], v138 offset:3072
	v_lshl_add_u64 v[158:159], s[14:15], 0, v[134:135]
	s_add_i32 m0, s3, 0xc000
	ds_read_b128 v[208:211], v153
	ds_read_b128 v[214:217], v153 offset:1024
	ds_read_b128 v[218:221], v153 offset:2048
	ds_read_b128 v[222:225], v153 offset:3072
	ds_read_b128 v[226:229], v153 offset:4096
	ds_read_b128 v[230:233], v153 offset:5120
	ds_read_b128 v[234:237], v153 offset:6144
	ds_read_b128 v[238:241], v153 offset:7168
	global_load_lds_dwordx4 v[158:159], off
	v_lshl_add_u64 v[158:159], s[14:15], 0, v[136:137]
	s_add_i32 m0, s3, 0xe000
	s_nop 0
	global_load_lds_dwordx4 v[158:159], off
	s_waitcnt vmcnt(8)
	s_waitcnt lgkmcnt(0)
	s_barrier
; #define PG8_STAGE(bufoff, gbase, voff) do { _Pragma("unroll") for (int _i = 0; _i < 2; ++_i) \
;         __builtin_amdgcn_global_load_lds((const unsigned*)((const char*)(gbase) + (voff)[_i]), (PG8_LAS unsigned*)(lds + (bufoff) + ldsw + _i * 8192), 16, 0, 0); } while (0)
; #define PG8_LDA(dst, b, h) do { _Pragma("unroll") for (int m = 0; m < 4; ++m) _Pragma("unroll") for (int k = 0; k < 2; ++k) dst[m][k] = *(const PG8_LAS bf16x8*)(lds + PG8_SA(b, h) + aoff + m * 2048 + k * 1024); } while (0)
; #define PG8_MMA(ai, bj, At, Bt) do { __builtin_amdgcn_s_setprio(1); _Pragma("unroll") for (int m = 0; m < 4; ++m) _Pragma("unroll") for (int n = 0; n < 2; ++n) _Pragma("unroll") for (int k = 0; k < 2; ++k) \
;         acc[ai][bj][m][n] = __builtin_amdgcn_mfma_f32_16x16x32_bf16(Bt[n][k], At[m][k], acc[ai][bj][m][n], 0, 0, 0); __builtin_amdgcn_s_setprio(0); } while (0)
; #define PG8_WAIT_V(n) asm volatile("s_waitcnt vmcnt(" #n ")" ::: "memory")
; #define PG8_WAIT_L(n) asm volatile("s_waitcnt lgkmcnt(" #n ")" ::: "memory")
; #define PG8_BAR __builtin_amdgcn_s_barrier()
; #define PG8_SCHED __builtin_amdgcn_sched_barrier(0)
; template <class Epi, class Sched, bool ALIGN_EPI = false, bool SP2 = false>
; __device__ __forceinline__ void gemm_phase(PG8_LAS unsigned char* lds, const Gemm g, const Sched& S, const Epi& E, const int tid) {
;     ...
;             PG8_WAIT_V(8); PG8_WAIT_L(0); PG8_BAR; PG8_MMA(0, 0, At, B0); PG8_MMA(0, 1, At, B1); PG8_BAR; PG8_SCHED;
;             PG8_LDA(At, 0, 1); PG8_STAGE(PG8_SB(0, 0), b2, voffB); PG8_STAGE(PG8_SB(0, 1), b2 + hstep, voffB); PG8_STAGE(PG8_SA(0, 0), a2, voffA);
;             PG8_WAIT_V(8); PG8_WAIT_L(0); PG8_BAR; PG8_MMA(1, 0, At, B0); PG8_MMA(1, 1, At, B1); PG8_BAR; PG8_SCHED;
	s_setprio 1
	s_waitcnt lgkmcnt(0)
	v_mfma_f32_16x16x32_bf16 v[124:127], v[140:143], v[208:211], v[124:127]
	v_mfma_f32_16x16x32_bf16 v[120:123], v[162:165], v[208:211], v[120:123]
	v_mfma_f32_16x16x32_bf16 v[108:111], v[140:143], v[218:221], v[108:111]
	v_mfma_f32_16x16x32_bf16 v[104:107], v[162:165], v[218:221], v[104:107]
	v_mfma_f32_16x16x32_bf16 v[92:95], v[140:143], v[226:229], v[92:95]
	v_mfma_f32_16x16x32_bf16 v[88:91], v[162:165], v[226:229], v[88:91]
	v_mfma_f32_16x16x32_bf16 v[76:79], v[140:143], v[234:237], v[76:79]
	v_mfma_f32_16x16x32_bf16 v[72:75], v[162:165], v[234:237], v[72:75]
	v_mfma_f32_16x16x32_bf16 v[124:127], v[154:157], v[214:217], v[124:127]
	v_mfma_f32_16x16x32_bf16 v[120:123], v[166:169], v[214:217], v[120:123]
	v_mfma_f32_16x16x32_bf16 v[108:111], v[154:157], v[222:225], v[108:111]
	v_mfma_f32_16x16x32_bf16 v[104:107], v[166:169], v[222:225], v[104:107]
	v_mfma_f32_16x16x32_bf16 v[92:95], v[154:157], v[230:233], v[92:95]
	v_mfma_f32_16x16x32_bf16 v[88:91], v[166:169], v[230:233], v[88:91]
	v_mfma_f32_16x16x32_bf16 v[76:79], v[154:157], v[238:241], v[76:79]
	v_mfma_f32_16x16x32_bf16 v[72:75], v[166:169], v[238:241], v[72:75]
	s_setprio 0
	s_setprio 1
	v_mfma_f32_16x16x32_bf16 v[116:119], v[170:173], v[208:211], v[116:119]
	v_mfma_f32_16x16x32_bf16 v[112:115], v[188:191], v[208:211], v[112:115]
	v_mfma_f32_16x16x32_bf16 v[100:103], v[170:173], v[218:221], v[100:103]
	v_mfma_f32_16x16x32_bf16 v[96:99], v[188:191], v[218:221], v[96:99]
	v_mfma_f32_16x16x32_bf16 v[84:87], v[170:173], v[226:229], v[84:87]
	v_mfma_f32_16x16x32_bf16 v[80:83], v[188:191], v[226:229], v[80:83]
	v_mfma_f32_16x16x32_bf16 v[68:71], v[170:173], v[234:237], v[68:71]
	v_mfma_f32_16x16x32_bf16 v[64:67], v[188:191], v[234:237], v[64:67]
	v_mfma_f32_16x16x32_bf16 v[116:119], v[184:187], v[214:217], v[116:119]
	v_mfma_f32_16x16x32_bf16 v[112:115], v[192:195], v[214:217], v[112:115]
	v_mfma_f32_16x16x32_bf16 v[100:103], v[184:187], v[222:225], v[100:103]
	v_mfma_f32_16x16x32_bf16 v[96:99], v[192:195], v[222:225], v[96:99]
	v_mfma_f32_16x16x32_bf16 v[84:87], v[184:187], v[230:233], v[84:87]
	v_mfma_f32_16x16x32_bf16 v[80:83], v[192:195], v[230:233], v[80:83]
	v_mfma_f32_16x16x32_bf16 v[68:71], v[184:187], v[238:241], v[68:71]
	v_mfma_f32_16x16x32_bf16 v[64:67], v[192:195], v[238:241], v[64:67]
	s_setprio 0
	s_barrier
	s_add_i32 s56, s56, s27
	v_lshl_add_u64 v[158:159], s[16:17], 0, v[160:161]
	s_mov_b32 m0, s56
	ds_read_b128 v[208:211], v153 offset:16384
	ds_read_b128 v[214:217], v153 offset:17408
	ds_read_b128 v[218:221], v153 offset:18432
	ds_read_b128 v[222:225], v153 offset:19456
	ds_read_b128 v[226:229], v153 offset:20480
	ds_read_b128 v[230:233], v153 offset:21504
	ds_read_b128 v[234:237], v153 offset:22528
	ds_read_b128 v[238:241], v153 offset:23552
	global_load_lds_dwordx4 v[158:159], off
	s_add_i32 m0, s56, 0x2000
	s_add_u32 s56, s16, 0x40000
	v_lshl_add_u64 v[174:175], s[16:17], 0, v[132:133]
	s_addc_u32 s57, s17, 0
	s_add_i32 s58, s58, s27
	global_load_lds_dwordx4 v[174:175], off
	v_lshl_add_u64 v[178:179], s[56:57], 0, v[160:161]
	s_mov_b32 m0, s58
	v_lshl_add_u64 v[180:181], s[20:21], 0, v[130:131]
	global_load_lds_dwordx4 v[178:179], off
	v_lshl_add_u64 v[178:179], s[56:57], 0, v[132:133]
	s_add_i32 m0, s58, 0x2000
	s_nop 0
	global_load_lds_dwordx4 v[178:179], off
	v_lshl_add_u64 v[178:179], s[20:21], 0, v[128:129]
	s_mov_b32 m0, s3
	s_nop 0
	global_load_lds_dwordx4 v[178:179], off
	s_mov_b32 m0, s30
	s_nop 0
	global_load_lds_dwordx4 v[180:181], off
	s_waitcnt vmcnt(8)
	s_waitcnt lgkmcnt(0)
	s_barrier
	s_setprio 1
	s_waitcnt lgkmcnt(0)
	v_mfma_f32_16x16x32_bf16 v[60:63], v[140:143], v[208:211], v[60:63]
	v_mfma_f32_16x16x32_bf16 v[56:59], v[162:165], v[208:211], v[56:59]
	v_mfma_f32_16x16x32_bf16 v[44:47], v[140:143], v[218:221], v[44:47]
	v_mfma_f32_16x16x32_bf16 v[40:43], v[162:165], v[218:221], v[40:43]
	v_mfma_f32_16x16x32_bf16 v[28:31], v[140:143], v[226:229], v[28:31]
	v_mfma_f32_16x16x32_bf16 v[24:27], v[162:165], v[226:229], v[24:27]
	v_mfma_f32_16x16x32_bf16 v[12:15], v[140:143], v[234:237], v[12:15]
	v_mfma_f32_16x16x32_bf16 v[8:11], v[162:165], v[234:237], v[8:11]
	v_mfma_f32_16x16x32_bf16 v[60:63], v[154:157], v[214:217], v[60:63]
	v_mfma_f32_16x16x32_bf16 v[56:59], v[166:169], v[214:217], v[56:59]
	v_mfma_f32_16x16x32_bf16 v[44:47], v[154:157], v[222:225], v[44:47]
	v_mfma_f32_16x16x32_bf16 v[40:43], v[166:169], v[222:225], v[40:43]
	v_mfma_f32_16x16x32_bf16 v[28:31], v[154:157], v[230:233], v[28:31]
	v_mfma_f32_16x16x32_bf16 v[24:27], v[166:169], v[230:233], v[24:27]
	v_mfma_f32_16x16x32_bf16 v[12:15], v[154:157], v[238:241], v[12:15]
	v_mfma_f32_16x16x32_bf16 v[8:11], v[166:169], v[238:241], v[8:11]
	s_setprio 0
	s_setprio 1
	v_mfma_f32_16x16x32_bf16 v[52:55], v[170:173], v[208:211], v[52:55]
	v_mfma_f32_16x16x32_bf16 v[48:51], v[188:191], v[208:211], v[48:51]
	v_mfma_f32_16x16x32_bf16 v[36:39], v[170:173], v[218:221], v[36:39]
	v_mfma_f32_16x16x32_bf16 v[32:35], v[188:191], v[218:221], v[32:35]
	v_mfma_f32_16x16x32_bf16 v[20:23], v[170:173], v[226:229], v[20:23]
	v_mfma_f32_16x16x32_bf16 v[16:19], v[188:191], v[226:229], v[16:19]
	v_mfma_f32_16x16x32_bf16 v[4:7], v[170:173], v[234:237], v[4:7]
	v_mfma_f32_16x16x32_bf16 v[0:3], v[188:191], v[234:237], v[0:3]
	v_mfma_f32_16x16x32_bf16 v[52:55], v[184:187], v[214:217], v[52:55]
	v_mfma_f32_16x16x32_bf16 v[48:51], v[192:195], v[214:217], v[48:51]
	v_mfma_f32_16x16x32_bf16 v[36:39], v[184:187], v[222:225], v[36:39]
	v_mfma_f32_16x16x32_bf16 v[32:35], v[192:195], v[222:225], v[32:35]
	v_mfma_f32_16x16x32_bf16 v[20:23], v[184:187], v[230:233], v[20:23]
	v_mfma_f32_16x16x32_bf16 v[16:19], v[192:195], v[230:233], v[16:19]
	v_mfma_f32_16x16x32_bf16 v[4:7], v[184:187], v[238:241], v[4:7]
	v_mfma_f32_16x16x32_bf16 v[0:3], v[192:195], v[238:241], v[0:3]
	s_setprio 0
	s_barrier
; #define PG8_STAGE(bufoff, gbase, voff) do { _Pragma("unroll") for (int _i = 0; _i < 2; ++_i) \
;         __builtin_amdgcn_global_load_lds((const unsigned*)((const char*)(gbase) + (voff)[_i]), (PG8_LAS unsigned*)(lds + (bufoff) + ldsw + _i * 8192), 16, 0, 0); } while (0)
; #define PG8_LDA(dst, b, h) do { _Pragma("unroll") for (int m = 0; m < 4; ++m) _Pragma("unroll") for (int k = 0; k < 2; ++k) dst[m][k] = *(const PG8_LAS bf16x8*)(lds + PG8_SA(b, h) + aoff + m * 2048 + k * 1024); } while (0)
; #define PG8_LDB(dst, b, h) do { _Pragma("unroll") for (int n = 0; n < 2; ++n) _Pragma("unroll") for (int k = 0; k < 2; ++k) dst[n][k] = *(const PG8_LAS bf16x8*)(lds + PG8_SB(b, h) + boff + n * 2048 + k * 1024); } while (0)
; #define PG8_MMA(ai, bj, At, Bt) do { __builtin_amdgcn_s_setprio(1); _Pragma("unroll") for (int m = 0; m < 4; ++m) _Pragma("unroll") for (int n = 0; n < 2; ++n) _Pragma("unroll") for (int k = 0; k < 2; ++k) \
;         acc[ai][bj][m][n] = __builtin_amdgcn_mfma_f32_16x16x32_bf16(Bt[n][k], At[m][k], acc[ai][bj][m][n], 0, 0, 0); __builtin_amdgcn_s_setprio(0); } while (0)
; #define PG8_WAIT_V(n) asm volatile("s_waitcnt vmcnt(" #n ")" ::: "memory")
; #define PG8_WAIT_L(n) asm volatile("s_waitcnt lgkmcnt(" #n ")" ::: "memory")
; #define PG8_BAR __builtin_amdgcn_s_barrier()
; #define PG8_SCHED __builtin_amdgcn_sched_barrier(0)
; template <class Epi, class Sched, bool ALIGN_EPI = false, bool SP2 = false>
; __device__ __forceinline__ void gemm_phase(PG8_LAS unsigned char* lds, const Gemm g, const Sched& S, const Epi& E, const int tid) {
;     ...
;             PG8_LDB(B0, 1, 0); PG8_LDB(B1, 1, 1); PG8_SCHED; PG8_LDA(At, 1, 0); PG8_STAGE(PG8_SA(0, 1), a2 + hstep, voffA);
;             PG8_WAIT_V(8); PG8_WAIT_L(0); PG8_BAR; PG8_MMA(0, 0, At, B0); PG8_MMA(0, 1, At, B1); PG8_BAR; PG8_SCHED;
	s_add_i32 s56, 0, 0x18000
	v_add_u32_e32 v138, s56, v147
	s_add_i32 s57, 0, 0x1c000
	ds_read_b128 v[140:143], v138
	ds_read_b128 v[154:157], v138 offset:1024
	ds_read_b128 v[162:165], v138 offset:2048
	ds_read_b128 v[166:169], v138 offset:3072
	v_add_u32_e32 v138, s57, v147
	ds_read_b128 v[170:173], v138
	ds_read_b128 v[184:187], v138 offset:1024
	ds_read_b128 v[188:191], v138 offset:2048
	ds_read_b128 v[192:195], v138 offset:3072
	s_add_u32 s20, s20, 0x40000
	s_addc_u32 s21, s21, 0
	s_mov_b32 m0, s31
	v_lshl_add_u64 v[196:197], s[20:21], 0, v[128:129]
	ds_read_b128 v[208:211], v153 offset:32768
	ds_read_b128 v[214:217], v153 offset:33792
	ds_read_b128 v[218:221], v153 offset:34816
	ds_read_b128 v[222:225], v153 offset:35840
	ds_read_b128 v[226:229], v153 offset:36864
	ds_read_b128 v[230:233], v153 offset:37888
	ds_read_b128 v[234:237], v153 offset:38912
	ds_read_b128 v[238:241], v153 offset:39936
	global_load_lds_dwordx4 v[196:197], off
	v_lshl_add_u64 v[196:197], s[20:21], 0, v[130:131]
	s_mov_b32 m0, s34
	s_nop 0
	global_load_lds_dwordx4 v[196:197], off
	s_waitcnt vmcnt(8)
	s_waitcnt lgkmcnt(0)
	s_barrier
	s_setprio 1
	s_waitcnt lgkmcnt(0)
	v_mfma_f32_16x16x32_bf16 v[124:127], v[140:143], v[208:211], v[124:127]
	v_mfma_f32_16x16x32_bf16 v[120:123], v[162:165], v[208:211], v[120:123]
	v_mfma_f32_16x16x32_bf16 v[108:111], v[140:143], v[218:221], v[108:111]
	v_mfma_f32_16x16x32_bf16 v[104:107], v[162:165], v[218:221], v[104:107]
	v_mfma_f32_16x16x32_bf16 v[92:95], v[140:143], v[226:229], v[92:95]
	v_mfma_f32_16x16x32_bf16 v[88:91], v[162:165], v[226:229], v[88:91]
	v_mfma_f32_16x16x32_bf16 v[76:79], v[140:143], v[234:237], v[76:79]
	v_mfma_f32_16x16x32_bf16 v[72:75], v[162:165], v[234:237], v[72:75]
	v_mfma_f32_16x16x32_bf16 v[124:127], v[154:157], v[214:217], v[124:127]
	v_mfma_f32_16x16x32_bf16 v[120:123], v[166:169], v[214:217], v[120:123]
	v_mfma_f32_16x16x32_bf16 v[108:111], v[154:157], v[222:225], v[108:111]
	v_mfma_f32_16x16x32_bf16 v[104:107], v[166:169], v[222:225], v[104:107]
	v_mfma_f32_16x16x32_bf16 v[92:95], v[154:157], v[230:233], v[92:95]
	v_mfma_f32_16x16x32_bf16 v[88:91], v[166:169], v[230:233], v[88:91]
	v_mfma_f32_16x16x32_bf16 v[76:79], v[154:157], v[238:241], v[76:79]
	v_mfma_f32_16x16x32_bf16 v[72:75], v[166:169], v[238:241], v[72:75]
	s_setprio 0
	s_setprio 1
	v_mfma_f32_16x16x32_bf16 v[116:119], v[170:173], v[208:211], v[116:119]
	v_mfma_f32_16x16x32_bf16 v[112:115], v[188:191], v[208:211], v[112:115]
	v_mfma_f32_16x16x32_bf16 v[100:103], v[170:173], v[218:221], v[100:103]
	v_mfma_f32_16x16x32_bf16 v[96:99], v[188:191], v[218:221], v[96:99]
	v_mfma_f32_16x16x32_bf16 v[84:87], v[170:173], v[226:229], v[84:87]
	v_mfma_f32_16x16x32_bf16 v[80:83], v[188:191], v[226:229], v[80:83]
	v_mfma_f32_16x16x32_bf16 v[68:71], v[170:173], v[234:237], v[68:71]
	v_mfma_f32_16x16x32_bf16 v[64:67], v[188:191], v[234:237], v[64:67]
	v_mfma_f32_16x16x32_bf16 v[116:119], v[184:187], v[214:217], v[116:119]
	v_mfma_f32_16x16x32_bf16 v[112:115], v[192:195], v[214:217], v[112:115]
	v_mfma_f32_16x16x32_bf16 v[100:103], v[184:187], v[222:225], v[100:103]
	v_mfma_f32_16x16x32_bf16 v[96:99], v[192:195], v[222:225], v[96:99]
	v_mfma_f32_16x16x32_bf16 v[84:87], v[184:187], v[230:233], v[84:87]
	v_mfma_f32_16x16x32_bf16 v[80:83], v[192:195], v[230:233], v[80:83]
	v_mfma_f32_16x16x32_bf16 v[68:71], v[184:187], v[238:241], v[68:71]
	v_mfma_f32_16x16x32_bf16 v[64:67], v[192:195], v[238:241], v[64:67]
	s_setprio 0
	s_barrier
; #define PG8_STAGE(bufoff, gbase, voff) do { _Pragma("unroll") for (int _i = 0; _i < 2; ++_i) \
;         __builtin_amdgcn_global_load_lds((const unsigned*)((const char*)(gbase) + (voff)[_i]), (PG8_LAS unsigned*)(lds + (bufoff) + ldsw + _i * 8192), 16, 0, 0); } while (0)
; #define PG8_LDA(dst, b, h) do { _Pragma("unroll") for (int m = 0; m < 4; ++m) _Pragma("unroll") for (int k = 0; k < 2; ++k) dst[m][k] = *(const PG8_LAS bf16x8*)(lds + PG8_SA(b, h) + aoff + m * 2048 + k * 1024); } while (0)
; #define PG8_MMA(ai, bj, At, Bt) do { __builtin_amdgcn_s_setprio(1); _Pragma("unroll") for (int m = 0; m < 4; ++m) _Pragma("unroll") for (int n = 0; n < 2; ++n) _Pragma("unroll") for (int k = 0; k < 2; ++k) \
;         acc[ai][bj][m][n] = __builtin_amdgcn_mfma_f32_16x16x32_bf16(Bt[n][k], At[m][k], acc[ai][bj][m][n], 0, 0, 0); __builtin_amdgcn_s_setprio(0); } while (0)
; #define PG8_WAIT_V(n) asm volatile("s_waitcnt vmcnt(" #n ")" ::: "memory")
; #define PG8_WAIT_L(n) asm volatile("s_waitcnt lgkmcnt(" #n ")" ::: "memory")
; #define PG8_BAR __builtin_amdgcn_s_barrier()
; #define PG8_SCHED __builtin_amdgcn_sched_barrier(0)
; template <class Epi, class Sched, bool ALIGN_EPI = false, bool SP2 = false>
; __device__ __forceinline__ void gemm_phase(PG8_LAS unsigned char* lds, const Gemm g, const Sched& S, const Epi& E, const int tid) {
;     ...
;             PG8_LDA(At, 1, 1); PG8_STAGE(PG8_SB(1, 0), b3, voffB); PG8_STAGE(PG8_SB(1, 1), b3 + hstep, voffB); PG8_STAGE(PG8_SA(1, 0), a3, voffA);
;             PG8_WAIT_V(8); PG8_WAIT_L(0); PG8_BAR; PG8_MMA(1, 0, At, B0); PG8_MMA(1, 1, At, B1); PG8_BAR; PG8_SCHED;
	s_add_i32 s20, s56, s27
	v_lshl_add_u64 v[158:159], v[158:159], 0, s[28:29]
	s_mov_b32 m0, s20
	ds_read_b128 v[208:211], v153 offset:49152
	ds_read_b128 v[214:217], v153 offset:50176
	ds_read_b128 v[218:221], v153 offset:51200
	ds_read_b128 v[222:225], v153 offset:52224
	ds_read_b128 v[226:229], v153 offset:53248
	ds_read_b128 v[230:233], v153 offset:54272
	ds_read_b128 v[234:237], v153 offset:55296
	ds_read_b128 v[238:241], v153 offset:56320
	global_load_lds_dwordx4 v[158:159], off
	s_add_i32 m0, s20, 0x2000
	s_add_u32 s16, s16, 0x40080
	v_lshl_add_u64 v[158:159], v[174:175], 0, s[28:29]
	s_addc_u32 s17, s17, 0
	s_add_i32 s20, s57, s27
	global_load_lds_dwordx4 v[158:159], off
	v_lshl_add_u64 v[158:159], s[16:17], 0, v[160:161]
	s_mov_b32 m0, s20
	s_nop 0
	global_load_lds_dwordx4 v[158:159], off
	v_lshl_add_u64 v[158:159], s[16:17], 0, v[132:133]
	s_add_i32 m0, s20, 0x2000
	s_nop 0
	global_load_lds_dwordx4 v[158:159], off
	v_lshl_add_u64 v[158:159], v[178:179], 0, s[28:29]
	s_mov_b32 m0, s81
	s_nop 0
	global_load_lds_dwordx4 v[158:159], off
	v_lshl_add_u64 v[158:159], v[180:181], 0, s[28:29]
	s_mov_b32 m0, s82
	s_nop 0
	global_load_lds_dwordx4 v[158:159], off
	s_waitcnt vmcnt(8)
	s_waitcnt lgkmcnt(0)
	s_barrier
	s_setprio 1
	s_waitcnt lgkmcnt(0)
	v_mfma_f32_16x16x32_bf16 v[60:63], v[140:143], v[208:211], v[60:63]
	v_mfma_f32_16x16x32_bf16 v[56:59], v[162:165], v[208:211], v[56:59]
	v_mfma_f32_16x16x32_bf16 v[44:47], v[140:143], v[218:221], v[44:47]
	v_mfma_f32_16x16x32_bf16 v[40:43], v[162:165], v[218:221], v[40:43]
	v_mfma_f32_16x16x32_bf16 v[28:31], v[140:143], v[226:229], v[28:31]
	v_mfma_f32_16x16x32_bf16 v[24:27], v[162:165], v[226:229], v[24:27]
	v_mfma_f32_16x16x32_bf16 v[12:15], v[140:143], v[234:237], v[12:15]
	v_mfma_f32_16x16x32_bf16 v[8:11], v[162:165], v[234:237], v[8:11]
	v_mfma_f32_16x16x32_bf16 v[60:63], v[154:157], v[214:217], v[60:63]
	v_mfma_f32_16x16x32_bf16 v[56:59], v[166:169], v[214:217], v[56:59]
	v_mfma_f32_16x16x32_bf16 v[44:47], v[154:157], v[222:225], v[44:47]
	v_mfma_f32_16x16x32_bf16 v[40:43], v[166:169], v[222:225], v[40:43]
	v_mfma_f32_16x16x32_bf16 v[28:31], v[154:157], v[230:233], v[28:31]
	v_mfma_f32_16x16x32_bf16 v[24:27], v[166:169], v[230:233], v[24:27]
	v_mfma_f32_16x16x32_bf16 v[12:15], v[154:157], v[238:241], v[12:15]
	v_mfma_f32_16x16x32_bf16 v[8:11], v[166:169], v[238:241], v[8:11]
	s_setprio 0
	s_setprio 1
	v_mfma_f32_16x16x32_bf16 v[52:55], v[170:173], v[208:211], v[52:55]
	s_add_i32 s51, s51, 2
	v_mfma_f32_16x16x32_bf16 v[48:51], v[188:191], v[208:211], v[48:51]
	s_add_u32 s14, s14, 0x100
	v_mfma_f32_16x16x32_bf16 v[36:39], v[170:173], v[218:221], v[36:39]
	s_addc_u32 s15, s15, 0
	v_mfma_f32_16x16x32_bf16 v[32:35], v[188:191], v[218:221], v[32:35]
	s_add_u32 s43, s43, 0x100
	v_mfma_f32_16x16x32_bf16 v[20:23], v[170:173], v[226:229], v[20:23]
	s_addc_u32 s49, s49, 0
	v_mfma_f32_16x16x32_bf16 v[16:19], v[188:191], v[226:229], v[16:19]
	s_cmp_gt_u32 s51, 13
	v_mfma_f32_16x16x32_bf16 v[4:7], v[170:173], v[234:237], v[4:7]
	v_mfma_f32_16x16x32_bf16 v[0:3], v[188:191], v[234:237], v[0:3]
	v_mfma_f32_16x16x32_bf16 v[52:55], v[184:187], v[214:217], v[52:55]
	v_mfma_f32_16x16x32_bf16 v[48:51], v[192:195], v[214:217], v[48:51]
	v_mfma_f32_16x16x32_bf16 v[36:39], v[184:187], v[222:225], v[36:39]
	v_mfma_f32_16x16x32_bf16 v[32:35], v[192:195], v[222:225], v[32:35]
	v_mfma_f32_16x16x32_bf16 v[20:23], v[184:187], v[230:233], v[20:23]
	v_mfma_f32_16x16x32_bf16 v[16:19], v[192:195], v[230:233], v[16:19]
	v_mfma_f32_16x16x32_bf16 v[4:7], v[184:187], v[238:241], v[4:7]
	v_mfma_f32_16x16x32_bf16 v[0:3], v[192:195], v[238:241], v[0:3]
	s_setprio 0
	s_barrier
	s_cbranch_scc0 .LBB0_467

; #define PG8_STAGE(bufoff, gbase, voff) do { _Pragma("unroll") for (int _i = 0; _i < 2; ++_i) \
;         __builtin_amdgcn_global_load_lds((const unsigned*)((const char*)(gbase) + (voff)[_i]), (PG8_LAS unsigned*)(lds + (bufoff) + ldsw + _i * 8192), 16, 0, 0); } while (0)
; #define PG8_LDA(dst, b, h) do { _Pragma("unroll") for (int m = 0; m < 4; ++m) _Pragma("unroll") for (int k = 0; k < 2; ++k) dst[m][k] = *(const PG8_LAS bf16x8*)(lds + PG8_SA(b, h) + aoff + m * 2048 + k * 1024); } while (0)
; #define PG8_LDB(dst, b, h) do { _Pragma("unroll") for (int n = 0; n < 2; ++n) _Pragma("unroll") for (int k = 0; k < 2; ++k) dst[n][k] = *(const PG8_LAS bf16x8*)(lds + PG8_SB(b, h) + boff + n * 2048 + k * 1024); } while (0)
; #define PG8_MMA(ai, bj, At, Bt) do { __builtin_amdgcn_s_setprio(1); _Pragma("unroll") for (int m = 0; m < 4; ++m) _Pragma("unroll") for (int n = 0; n < 2; ++n) _Pragma("unroll") for (int k = 0; k < 2; ++k) \
;         acc[ai][bj][m][n] = __builtin_amdgcn_mfma_f32_16x16x32_bf16(Bt[n][k], At[m][k], acc[ai][bj][m][n], 0, 0, 0); __builtin_amdgcn_s_setprio(0); } while (0)
; #define PG8_WAIT_V(n) asm volatile("s_waitcnt vmcnt(" #n ")" ::: "memory")
; #define PG8_WAIT_L(n) asm volatile("s_waitcnt lgkmcnt(" #n ")" ::: "memory")
; #define PG8_BAR __builtin_amdgcn_s_barrier()
; #define PG8_SCHED __builtin_amdgcn_sched_barrier(0)
; template <class Epi, class Sched, bool ALIGN_EPI = false, bool SP2 = false>
; __device__ __forceinline__ void gemm_phase(PG8_LAS unsigned char* lds, const Gemm g, const Sched& S, const Epi& E, const int tid) {
;     ...
;             PG8_WAIT_V(8); PG8_WAIT_L(0); PG8_BAR; PG8_MMA(1, 0, At, B0); PG8_MMA(1, 1, At, B1); PG8_BAR; PG8_SCHED;
;             PG8_LDB(B0, 1, 0); PG8_LDB(B1, 1, 1); PG8_SCHED; PG8_LDA(At, 1, 0); PG8_STAGE(PG8_SA(0, 1), a2 + hstep, voffA);
;             PG8_WAIT_V(8); PG8_WAIT_L(0); PG8_BAR; PG8_MMA(0, 0, At, B0); PG8_MMA(0, 1, At, B1); PG8_BAR; PG8_SCHED;
.Lmy_wj_2:
	s_waitcnt lgkmcnt(0)
	s_barrier
	s_setprio 1
	s_waitcnt lgkmcnt(0)
	v_mfma_f32_16x16x32_bf16 v[60:63], v[150:153], v[208:211], 0
	v_mfma_f32_16x16x32_bf16 v[52:55], v[162:165], v[208:211], 0
	v_mfma_f32_16x16x32_bf16 v[44:47], v[150:153], v[218:221], 0
	v_mfma_f32_16x16x32_bf16 v[36:39], v[162:165], v[218:221], 0
	v_mfma_f32_16x16x32_bf16 v[28:31], v[150:153], v[226:229], 0
	v_mfma_f32_16x16x32_bf16 v[20:23], v[162:165], v[226:229], 0
	v_mfma_f32_16x16x32_bf16 v[12:15], v[150:153], v[234:237], 0
	v_mfma_f32_16x16x32_bf16 v[4:7], v[162:165], v[234:237], 0
	v_mfma_f32_16x16x32_bf16 v[60:63], v[154:157], v[214:217], v[60:63]
	v_mfma_f32_16x16x32_bf16 v[52:55], v[166:169], v[214:217], v[52:55]
	v_mfma_f32_16x16x32_bf16 v[44:47], v[154:157], v[222:225], v[44:47]
	v_mfma_f32_16x16x32_bf16 v[36:39], v[166:169], v[222:225], v[36:39]
	v_mfma_f32_16x16x32_bf16 v[28:31], v[154:157], v[230:233], v[28:31]
	v_mfma_f32_16x16x32_bf16 v[20:23], v[166:169], v[230:233], v[20:23]
	v_mfma_f32_16x16x32_bf16 v[12:15], v[154:157], v[238:241], v[12:15]
	v_mfma_f32_16x16x32_bf16 v[4:7], v[166:169], v[238:241], v[4:7]
	s_setprio 0
	s_setprio 1
	v_mfma_f32_16x16x32_bf16 v[56:59], v[170:173], v[208:211], 0
	v_mfma_f32_16x16x32_bf16 v[48:51], v[188:191], v[208:211], 0
	v_mfma_f32_16x16x32_bf16 v[40:43], v[170:173], v[218:221], 0
	v_mfma_f32_16x16x32_bf16 v[32:35], v[188:191], v[218:221], 0
	v_mfma_f32_16x16x32_bf16 v[24:27], v[170:173], v[226:229], 0
	v_mfma_f32_16x16x32_bf16 v[16:19], v[188:191], v[226:229], 0
	v_mfma_f32_16x16x32_bf16 v[8:11], v[170:173], v[234:237], 0
	v_mfma_f32_16x16x32_bf16 v[0:3], v[188:191], v[234:237], 0
	v_mfma_f32_16x16x32_bf16 v[56:59], v[184:187], v[214:217], v[56:59]
	v_mfma_f32_16x16x32_bf16 v[48:51], v[192:195], v[214:217], v[48:51]
	v_mfma_f32_16x16x32_bf16 v[40:43], v[184:187], v[222:225], v[40:43]
	v_mfma_f32_16x16x32_bf16 v[32:35], v[192:195], v[222:225], v[32:35]
	v_mfma_f32_16x16x32_bf16 v[24:27], v[184:187], v[230:233], v[24:27]
	v_mfma_f32_16x16x32_bf16 v[16:19], v[192:195], v[230:233], v[16:19]
	v_mfma_f32_16x16x32_bf16 v[8:11], v[184:187], v[238:241], v[8:11]
	v_mfma_f32_16x16x32_bf16 v[0:3], v[192:195], v[238:241], v[0:3]
	s_setprio 0
	s_barrier
	s_add_i32 s52, 0, 0x18000
	v_add_u32_e32 v138, s52, v141
	s_add_i32 s53, 0, 0x1c000
	ds_read_b128 v[150:153], v138
	ds_read_b128 v[154:157], v138 offset:1024
	ds_read_b128 v[162:165], v138 offset:2048
	ds_read_b128 v[166:169], v138 offset:3072
	v_add_u32_e32 v138, s53, v141
	ds_read_b128 v[170:173], v138
	ds_read_b128 v[184:187], v138 offset:1024
	ds_read_b128 v[188:191], v138 offset:2048
	ds_read_b128 v[192:195], v138 offset:3072
	s_add_u32 s22, s22, 0x40000
	s_addc_u32 s23, s23, 0
	s_mov_b32 m0, s45
	v_lshl_add_u64 v[196:197], s[22:23], 0, v[128:129]
	ds_read_b128 v[208:211], v149 offset:32768
	ds_read_b128 v[214:217], v149 offset:33792
	ds_read_b128 v[218:221], v149 offset:34816
	ds_read_b128 v[222:225], v149 offset:35840
	ds_read_b128 v[226:229], v149 offset:36864
	ds_read_b128 v[230:233], v149 offset:37888
	ds_read_b128 v[234:237], v149 offset:38912
	ds_read_b128 v[238:241], v149 offset:39936
	global_load_lds_dwordx4 v[196:197], off
	v_lshl_add_u64 v[196:197], s[22:23], 0, v[130:131]
	s_mov_b32 m0, s46
	s_nop 0
	global_load_lds_dwordx4 v[196:197], off
	s_waitcnt vmcnt(8)
	s_waitcnt lgkmcnt(0)
	s_barrier
	s_setprio 1
	s_waitcnt lgkmcnt(0)
	v_mfma_f32_16x16x32_bf16 v[124:127], v[150:153], v[208:211], v[124:127]
	v_mfma_f32_16x16x32_bf16 v[116:119], v[162:165], v[208:211], v[116:119]
	v_mfma_f32_16x16x32_bf16 v[108:111], v[150:153], v[218:221], v[108:111]
	v_mfma_f32_16x16x32_bf16 v[100:103], v[162:165], v[218:221], v[100:103]
	v_mfma_f32_16x16x32_bf16 v[92:95], v[150:153], v[226:229], v[92:95]
	v_mfma_f32_16x16x32_bf16 v[84:87], v[162:165], v[226:229], v[84:87]
	v_mfma_f32_16x16x32_bf16 v[76:79], v[150:153], v[234:237], v[76:79]
	v_mfma_f32_16x16x32_bf16 v[68:71], v[162:165], v[234:237], v[68:71]
	v_mfma_f32_16x16x32_bf16 v[124:127], v[154:157], v[214:217], v[124:127]
	v_mfma_f32_16x16x32_bf16 v[116:119], v[166:169], v[214:217], v[116:119]
	v_mfma_f32_16x16x32_bf16 v[108:111], v[154:157], v[222:225], v[108:111]
	v_mfma_f32_16x16x32_bf16 v[100:103], v[166:169], v[222:225], v[100:103]
	v_mfma_f32_16x16x32_bf16 v[92:95], v[154:157], v[230:233], v[92:95]
	v_mfma_f32_16x16x32_bf16 v[84:87], v[166:169], v[230:233], v[84:87]
	v_mfma_f32_16x16x32_bf16 v[76:79], v[154:157], v[238:241], v[76:79]
	v_mfma_f32_16x16x32_bf16 v[68:71], v[166:169], v[238:241], v[68:71]
	s_setprio 0
	s_setprio 1
	v_mfma_f32_16x16x32_bf16 v[120:123], v[170:173], v[208:211], v[120:123]
	v_mfma_f32_16x16x32_bf16 v[112:115], v[188:191], v[208:211], v[112:115]
	v_mfma_f32_16x16x32_bf16 v[104:107], v[170:173], v[218:221], v[104:107]
	v_mfma_f32_16x16x32_bf16 v[96:99], v[188:191], v[218:221], v[96:99]
	v_mfma_f32_16x16x32_bf16 v[88:91], v[170:173], v[226:229], v[88:91]
	v_mfma_f32_16x16x32_bf16 v[80:83], v[188:191], v[226:229], v[80:83]
	v_mfma_f32_16x16x32_bf16 v[72:75], v[170:173], v[234:237], v[72:75]
	v_mfma_f32_16x16x32_bf16 v[64:67], v[188:191], v[234:237], v[64:67]
	v_mfma_f32_16x16x32_bf16 v[120:123], v[184:187], v[214:217], v[120:123]
	v_mfma_f32_16x16x32_bf16 v[112:115], v[192:195], v[214:217], v[112:115]
	v_mfma_f32_16x16x32_bf16 v[104:107], v[184:187], v[222:225], v[104:107]
	v_mfma_f32_16x16x32_bf16 v[96:99], v[192:195], v[222:225], v[96:99]
	v_mfma_f32_16x16x32_bf16 v[88:91], v[184:187], v[230:233], v[88:91]
	v_mfma_f32_16x16x32_bf16 v[80:83], v[192:195], v[230:233], v[80:83]
	v_mfma_f32_16x16x32_bf16 v[72:75], v[184:187], v[238:241], v[72:75]
	v_mfma_f32_16x16x32_bf16 v[64:67], v[192:195], v[238:241], v[64:67]
	s_setprio 0
	s_barrier
; #define PG8_STAGE(bufoff, gbase, voff) do { _Pragma("unroll") for (int _i = 0; _i < 2; ++_i) \
;         __builtin_amdgcn_global_load_lds((const unsigned*)((const char*)(gbase) + (voff)[_i]), (PG8_LAS unsigned*)(lds + (bufoff) + ldsw + _i * 8192), 16, 0, 0); } while (0)
; #define PG8_LDA(dst, b, h) do { _Pragma("unroll") for (int m = 0; m < 4; ++m) _Pragma("unroll") for (int k = 0; k < 2; ++k) dst[m][k] = *(const PG8_LAS bf16x8*)(lds + PG8_SA(b, h) + aoff + m * 2048 + k * 1024); } while (0)
; #define PG8_WAIT_V(n) asm volatile("s_waitcnt vmcnt(" #n ")" ::: "memory")
; #define PG8_WAIT_L(n) asm volatile("s_waitcnt lgkmcnt(" #n ")" ::: "memory")
; #define PG8_BAR __builtin_amdgcn_s_barrier()
; template <class Epi, class Sched, bool ALIGN_EPI = false, bool SP2 = false>
; __device__ __forceinline__ void gemm_phase(PG8_LAS unsigned char* lds, const Gemm g, const Sched& S, const Epi& E, const int tid) {
;     ...
;         for (int t = 0; t < nt; t += 2) {
;             const bool last = (t == nt - 2);
;             const char* a1 = cA + (size_t)(t + 1) * kstep;
;             const char* a2 = last ? nA : cA + (size_t)(t + 2) * kstep; const char* b2 = last ? nB : cB + (size_t)(t + 2) * kstep;
;             const char* a3 = a2 + kstep; const char* b3 = b2 + kstep;
;             if (last && has_next) S.a_ready(nxt);
;             if constexpr (SP2) {
;             PG8_LDB(B0, 0, 0); PG8_LDB(B1, 0, 1); PG8_SCHED; PG8_LDA(At, 0, 0); PG8_STAGE(PG8_SA(1, 1), a1 + hstep, voffA);
;             PG8_WAIT_V(8); PG8_WAIT_L(0); PG8_BAR; PG8_MMA(0, 0, At, B0); PG8_MMA(0, 1, At, B1); PG8_BAR; PG8_SCHED;
;             PG8_LDA(At, 0, 1); PG8_STAGE(PG8_SB(0, 0), b2, voffB); PG8_STAGE(PG8_SB(0, 1), b2 + hstep, voffB); PG8_STAGE(PG8_SA(0, 0), a2, voffA);
;             PG8_WAIT_V(8); PG8_WAIT_L(0); PG8_BAR; PG8_MMA(1, 0, At, B0); PG8_MMA(1, 1, At, B1); PG8_BAR; PG8_SCHED;
;             PG8_LDB(B0, 1, 0); PG8_LDB(B1, 1, 1); PG8_SCHED; PG8_LDA(At, 1, 0); PG8_STAGE(PG8_SA(0, 1), a2 + hstep, voffA);
;             PG8_WAIT_V(8); PG8_WAIT_L(0); PG8_BAR; PG8_MMA(0, 0, At, B0); PG8_MMA(0, 1, At, B1); PG8_BAR; PG8_SCHED;
;             PG8_LDA(At, 1, 1); PG8_STAGE(PG8_SB(1, 0), b3, voffB); PG8_STAGE(PG8_SB(1, 1), b3 + hstep, voffB); PG8_STAGE(PG8_SA(1, 0), a3, voffA);
;             PG8_WAIT_V(8); PG8_WAIT_L(0); PG8_BAR; PG8_MMA(1, 0, At, B0); PG8_MMA(1, 1, At, B1); PG8_BAR; PG8_SCHED;
	s_add_i32 s22, s52, s34
	v_lshl_add_u64 v[158:159], v[158:159], 0, s[28:29]
	s_mov_b32 m0, s22
	ds_read_b128 v[208:211], v149 offset:49152
	ds_read_b128 v[214:217], v149 offset:50176
	ds_read_b128 v[218:221], v149 offset:51200
	ds_read_b128 v[222:225], v149 offset:52224
	ds_read_b128 v[226:229], v149 offset:53248
	ds_read_b128 v[230:233], v149 offset:54272
	ds_read_b128 v[234:237], v149 offset:55296
	ds_read_b128 v[238:241], v149 offset:56320
	global_load_lds_dwordx4 v[158:159], off
	s_add_i32 m0, s22, 0x2000
	s_add_u32 s20, s20, 0x40080
	v_lshl_add_u64 v[158:159], v[174:175], 0, s[28:29]
	s_addc_u32 s21, s21, 0
	s_add_i32 s22, s53, s34
	global_load_lds_dwordx4 v[158:159], off
	v_lshl_add_u64 v[158:159], s[20:21], 0, v[160:161]
	s_mov_b32 m0, s22
	s_nop 0
	global_load_lds_dwordx4 v[158:159], off
	v_lshl_add_u64 v[158:159], s[20:21], 0, v[132:133]
	s_add_i32 m0, s22, 0x2000
	s_nop 0
	global_load_lds_dwordx4 v[158:159], off
	v_lshl_add_u64 v[158:159], v[178:179], 0, s[28:29]
	s_mov_b32 m0, s49
	s_nop 0
	global_load_lds_dwordx4 v[158:159], off
	v_lshl_add_u64 v[158:159], v[180:181], 0, s[28:29]
	s_mov_b32 m0, s50
	s_nop 0
	global_load_lds_dwordx4 v[158:159], off
	s_waitcnt vmcnt(8)
	s_waitcnt lgkmcnt(0)
	s_barrier
	s_setprio 1
	s_waitcnt lgkmcnt(0)
	v_mfma_f32_16x16x32_bf16 v[60:63], v[150:153], v[208:211], v[60:63]
	v_mfma_f32_16x16x32_bf16 v[52:55], v[162:165], v[208:211], v[52:55]
	v_mfma_f32_16x16x32_bf16 v[44:47], v[150:153], v[218:221], v[44:47]
	v_mfma_f32_16x16x32_bf16 v[36:39], v[162:165], v[218:221], v[36:39]
	v_mfma_f32_16x16x32_bf16 v[28:31], v[150:153], v[226:229], v[28:31]
	v_mfma_f32_16x16x32_bf16 v[20:23], v[162:165], v[226:229], v[20:23]
	v_mfma_f32_16x16x32_bf16 v[12:15], v[150:153], v[234:237], v[12:15]
	v_mfma_f32_16x16x32_bf16 v[4:7], v[162:165], v[234:237], v[4:7]
	v_mfma_f32_16x16x32_bf16 v[60:63], v[154:157], v[214:217], v[60:63]
	v_mfma_f32_16x16x32_bf16 v[52:55], v[166:169], v[214:217], v[52:55]
	v_mfma_f32_16x16x32_bf16 v[44:47], v[154:157], v[222:225], v[44:47]
	v_mfma_f32_16x16x32_bf16 v[36:39], v[166:169], v[222:225], v[36:39]
	v_mfma_f32_16x16x32_bf16 v[28:31], v[154:157], v[230:233], v[28:31]
	v_mfma_f32_16x16x32_bf16 v[20:23], v[166:169], v[230:233], v[20:23]
	v_mfma_f32_16x16x32_bf16 v[12:15], v[154:157], v[238:241], v[12:15]
	v_mfma_f32_16x16x32_bf16 v[4:7], v[166:169], v[238:241], v[4:7]
	s_setprio 0
	s_setprio 1
	v_mfma_f32_16x16x32_bf16 v[56:59], v[170:173], v[208:211], v[56:59]
	s_add_i32 s51, s51, 2
	v_mfma_f32_16x16x32_bf16 v[48:51], v[188:191], v[208:211], v[48:51]
	s_add_u32 s18, s18, 0x100
	v_mfma_f32_16x16x32_bf16 v[40:43], v[170:173], v[218:221], v[40:43]
	s_addc_u32 s19, s19, 0
	v_mfma_f32_16x16x32_bf16 v[32:35], v[188:191], v[218:221], v[32:35]
	s_add_u32 s42, s42, 0x100
	v_mfma_f32_16x16x32_bf16 v[24:27], v[170:173], v[226:229], v[24:27]
	s_addc_u32 s43, s43, 0
	v_mfma_f32_16x16x32_bf16 v[16:19], v[188:191], v[226:229], v[16:19]
	s_cmp_gt_u32 s51, 13
	v_mfma_f32_16x16x32_bf16 v[8:11], v[170:173], v[234:237], v[8:11]
	v_mfma_f32_16x16x32_bf16 v[0:3], v[188:191], v[234:237], v[0:3]
	v_mfma_f32_16x16x32_bf16 v[56:59], v[184:187], v[214:217], v[56:59]
	v_mfma_f32_16x16x32_bf16 v[48:51], v[192:195], v[214:217], v[48:51]
	v_mfma_f32_16x16x32_bf16 v[40:43], v[184:187], v[222:225], v[40:43]
	v_mfma_f32_16x16x32_bf16 v[32:35], v[192:195], v[222:225], v[32:35]
	v_mfma_f32_16x16x32_bf16 v[24:27], v[184:187], v[230:233], v[24:27]
	v_mfma_f32_16x16x32_bf16 v[16:19], v[192:195], v[230:233], v[16:19]
	v_mfma_f32_16x16x32_bf16 v[8:11], v[184:187], v[238:241], v[8:11]
	v_mfma_f32_16x16x32_bf16 v[0:3], v[192:195], v[238:241], v[0:3]
	s_setprio 0
	s_barrier
	s_cbranch_scc1 .Lmy_kdone_2
.LBB0_517:
	s_add_u32 s20, s18, 0xfffc0080
	s_addc_u32 s21, s19, -1
	s_add_i32 s52, 0, 0x10000
	s_cmp_eq_u32 s51, 12
	s_cselect_b32 s23, s11, s21
	s_cselect_b32 s22, s36, s20
	v_add_u32_e32 v138, s52, v141
	s_cselect_b32 s21, s9, s43
	s_cselect_b32 s20, s37, s42
	s_add_i32 s56, 0, 0x14000
	ds_read_b128 v[150:153], v138
	ds_read_b128 v[154:157], v138 offset:1024
	ds_read_b128 v[162:165], v138 offset:2048
	ds_read_b128 v[166:169], v138 offset:3072
	v_add_u32_e32 v138, s56, v141
	ds_read_b128 v[170:173], v138
	ds_read_b128 v[184:187], v138 offset:1024
	ds_read_b128 v[188:191], v138 offset:2048
	ds_read_b128 v[192:195], v138 offset:3072
	v_lshl_add_u64 v[158:159], s[18:19], 0, v[134:135]
	s_add_i32 m0, s35, 0xc000
	ds_read_b128 v[208:211], v149
	ds_read_b128 v[214:217], v149 offset:1024
	ds_read_b128 v[218:221], v149 offset:2048
	ds_read_b128 v[222:225], v149 offset:3072
	ds_read_b128 v[226:229], v149 offset:4096
	ds_read_b128 v[230:233], v149 offset:5120
	ds_read_b128 v[234:237], v149 offset:6144
	ds_read_b128 v[238:241], v149 offset:7168
	global_load_lds_dwordx4 v[158:159], off
	v_lshl_add_u64 v[158:159], s[18:19], 0, v[136:137]
	s_add_i32 m0, s35, 0xe000
	s_nop 0
	global_load_lds_dwordx4 v[158:159], off
	s_waitcnt vmcnt(8)
	s_waitcnt lgkmcnt(0)
	s_barrier
; #define PG8_STAGE(bufoff, gbase, voff) do { _Pragma("unroll") for (int _i = 0; _i < 2; ++_i) \
;         __builtin_amdgcn_global_load_lds((const unsigned*)((const char*)(gbase) + (voff)[_i]), (PG8_LAS unsigned*)(lds + (bufoff) + ldsw + _i * 8192), 16, 0, 0); } while (0)
; #define PG8_LDA(dst, b, h) do { _Pragma("unroll") for (int m = 0; m < 4; ++m) _Pragma("unroll") for (int k = 0; k < 2; ++k) dst[m][k] = *(const PG8_LAS bf16x8*)(lds + PG8_SA(b, h) + aoff + m * 2048 + k * 1024); } while (0)
; #define PG8_MMA(ai, bj, At, Bt) do { __builtin_amdgcn_s_setprio(1); _Pragma("unroll") for (int m = 0; m < 4; ++m) _Pragma("unroll") for (int n = 0; n < 2; ++n) _Pragma("unroll") for (int k = 0; k < 2; ++k) \
;         acc[ai][bj][m][n] = __builtin_amdgcn_mfma_f32_16x16x32_bf16(Bt[n][k], At[m][k], acc[ai][bj][m][n], 0, 0, 0); __builtin_amdgcn_s_setprio(0); } while (0)
; #define PG8_WAIT_V(n) asm volatile("s_waitcnt vmcnt(" #n ")" ::: "memory")
; #define PG8_WAIT_L(n) asm volatile("s_waitcnt lgkmcnt(" #n ")" ::: "memory")
; #define PG8_BAR __builtin_amdgcn_s_barrier()
; #define PG8_SCHED __builtin_amdgcn_sched_barrier(0)
; template <class Epi, class Sched, bool ALIGN_EPI = false, bool SP2 = false>
; __device__ __forceinline__ void gemm_phase(PG8_LAS unsigned char* lds, const Gemm g, const Sched& S, const Epi& E, const int tid) {
;     ...
;             PG8_WAIT_V(8); PG8_WAIT_L(0); PG8_BAR; PG8_MMA(0, 0, At, B0); PG8_MMA(0, 1, At, B1); PG8_BAR; PG8_SCHED;
;             PG8_LDA(At, 0, 1); PG8_STAGE(PG8_SB(0, 0), b2, voffB); PG8_STAGE(PG8_SB(0, 1), b2 + hstep, voffB); PG8_STAGE(PG8_SA(0, 0), a2, voffA);
;             PG8_WAIT_V(8); PG8_WAIT_L(0); PG8_BAR; PG8_MMA(1, 0, At, B0); PG8_MMA(1, 1, At, B1); PG8_BAR; PG8_SCHED;
	s_setprio 1
	s_waitcnt lgkmcnt(0)
	v_mfma_f32_16x16x32_bf16 v[124:127], v[150:153], v[208:211], v[124:127]
	v_mfma_f32_16x16x32_bf16 v[116:119], v[162:165], v[208:211], v[116:119]
	v_mfma_f32_16x16x32_bf16 v[108:111], v[150:153], v[218:221], v[108:111]
	v_mfma_f32_16x16x32_bf16 v[100:103], v[162:165], v[218:221], v[100:103]
	v_mfma_f32_16x16x32_bf16 v[92:95], v[150:153], v[226:229], v[92:95]
	v_mfma_f32_16x16x32_bf16 v[84:87], v[162:165], v[226:229], v[84:87]
	v_mfma_f32_16x16x32_bf16 v[76:79], v[150:153], v[234:237], v[76:79]
	v_mfma_f32_16x16x32_bf16 v[68:71], v[162:165], v[234:237], v[68:71]
	v_mfma_f32_16x16x32_bf16 v[124:127], v[154:157], v[214:217], v[124:127]
	v_mfma_f32_16x16x32_bf16 v[116:119], v[166:169], v[214:217], v[116:119]
	v_mfma_f32_16x16x32_bf16 v[108:111], v[154:157], v[222:225], v[108:111]
	v_mfma_f32_16x16x32_bf16 v[100:103], v[166:169], v[222:225], v[100:103]
	v_mfma_f32_16x16x32_bf16 v[92:95], v[154:157], v[230:233], v[92:95]
	v_mfma_f32_16x16x32_bf16 v[84:87], v[166:169], v[230:233], v[84:87]
	v_mfma_f32_16x16x32_bf16 v[76:79], v[154:157], v[238:241], v[76:79]
	v_mfma_f32_16x16x32_bf16 v[68:71], v[166:169], v[238:241], v[68:71]
	s_setprio 0
	s_setprio 1
	v_mfma_f32_16x16x32_bf16 v[120:123], v[170:173], v[208:211], v[120:123]
	v_mfma_f32_16x16x32_bf16 v[112:115], v[188:191], v[208:211], v[112:115]
	v_mfma_f32_16x16x32_bf16 v[104:107], v[170:173], v[218:221], v[104:107]
	v_mfma_f32_16x16x32_bf16 v[96:99], v[188:191], v[218:221], v[96:99]
	v_mfma_f32_16x16x32_bf16 v[88:91], v[170:173], v[226:229], v[88:91]
	v_mfma_f32_16x16x32_bf16 v[80:83], v[188:191], v[226:229], v[80:83]
	v_mfma_f32_16x16x32_bf16 v[72:75], v[170:173], v[234:237], v[72:75]
	v_mfma_f32_16x16x32_bf16 v[64:67], v[188:191], v[234:237], v[64:67]
	v_mfma_f32_16x16x32_bf16 v[120:123], v[184:187], v[214:217], v[120:123]
	v_mfma_f32_16x16x32_bf16 v[112:115], v[192:195], v[214:217], v[112:115]
	v_mfma_f32_16x16x32_bf16 v[104:107], v[184:187], v[222:225], v[104:107]
	v_mfma_f32_16x16x32_bf16 v[96:99], v[192:195], v[222:225], v[96:99]
	v_mfma_f32_16x16x32_bf16 v[88:91], v[184:187], v[230:233], v[88:91]
	v_mfma_f32_16x16x32_bf16 v[80:83], v[192:195], v[230:233], v[80:83]
	v_mfma_f32_16x16x32_bf16 v[72:75], v[184:187], v[238:241], v[72:75]
	v_mfma_f32_16x16x32_bf16 v[64:67], v[192:195], v[238:241], v[64:67]
	s_setprio 0
	s_barrier
	s_add_i32 s52, s52, s34
	v_lshl_add_u64 v[158:159], s[20:21], 0, v[160:161]
	s_mov_b32 m0, s52
	ds_read_b128 v[208:211], v149 offset:16384
	ds_read_b128 v[214:217], v149 offset:17408
	ds_read_b128 v[218:221], v149 offset:18432
	ds_read_b128 v[222:225], v149 offset:19456
	ds_read_b128 v[226:229], v149 offset:20480
	ds_read_b128 v[230:233], v149 offset:21504
	ds_read_b128 v[234:237], v149 offset:22528
	ds_read_b128 v[238:241], v149 offset:23552
	global_load_lds_dwordx4 v[158:159], off
	s_add_i32 m0, s52, 0x2000
	s_add_u32 s52, s20, 0x40000
	v_lshl_add_u64 v[174:175], s[20:21], 0, v[132:133]
	s_addc_u32 s53, s21, 0
	s_add_i32 s56, s56, s34
	global_load_lds_dwordx4 v[174:175], off
	v_lshl_add_u64 v[178:179], s[52:53], 0, v[160:161]
	s_mov_b32 m0, s56
	v_lshl_add_u64 v[180:181], s[22:23], 0, v[130:131]
	global_load_lds_dwordx4 v[178:179], off
	v_lshl_add_u64 v[178:179], s[52:53], 0, v[132:133]
	s_add_i32 m0, s56, 0x2000
	s_nop 0
	global_load_lds_dwordx4 v[178:179], off
	v_lshl_add_u64 v[178:179], s[22:23], 0, v[128:129]
	s_mov_b32 m0, s35
	s_nop 0
	global_load_lds_dwordx4 v[178:179], off
	s_mov_b32 m0, s44
	s_nop 0
	global_load_lds_dwordx4 v[180:181], off
	s_waitcnt vmcnt(8)
	s_waitcnt lgkmcnt(0)
	s_barrier
	s_setprio 1
	s_waitcnt lgkmcnt(0)
	v_mfma_f32_16x16x32_bf16 v[60:63], v[150:153], v[208:211], v[60:63]
	v_mfma_f32_16x16x32_bf16 v[52:55], v[162:165], v[208:211], v[52:55]
	v_mfma_f32_16x16x32_bf16 v[44:47], v[150:153], v[218:221], v[44:47]
	v_mfma_f32_16x16x32_bf16 v[36:39], v[162:165], v[218:221], v[36:39]
	v_mfma_f32_16x16x32_bf16 v[28:31], v[150:153], v[226:229], v[28:31]
	v_mfma_f32_16x16x32_bf16 v[20:23], v[162:165], v[226:229], v[20:23]
	v_mfma_f32_16x16x32_bf16 v[12:15], v[150:153], v[234:237], v[12:15]
	v_mfma_f32_16x16x32_bf16 v[4:7], v[162:165], v[234:237], v[4:7]
	v_mfma_f32_16x16x32_bf16 v[60:63], v[154:157], v[214:217], v[60:63]
	v_mfma_f32_16x16x32_bf16 v[52:55], v[166:169], v[214:217], v[52:55]
	v_mfma_f32_16x16x32_bf16 v[44:47], v[154:157], v[222:225], v[44:47]
	v_mfma_f32_16x16x32_bf16 v[36:39], v[166:169], v[222:225], v[36:39]
	v_mfma_f32_16x16x32_bf16 v[28:31], v[154:157], v[230:233], v[28:31]
	v_mfma_f32_16x16x32_bf16 v[20:23], v[166:169], v[230:233], v[20:23]
	v_mfma_f32_16x16x32_bf16 v[12:15], v[154:157], v[238:241], v[12:15]
	v_mfma_f32_16x16x32_bf16 v[4:7], v[166:169], v[238:241], v[4:7]
	s_setprio 0
	s_setprio 1
	v_mfma_f32_16x16x32_bf16 v[56:59], v[170:173], v[208:211], v[56:59]
	v_mfma_f32_16x16x32_bf16 v[48:51], v[188:191], v[208:211], v[48:51]
	v_mfma_f32_16x16x32_bf16 v[40:43], v[170:173], v[218:221], v[40:43]
	v_mfma_f32_16x16x32_bf16 v[32:35], v[188:191], v[218:221], v[32:35]
	v_mfma_f32_16x16x32_bf16 v[24:27], v[170:173], v[226:229], v[24:27]
	v_mfma_f32_16x16x32_bf16 v[16:19], v[188:191], v[226:229], v[16:19]
	v_mfma_f32_16x16x32_bf16 v[8:11], v[170:173], v[234:237], v[8:11]
	v_mfma_f32_16x16x32_bf16 v[0:3], v[188:191], v[234:237], v[0:3]
	v_mfma_f32_16x16x32_bf16 v[56:59], v[184:187], v[214:217], v[56:59]
	v_mfma_f32_16x16x32_bf16 v[48:51], v[192:195], v[214:217], v[48:51]
	v_mfma_f32_16x16x32_bf16 v[40:43], v[184:187], v[222:225], v[40:43]
	v_mfma_f32_16x16x32_bf16 v[32:35], v[192:195], v[222:225], v[32:35]
	v_mfma_f32_16x16x32_bf16 v[24:27], v[184:187], v[230:233], v[24:27]
	v_mfma_f32_16x16x32_bf16 v[16:19], v[192:195], v[230:233], v[16:19]
	v_mfma_f32_16x16x32_bf16 v[8:11], v[184:187], v[238:241], v[8:11]
	v_mfma_f32_16x16x32_bf16 v[0:3], v[192:195], v[238:241], v[0:3]
	s_setprio 0
	s_barrier
; #define PG8_STAGE(bufoff, gbase, voff) do { _Pragma("unroll") for (int _i = 0; _i < 2; ++_i) \
;         __builtin_amdgcn_global_load_lds((const unsigned*)((const char*)(gbase) + (voff)[_i]), (PG8_LAS unsigned*)(lds + (bufoff) + ldsw + _i * 8192), 16, 0, 0); } while (0)
; #define PG8_LDA(dst, b, h) do { _Pragma("unroll") for (int m = 0; m < 4; ++m) _Pragma("unroll") for (int k = 0; k < 2; ++k) dst[m][k] = *(const PG8_LAS bf16x8*)(lds + PG8_SA(b, h) + aoff + m * 2048 + k * 1024); } while (0)
; #define PG8_LDB(dst, b, h) do { _Pragma("unroll") for (int n = 0; n < 2; ++n) _Pragma("unroll") for (int k = 0; k < 2; ++k) dst[n][k] = *(const PG8_LAS bf16x8*)(lds + PG8_SB(b, h) + boff + n * 2048 + k * 1024); } while (0)
; #define PG8_MMA(ai, bj, At, Bt) do { __builtin_amdgcn_s_setprio(1); _Pragma("unroll") for (int m = 0; m < 4; ++m) _Pragma("unroll") for (int n = 0; n < 2; ++n) _Pragma("unroll") for (int k = 0; k < 2; ++k) \
;         acc[ai][bj][m][n] = __builtin_amdgcn_mfma_f32_16x16x32_bf16(Bt[n][k], At[m][k], acc[ai][bj][m][n], 0, 0, 0); __builtin_amdgcn_s_setprio(0); } while (0)
; #define PG8_WAIT_V(n) asm volatile("s_waitcnt vmcnt(" #n ")" ::: "memory")
; #define PG8_WAIT_L(n) asm volatile("s_waitcnt lgkmcnt(" #n ")" ::: "memory")
; #define PG8_BAR __builtin_amdgcn_s_barrier()
; #define PG8_SCHED __builtin_amdgcn_sched_barrier(0)
; template <class Epi, class Sched, bool ALIGN_EPI = false, bool SP2 = false>
; __device__ __forceinline__ void gemm_phase(PG8_LAS unsigned char* lds, const Gemm g, const Sched& S, const Epi& E, const int tid) {
;     ...
;             PG8_LDB(B0, 1, 0); PG8_LDB(B1, 1, 1); PG8_SCHED; PG8_LDA(At, 1, 0); PG8_STAGE(PG8_SA(0, 1), a2 + hstep, voffA);
;             PG8_WAIT_V(8); PG8_WAIT_L(0); PG8_BAR; PG8_MMA(0, 0, At, B0); PG8_MMA(0, 1, At, B1); PG8_BAR; PG8_SCHED;
	s_add_i32 s52, 0, 0x18000
	v_add_u32_e32 v138, s52, v141
	s_add_i32 s53, 0, 0x1c000
	ds_read_b128 v[150:153], v138
	ds_read_b128 v[154:157], v138 offset:1024
	ds_read_b128 v[162:165], v138 offset:2048
	ds_read_b128 v[166:169], v138 offset:3072
	v_add_u32_e32 v138, s53, v141
	ds_read_b128 v[170:173], v138
	ds_read_b128 v[184:187], v138 offset:1024
	ds_read_b128 v[188:191], v138 offset:2048
	ds_read_b128 v[192:195], v138 offset:3072
	s_add_u32 s22, s22, 0x40000
	s_addc_u32 s23, s23, 0
	s_mov_b32 m0, s45
	v_lshl_add_u64 v[196:197], s[22:23], 0, v[128:129]
	ds_read_b128 v[208:211], v149 offset:32768
	ds_read_b128 v[214:217], v149 offset:33792
	ds_read_b128 v[218:221], v149 offset:34816
	ds_read_b128 v[222:225], v149 offset:35840
	ds_read_b128 v[226:229], v149 offset:36864
	ds_read_b128 v[230:233], v149 offset:37888
	ds_read_b128 v[234:237], v149 offset:38912
	ds_read_b128 v[238:241], v149 offset:39936
	global_load_lds_dwordx4 v[196:197], off
	v_lshl_add_u64 v[196:197], s[22:23], 0, v[130:131]
	s_mov_b32 m0, s46
	s_nop 0
	global_load_lds_dwordx4 v[196:197], off
	s_waitcnt vmcnt(8)
	s_waitcnt lgkmcnt(0)
	s_barrier
	s_setprio 1
	s_waitcnt lgkmcnt(0)
	v_mfma_f32_16x16x32_bf16 v[124:127], v[150:153], v[208:211], v[124:127]
	v_mfma_f32_16x16x32_bf16 v[116:119], v[162:165], v[208:211], v[116:119]
	v_mfma_f32_16x16x32_bf16 v[108:111], v[150:153], v[218:221], v[108:111]
	v_mfma_f32_16x16x32_bf16 v[100:103], v[162:165], v[218:221], v[100:103]
	v_mfma_f32_16x16x32_bf16 v[92:95], v[150:153], v[226:229], v[92:95]
	v_mfma_f32_16x16x32_bf16 v[84:87], v[162:165], v[226:229], v[84:87]
	v_mfma_f32_16x16x32_bf16 v[76:79], v[150:153], v[234:237], v[76:79]
	v_mfma_f32_16x16x32_bf16 v[68:71], v[162:165], v[234:237], v[68:71]
	v_mfma_f32_16x16x32_bf16 v[124:127], v[154:157], v[214:217], v[124:127]
	v_mfma_f32_16x16x32_bf16 v[116:119], v[166:169], v[214:217], v[116:119]
	v_mfma_f32_16x16x32_bf16 v[108:111], v[154:157], v[222:225], v[108:111]
	v_mfma_f32_16x16x32_bf16 v[100:103], v[166:169], v[222:225], v[100:103]
	v_mfma_f32_16x16x32_bf16 v[92:95], v[154:157], v[230:233], v[92:95]
	v_mfma_f32_16x16x32_bf16 v[84:87], v[166:169], v[230:233], v[84:87]
	v_mfma_f32_16x16x32_bf16 v[76:79], v[154:157], v[238:241], v[76:79]
	v_mfma_f32_16x16x32_bf16 v[68:71], v[166:169], v[238:241], v[68:71]
	s_setprio 0
	s_setprio 1
	v_mfma_f32_16x16x32_bf16 v[120:123], v[170:173], v[208:211], v[120:123]
	v_mfma_f32_16x16x32_bf16 v[112:115], v[188:191], v[208:211], v[112:115]
	v_mfma_f32_16x16x32_bf16 v[104:107], v[170:173], v[218:221], v[104:107]
	v_mfma_f32_16x16x32_bf16 v[96:99], v[188:191], v[218:221], v[96:99]
	v_mfma_f32_16x16x32_bf16 v[88:91], v[170:173], v[226:229], v[88:91]
	v_mfma_f32_16x16x32_bf16 v[80:83], v[188:191], v[226:229], v[80:83]
	v_mfma_f32_16x16x32_bf16 v[72:75], v[170:173], v[234:237], v[72:75]
	v_mfma_f32_16x16x32_bf16 v[64:67], v[188:191], v[234:237], v[64:67]
	v_mfma_f32_16x16x32_bf16 v[120:123], v[184:187], v[214:217], v[120:123]
	v_mfma_f32_16x16x32_bf16 v[112:115], v[192:195], v[214:217], v[112:115]
	v_mfma_f32_16x16x32_bf16 v[104:107], v[184:187], v[222:225], v[104:107]
	v_mfma_f32_16x16x32_bf16 v[96:99], v[192:195], v[222:225], v[96:99]
	v_mfma_f32_16x16x32_bf16 v[88:91], v[184:187], v[230:233], v[88:91]
	v_mfma_f32_16x16x32_bf16 v[80:83], v[192:195], v[230:233], v[80:83]
	v_mfma_f32_16x16x32_bf16 v[72:75], v[184:187], v[238:241], v[72:75]
	v_mfma_f32_16x16x32_bf16 v[64:67], v[192:195], v[238:241], v[64:67]
	s_setprio 0
	s_barrier
; #define PG8_STAGE(bufoff, gbase, voff) do { _Pragma("unroll") for (int _i = 0; _i < 2; ++_i) \
;         __builtin_amdgcn_global_load_lds((const unsigned*)((const char*)(gbase) + (voff)[_i]), (PG8_LAS unsigned*)(lds + (bufoff) + ldsw + _i * 8192), 16, 0, 0); } while (0)
; #define PG8_LDA(dst, b, h) do { _Pragma("unroll") for (int m = 0; m < 4; ++m) _Pragma("unroll") for (int k = 0; k < 2; ++k) dst[m][k] = *(const PG8_LAS bf16x8*)(lds + PG8_SA(b, h) + aoff + m * 2048 + k * 1024); } while (0)
; #define PG8_MMA(ai, bj, At, Bt) do { __builtin_amdgcn_s_setprio(1); _Pragma("unroll") for (int m = 0; m < 4; ++m) _Pragma("unroll") for (int n = 0; n < 2; ++n) _Pragma("unroll") for (int k = 0; k < 2; ++k) \
;         acc[ai][bj][m][n] = __builtin_amdgcn_mfma_f32_16x16x32_bf16(Bt[n][k], At[m][k], acc[ai][bj][m][n], 0, 0, 0); __builtin_amdgcn_s_setprio(0); } while (0)
; #define PG8_WAIT_V(n) asm volatile("s_waitcnt vmcnt(" #n ")" ::: "memory")
; #define PG8_WAIT_L(n) asm volatile("s_waitcnt lgkmcnt(" #n ")" ::: "memory")
; #define PG8_BAR __builtin_amdgcn_s_barrier()
; #define PG8_SCHED __builtin_amdgcn_sched_barrier(0)
; template <class Epi, class Sched, bool ALIGN_EPI = false, bool SP2 = false>
; __device__ __forceinline__ void gemm_phase(PG8_LAS unsigned char* lds, const Gemm g, const Sched& S, const Epi& E, const int tid) {
;     ...
;             PG8_LDA(At, 1, 1); PG8_STAGE(PG8_SB(1, 0), b3, voffB); PG8_STAGE(PG8_SB(1, 1), b3 + hstep, voffB); PG8_STAGE(PG8_SA(1, 0), a3, voffA);
;             PG8_WAIT_V(8); PG8_WAIT_L(0); PG8_BAR; PG8_MMA(1, 0, At, B0); PG8_MMA(1, 1, At, B1); PG8_BAR; PG8_SCHED;
	s_add_i32 s22, s52, s34
	v_lshl_add_u64 v[158:159], v[158:159], 0, s[28:29]
	s_mov_b32 m0, s22
	ds_read_b128 v[208:211], v149 offset:49152
	ds_read_b128 v[214:217], v149 offset:50176
	ds_read_b128 v[218:221], v149 offset:51200
	ds_read_b128 v[222:225], v149 offset:52224
	ds_read_b128 v[226:229], v149 offset:53248
	ds_read_b128 v[230:233], v149 offset:54272
	ds_read_b128 v[234:237], v149 offset:55296
	ds_read_b128 v[238:241], v149 offset:56320
	global_load_lds_dwordx4 v[158:159], off
	s_add_i32 m0, s22, 0x2000
	s_add_u32 s20, s20, 0x40080
	v_lshl_add_u64 v[158:159], v[174:175], 0, s[28:29]
	s_addc_u32 s21, s21, 0
	s_add_i32 s22, s53, s34
	global_load_lds_dwordx4 v[158:159], off
	v_lshl_add_u64 v[158:159], s[20:21], 0, v[160:161]
	s_mov_b32 m0, s22
	s_nop 0
	global_load_lds_dwordx4 v[158:159], off
	v_lshl_add_u64 v[158:159], s[20:21], 0, v[132:133]
	s_add_i32 m0, s22, 0x2000
	s_nop 0
	global_load_lds_dwordx4 v[158:159], off
	v_lshl_add_u64 v[158:159], v[178:179], 0, s[28:29]
	s_mov_b32 m0, s49
	s_nop 0
	global_load_lds_dwordx4 v[158:159], off
	v_lshl_add_u64 v[158:159], v[180:181], 0, s[28:29]
	s_mov_b32 m0, s50
	s_nop 0
	global_load_lds_dwordx4 v[158:159], off
	s_waitcnt vmcnt(8)
	s_waitcnt lgkmcnt(0)
	s_barrier
	s_setprio 1
	s_waitcnt lgkmcnt(0)
	v_mfma_f32_16x16x32_bf16 v[60:63], v[150:153], v[208:211], v[60:63]
	v_mfma_f32_16x16x32_bf16 v[52:55], v[162:165], v[208:211], v[52:55]
	v_mfma_f32_16x16x32_bf16 v[44:47], v[150:153], v[218:221], v[44:47]
	v_mfma_f32_16x16x32_bf16 v[36:39], v[162:165], v[218:221], v[36:39]
	v_mfma_f32_16x16x32_bf16 v[28:31], v[150:153], v[226:229], v[28:31]
	v_mfma_f32_16x16x32_bf16 v[20:23], v[162:165], v[226:229], v[20:23]
	v_mfma_f32_16x16x32_bf16 v[12:15], v[150:153], v[234:237], v[12:15]
	v_mfma_f32_16x16x32_bf16 v[4:7], v[162:165], v[234:237], v[4:7]
	v_mfma_f32_16x16x32_bf16 v[60:63], v[154:157], v[214:217], v[60:63]
	v_mfma_f32_16x16x32_bf16 v[52:55], v[166:169], v[214:217], v[52:55]
	v_mfma_f32_16x16x32_bf16 v[44:47], v[154:157], v[222:225], v[44:47]
	v_mfma_f32_16x16x32_bf16 v[36:39], v[166:169], v[222:225], v[36:39]
	v_mfma_f32_16x16x32_bf16 v[28:31], v[154:157], v[230:233], v[28:31]
	v_mfma_f32_16x16x32_bf16 v[20:23], v[166:169], v[230:233], v[20:23]
	v_mfma_f32_16x16x32_bf16 v[12:15], v[154:157], v[238:241], v[12:15]
	v_mfma_f32_16x16x32_bf16 v[4:7], v[166:169], v[238:241], v[4:7]
	s_setprio 0
	s_setprio 1
	v_mfma_f32_16x16x32_bf16 v[56:59], v[170:173], v[208:211], v[56:59]
	s_add_i32 s51, s51, 2
	v_mfma_f32_16x16x32_bf16 v[48:51], v[188:191], v[208:211], v[48:51]
	s_add_u32 s18, s18, 0x100
	v_mfma_f32_16x16x32_bf16 v[40:43], v[170:173], v[218:221], v[40:43]
	s_addc_u32 s19, s19, 0
	v_mfma_f32_16x16x32_bf16 v[32:35], v[188:191], v[218:221], v[32:35]
	s_add_u32 s42, s42, 0x100
	v_mfma_f32_16x16x32_bf16 v[24:27], v[170:173], v[226:229], v[24:27]
	s_addc_u32 s43, s43, 0
	v_mfma_f32_16x16x32_bf16 v[16:19], v[188:191], v[226:229], v[16:19]
	s_cmp_gt_u32 s51, 13
	v_mfma_f32_16x16x32_bf16 v[8:11], v[170:173], v[234:237], v[8:11]
	v_mfma_f32_16x16x32_bf16 v[0:3], v[188:191], v[234:237], v[0:3]
	v_mfma_f32_16x16x32_bf16 v[56:59], v[184:187], v[214:217], v[56:59]
	v_mfma_f32_16x16x32_bf16 v[48:51], v[192:195], v[214:217], v[48:51]
	v_mfma_f32_16x16x32_bf16 v[40:43], v[184:187], v[222:225], v[40:43]
	v_mfma_f32_16x16x32_bf16 v[32:35], v[192:195], v[222:225], v[32:35]
	v_mfma_f32_16x16x32_bf16 v[24:27], v[184:187], v[230:233], v[24:27]
	v_mfma_f32_16x16x32_bf16 v[16:19], v[192:195], v[230:233], v[16:19]
	v_mfma_f32_16x16x32_bf16 v[8:11], v[184:187], v[238:241], v[8:11]
	v_mfma_f32_16x16x32_bf16 v[0:3], v[192:195], v[238:241], v[0:3]
	s_setprio 0
	s_barrier
	s_cbranch_scc0 .LBB0_517

; #define PG8_STAGE(bufoff, gbase, voff) do { _Pragma("unroll") for (int _i = 0; _i < 2; ++_i) \
;         __builtin_amdgcn_global_load_lds((const unsigned*)((const char*)(gbase) + (voff)[_i]), (PG8_LAS unsigned*)(lds + (bufoff) + ldsw + _i * 8192), 16, 0, 0); } while (0)
; #define PG8_LDA(dst, b, h) do { _Pragma("unroll") for (int m = 0; m < 4; ++m) _Pragma("unroll") for (int k = 0; k < 2; ++k) dst[m][k] = *(const PG8_LAS bf16x8*)(lds + PG8_SA(b, h) + aoff + m * 2048 + k * 1024); } while (0)
; #define PG8_LDB(dst, b, h) do { _Pragma("unroll") for (int n = 0; n < 2; ++n) _Pragma("unroll") for (int k = 0; k < 2; ++k) dst[n][k] = *(const PG8_LAS bf16x8*)(lds + PG8_SB(b, h) + boff + n * 2048 + k * 1024); } while (0)
; #define PG8_MMA(ai, bj, At, Bt) do { __builtin_amdgcn_s_setprio(1); _Pragma("unroll") for (int m = 0; m < 4; ++m) _Pragma("unroll") for (int n = 0; n < 2; ++n) _Pragma("unroll") for (int k = 0; k < 2; ++k) \
;         acc[ai][bj][m][n] = __builtin_amdgcn_mfma_f32_16x16x32_bf16(Bt[n][k], At[m][k], acc[ai][bj][m][n], 0, 0, 0); __builtin_amdgcn_s_setprio(0); } while (0)
; #define PG8_WAIT_V(n) asm volatile("s_waitcnt vmcnt(" #n ")" ::: "memory")
; #define PG8_BAR __builtin_amdgcn_s_barrier()
; template <class Epi, class Sched, bool ALIGN_EPI = false, bool SP2 = false>
; __device__ __forceinline__ void gemm_phase(PG8_LAS unsigned char* lds, const Gemm g, const Sched& S, const Epi& E, const int tid) {
;     ...
;         for (int t = 0; t < nt; t += 2) {
;             const bool last = (t == nt - 2);
;             const char* a1 = cA + (size_t)(t + 1) * kstep;
;             const char* a2 = last ? nA : cA + (size_t)(t + 2) * kstep; const char* b2 = last ? nB : cB + (size_t)(t + 2) * kstep;
;             const char* a3 = a2 + kstep; const char* b3 = b2 + kstep;
;             if (last && has_next) S.a_ready(nxt);
;             if constexpr (SP2) {
;             PG8_LDB(B0, 0, 0); PG8_LDB(B1, 0, 1); PG8_SCHED; PG8_LDA(At, 0, 0); PG8_STAGE(PG8_SA(1, 1), a1 + hstep, voffA);
;             PG8_WAIT_V(8); PG8_WAIT_L(0); PG8_BAR; PG8_MMA(0, 0, At, B0); PG8_MMA(0, 1, At, B1); PG8_BAR; PG8_SCHED;
;             PG8_LDA(At, 0, 1); PG8_STAGE(PG8_SB(0, 0), b2, voffB); PG8_STAGE(PG8_SB(0, 1), b2 + hstep, voffB); PG8_STAGE(PG8_SA(0, 0), a2, voffA);
;             PG8_WAIT_V(8); PG8_WAIT_L(0); PG8_BAR; PG8_MMA(1, 0, At, B0); PG8_MMA(1, 1, At, B1); PG8_BAR; PG8_SCHED;
.LBB0_620:
	s_add_u32 s44, s50, 0x80
	s_addc_u32 s45, s51, 0
	s_add_u32 s37, s48, 0x100
	s_addc_u32 s50, s49, 0
	s_mov_b32 s48, 0
	s_add_i32 s51, s48, 2
	s_add_u32 vcc_lo, s44, 0x80
	s_addc_u32 s49, s45, 0
	s_cmp_eq_u32 s82, s48
	s_cselect_b32 s49, s35, s49
	s_cselect_b32 s48, s34, vcc_lo
	v_add_u32_e32 v156, s59, v174
	s_cselect_b32 vcc_hi, s47, s50
	s_cselect_b32 vcc_lo, s46, s37
	s_add_i32 s90, 0, 0x14000
	s_waitcnt lgkmcnt(0)
	ds_read_b128 v[144:147], v156
	ds_read_b128 v[148:151], v156 offset:1024
	ds_read_b128 v[152:155], v156 offset:2048
	ds_read_b128 v[184:187], v156 offset:3072
	v_add_u32_e32 v156, s90, v174
	ds_read_b128 v[188:191], v156
	ds_read_b128 v[192:195], v156 offset:1024
	ds_read_b128 v[214:217], v156 offset:2048
	ds_read_b128 v[218:221], v156 offset:3072
	v_lshl_add_u64 v[156:157], s[44:45], 0, v[140:141]
	s_add_i32 m0, s66, 0xc000
	ds_read_b128 v[222:225], v175
	ds_read_b128 v[226:229], v175 offset:1024
	ds_read_b128 v[230:233], v175 offset:2048
	ds_read_b128 v[234:237], v175 offset:3072
	ds_read_b128 v[238:241], v175 offset:4096
	ds_read_b128 v[242:245], v175 offset:5120
	ds_read_b128 v[246:249], v175 offset:6144
	ds_read_b128 v[208:211], v175 offset:7168
	global_load_lds_dwordx4 v[156:157], off
	v_lshl_add_u64 v[156:157], s[44:45], 0, v[142:143]
	s_add_i32 m0, s66, 0xe000
	s_nop 0
	global_load_lds_dwordx4 v[156:157], off
	s_waitcnt vmcnt(8)
	s_waitcnt lgkmcnt(0)
	s_barrier
	s_setprio 1
	s_waitcnt lgkmcnt(0)
	v_mfma_f32_16x16x32_bf16 v[124:127], v[144:147], v[222:225], 0
	v_mfma_f32_16x16x32_bf16 v[120:123], v[152:155], v[222:225], 0
	v_mfma_f32_16x16x32_bf16 v[108:111], v[144:147], v[230:233], 0
	v_mfma_f32_16x16x32_bf16 v[104:107], v[152:155], v[230:233], 0
	v_mfma_f32_16x16x32_bf16 v[92:95], v[144:147], v[238:241], 0
	v_mfma_f32_16x16x32_bf16 v[88:91], v[152:155], v[238:241], 0
	v_mfma_f32_16x16x32_bf16 v[76:79], v[144:147], v[246:249], 0
	v_mfma_f32_16x16x32_bf16 v[72:75], v[152:155], v[246:249], 0
	v_mfma_f32_16x16x32_bf16 v[124:127], v[148:151], v[226:229], v[124:127]
	v_mfma_f32_16x16x32_bf16 v[120:123], v[184:187], v[226:229], v[120:123]
	v_mfma_f32_16x16x32_bf16 v[108:111], v[148:151], v[234:237], v[108:111]
	v_mfma_f32_16x16x32_bf16 v[104:107], v[184:187], v[234:237], v[104:107]
	v_mfma_f32_16x16x32_bf16 v[92:95], v[148:151], v[242:245], v[92:95]
	v_mfma_f32_16x16x32_bf16 v[88:91], v[184:187], v[242:245], v[88:91]
	v_mfma_f32_16x16x32_bf16 v[76:79], v[148:151], v[208:211], v[76:79]
	v_mfma_f32_16x16x32_bf16 v[72:75], v[184:187], v[208:211], v[72:75]
	s_setprio 0
	s_setprio 1
	v_mfma_f32_16x16x32_bf16 v[116:119], v[188:191], v[222:225], 0
	v_mfma_f32_16x16x32_bf16 v[112:115], v[214:217], v[222:225], 0
	v_mfma_f32_16x16x32_bf16 v[100:103], v[188:191], v[230:233], 0
	v_mfma_f32_16x16x32_bf16 v[96:99], v[214:217], v[230:233], 0
	v_mfma_f32_16x16x32_bf16 v[84:87], v[188:191], v[238:241], 0
	v_mfma_f32_16x16x32_bf16 v[80:83], v[214:217], v[238:241], 0
	v_mfma_f32_16x16x32_bf16 v[68:71], v[188:191], v[246:249], 0
	v_mfma_f32_16x16x32_bf16 v[64:67], v[214:217], v[246:249], 0
	v_mfma_f32_16x16x32_bf16 v[116:119], v[192:195], v[226:229], v[116:119]
	v_mfma_f32_16x16x32_bf16 v[112:115], v[218:221], v[226:229], v[112:115]
	v_mfma_f32_16x16x32_bf16 v[100:103], v[192:195], v[234:237], v[100:103]
	v_mfma_f32_16x16x32_bf16 v[96:99], v[218:221], v[234:237], v[96:99]
	v_mfma_f32_16x16x32_bf16 v[84:87], v[192:195], v[242:245], v[84:87]
	v_mfma_f32_16x16x32_bf16 v[80:83], v[218:221], v[242:245], v[80:83]
	v_mfma_f32_16x16x32_bf16 v[68:71], v[192:195], v[208:211], v[68:71]
	v_mfma_f32_16x16x32_bf16 v[64:67], v[218:221], v[208:211], v[64:67]
	s_setprio 0
	s_barrier
	s_add_i32 s91, s59, s65
	v_lshl_add_u64 v[156:157], vcc, 0, v[160:161]
	s_mov_b32 m0, s91
	ds_read_b128 v[208:211], v175 offset:16384
	ds_read_b128 v[222:225], v175 offset:17408
	ds_read_b128 v[226:229], v175 offset:18432
	ds_read_b128 v[230:233], v175 offset:19456
	ds_read_b128 v[234:237], v175 offset:20480
	ds_read_b128 v[238:241], v175 offset:21504
	ds_read_b128 v[242:245], v175 offset:22528
	ds_read_b128 v[246:249], v175 offset:23552
	global_load_lds_dwordx4 v[156:157], off
	s_add_i32 m0, s91, 0x2000
	v_lshl_add_u64 v[250:251], vcc, 0, v[136:137]
	s_add_u32 vcc_lo, vcc_lo, s94
	s_addc_u32 vcc_hi, vcc_hi, 0
	s_add_i32 s90, s90, s65
	global_load_lds_dwordx4 v[250:251], off
	v_lshl_add_u64 v[178:179], vcc, 0, v[160:161]
	s_mov_b32 m0, s90
	v_lshl_add_u64 v[180:181], vcc, 0, v[136:137]
	global_load_lds_dwordx4 v[178:179], off
	s_add_i32 m0, s90, 0x2000
	v_lshl_add_u64 v[204:205], s[48:49], 0, v[132:133]
	global_load_lds_dwordx4 v[180:181], off
	s_mov_b32 m0, s66
	v_lshl_add_u64 v[196:197], s[48:49], 0, v[134:135]
	global_load_lds_dwordx4 v[204:205], off
	s_mov_b32 m0, s67
	s_nop 0
	global_load_lds_dwordx4 v[196:197], off
	s_waitcnt vmcnt(8)
	s_waitcnt lgkmcnt(0)
	s_barrier
; #define PG8_STAGE(bufoff, gbase, voff) do { _Pragma("unroll") for (int _i = 0; _i < 2; ++_i) \
;         __builtin_amdgcn_global_load_lds((const unsigned*)((const char*)(gbase) + (voff)[_i]), (PG8_LAS unsigned*)(lds + (bufoff) + ldsw + _i * 8192), 16, 0, 0); } while (0)
; #define PG8_LDA(dst, b, h) do { _Pragma("unroll") for (int m = 0; m < 4; ++m) _Pragma("unroll") for (int k = 0; k < 2; ++k) dst[m][k] = *(const PG8_LAS bf16x8*)(lds + PG8_SA(b, h) + aoff + m * 2048 + k * 1024); } while (0)
; #define PG8_LDB(dst, b, h) do { _Pragma("unroll") for (int n = 0; n < 2; ++n) _Pragma("unroll") for (int k = 0; k < 2; ++k) dst[n][k] = *(const PG8_LAS bf16x8*)(lds + PG8_SB(b, h) + boff + n * 2048 + k * 1024); } while (0)
; #define PG8_MMA(ai, bj, At, Bt) do { __builtin_amdgcn_s_setprio(1); _Pragma("unroll") for (int m = 0; m < 4; ++m) _Pragma("unroll") for (int n = 0; n < 2; ++n) _Pragma("unroll") for (int k = 0; k < 2; ++k) \
;         acc[ai][bj][m][n] = __builtin_amdgcn_mfma_f32_16x16x32_bf16(Bt[n][k], At[m][k], acc[ai][bj][m][n], 0, 0, 0); __builtin_amdgcn_s_setprio(0); } while (0)
; #define PG8_WAIT_V(n) asm volatile("s_waitcnt vmcnt(" #n ")" ::: "memory")
; #define PG8_WAIT_L(n) asm volatile("s_waitcnt lgkmcnt(" #n ")" ::: "memory")
; #define PG8_BAR __builtin_amdgcn_s_barrier()
; #define PG8_SCHED __builtin_amdgcn_sched_barrier(0)
; template <class Epi, class Sched, bool ALIGN_EPI = false, bool SP2 = false>
; __device__ __forceinline__ void gemm_phase(PG8_LAS unsigned char* lds, const Gemm g, const Sched& S, const Epi& E, const int tid) {
;     ...
;             PG8_WAIT_V(8); PG8_WAIT_L(0); PG8_BAR; PG8_MMA(1, 0, At, B0); PG8_MMA(1, 1, At, B1); PG8_BAR; PG8_SCHED;
;             PG8_LDB(B0, 1, 0); PG8_LDB(B1, 1, 1); PG8_SCHED; PG8_LDA(At, 1, 0); PG8_STAGE(PG8_SA(0, 1), a2 + hstep, voffA);
;             PG8_WAIT_V(8); PG8_WAIT_L(0); PG8_BAR; PG8_MMA(0, 0, At, B0); PG8_MMA(0, 1, At, B1); PG8_BAR; PG8_SCHED;
	s_setprio 1
	s_waitcnt lgkmcnt(0)
	v_mfma_f32_16x16x32_bf16 v[60:63], v[144:147], v[208:211], 0
	v_mfma_f32_16x16x32_bf16 v[56:59], v[152:155], v[208:211], 0
	v_mfma_f32_16x16x32_bf16 v[44:47], v[144:147], v[226:229], 0
	v_mfma_f32_16x16x32_bf16 v[40:43], v[152:155], v[226:229], 0
	v_mfma_f32_16x16x32_bf16 v[28:31], v[144:147], v[234:237], 0
	v_mfma_f32_16x16x32_bf16 v[24:27], v[152:155], v[234:237], 0
	v_mfma_f32_16x16x32_bf16 v[12:15], v[144:147], v[242:245], 0
	v_mfma_f32_16x16x32_bf16 v[8:11], v[152:155], v[242:245], 0
	v_mfma_f32_16x16x32_bf16 v[60:63], v[148:151], v[222:225], v[60:63]
	v_mfma_f32_16x16x32_bf16 v[56:59], v[184:187], v[222:225], v[56:59]
	v_mfma_f32_16x16x32_bf16 v[44:47], v[148:151], v[230:233], v[44:47]
	v_mfma_f32_16x16x32_bf16 v[40:43], v[184:187], v[230:233], v[40:43]
	v_mfma_f32_16x16x32_bf16 v[28:31], v[148:151], v[238:241], v[28:31]
	v_mfma_f32_16x16x32_bf16 v[24:27], v[184:187], v[238:241], v[24:27]
	v_mfma_f32_16x16x32_bf16 v[12:15], v[148:151], v[246:249], v[12:15]
	v_mfma_f32_16x16x32_bf16 v[8:11], v[184:187], v[246:249], v[8:11]
	s_setprio 0
	s_setprio 1
	v_mfma_f32_16x16x32_bf16 v[52:55], v[188:191], v[208:211], 0
	v_mfma_f32_16x16x32_bf16 v[48:51], v[214:217], v[208:211], 0
	v_mfma_f32_16x16x32_bf16 v[36:39], v[188:191], v[226:229], 0
	v_mfma_f32_16x16x32_bf16 v[32:35], v[214:217], v[226:229], 0
	v_mfma_f32_16x16x32_bf16 v[20:23], v[188:191], v[234:237], 0
	v_mfma_f32_16x16x32_bf16 v[16:19], v[214:217], v[234:237], 0
	v_mfma_f32_16x16x32_bf16 v[4:7], v[188:191], v[242:245], 0
	v_mfma_f32_16x16x32_bf16 v[0:3], v[214:217], v[242:245], 0
	v_mfma_f32_16x16x32_bf16 v[52:55], v[192:195], v[222:225], v[52:55]
	v_mfma_f32_16x16x32_bf16 v[48:51], v[218:221], v[222:225], v[48:51]
	v_mfma_f32_16x16x32_bf16 v[36:39], v[192:195], v[230:233], v[36:39]
	v_mfma_f32_16x16x32_bf16 v[32:35], v[218:221], v[230:233], v[32:35]
	v_mfma_f32_16x16x32_bf16 v[20:23], v[192:195], v[238:241], v[20:23]
	v_mfma_f32_16x16x32_bf16 v[16:19], v[218:221], v[238:241], v[16:19]
	v_mfma_f32_16x16x32_bf16 v[4:7], v[192:195], v[246:249], v[4:7]
	v_mfma_f32_16x16x32_bf16 v[0:3], v[218:221], v[246:249], v[0:3]
	s_setprio 0
	s_barrier
	s_add_i32 s90, 0, 0x18000
	v_add_u32_e32 v183, s90, v174
	s_add_i32 s91, 0, 0x1c000
	ds_read_b128 v[144:147], v183
	ds_read_b128 v[148:151], v183 offset:1024
	ds_read_b128 v[152:155], v183 offset:2048
	ds_read_b128 v[184:187], v183 offset:3072
	v_add_u32_e32 v183, s91, v174
	ds_read_b128 v[188:191], v183
	ds_read_b128 v[192:195], v183 offset:1024
	ds_read_b128 v[208:211], v183 offset:2048
	ds_read_b128 v[214:217], v183 offset:3072
	s_add_u32 s48, s48, s94
	s_addc_u32 s49, s49, 0
	s_mov_b32 m0, s68
	v_lshl_add_u64 v[198:199], s[48:49], 0, v[132:133]
	ds_read_b128 v[218:221], v175 offset:32768
	ds_read_b128 v[222:225], v175 offset:33792
	ds_read_b128 v[226:229], v175 offset:34816
	ds_read_b128 v[230:233], v175 offset:35840
	ds_read_b128 v[234:237], v175 offset:36864
	ds_read_b128 v[238:241], v175 offset:37888
	ds_read_b128 v[242:245], v175 offset:38912
	ds_read_b128 v[246:249], v175 offset:39936
	global_load_lds_dwordx4 v[198:199], off
	v_lshl_add_u64 v[198:199], s[48:49], 0, v[134:135]
	s_mov_b32 m0, s69
	s_nop 0
	global_load_lds_dwordx4 v[198:199], off
	s_waitcnt vmcnt(8)
	s_waitcnt lgkmcnt(0)
	s_barrier
	s_setprio 1
	s_waitcnt lgkmcnt(0)
	v_mfma_f32_16x16x32_bf16 v[124:127], v[144:147], v[218:221], v[124:127]
	v_mfma_f32_16x16x32_bf16 v[120:123], v[152:155], v[218:221], v[120:123]
	v_mfma_f32_16x16x32_bf16 v[108:111], v[144:147], v[226:229], v[108:111]
	v_mfma_f32_16x16x32_bf16 v[104:107], v[152:155], v[226:229], v[104:107]
	v_mfma_f32_16x16x32_bf16 v[92:95], v[144:147], v[234:237], v[92:95]
	v_mfma_f32_16x16x32_bf16 v[88:91], v[152:155], v[234:237], v[88:91]
	v_mfma_f32_16x16x32_bf16 v[76:79], v[144:147], v[242:245], v[76:79]
	v_mfma_f32_16x16x32_bf16 v[72:75], v[152:155], v[242:245], v[72:75]
	v_mfma_f32_16x16x32_bf16 v[124:127], v[148:151], v[222:225], v[124:127]
	v_mfma_f32_16x16x32_bf16 v[120:123], v[184:187], v[222:225], v[120:123]
	v_mfma_f32_16x16x32_bf16 v[108:111], v[148:151], v[230:233], v[108:111]
	v_mfma_f32_16x16x32_bf16 v[104:107], v[184:187], v[230:233], v[104:107]
	v_mfma_f32_16x16x32_bf16 v[92:95], v[148:151], v[238:241], v[92:95]
	v_mfma_f32_16x16x32_bf16 v[88:91], v[184:187], v[238:241], v[88:91]
	v_mfma_f32_16x16x32_bf16 v[76:79], v[148:151], v[246:249], v[76:79]
	v_mfma_f32_16x16x32_bf16 v[72:75], v[184:187], v[246:249], v[72:75]
	s_setprio 0
	s_setprio 1
	v_mfma_f32_16x16x32_bf16 v[116:119], v[188:191], v[218:221], v[116:119]
	v_mfma_f32_16x16x32_bf16 v[112:115], v[208:211], v[218:221], v[112:115]
	v_mfma_f32_16x16x32_bf16 v[100:103], v[188:191], v[226:229], v[100:103]
	v_mfma_f32_16x16x32_bf16 v[96:99], v[208:211], v[226:229], v[96:99]
	v_mfma_f32_16x16x32_bf16 v[84:87], v[188:191], v[234:237], v[84:87]
	v_mfma_f32_16x16x32_bf16 v[80:83], v[208:211], v[234:237], v[80:83]
	v_mfma_f32_16x16x32_bf16 v[68:71], v[188:191], v[242:245], v[68:71]
	v_mfma_f32_16x16x32_bf16 v[64:67], v[208:211], v[242:245], v[64:67]
	v_mfma_f32_16x16x32_bf16 v[116:119], v[192:195], v[222:225], v[116:119]
	v_mfma_f32_16x16x32_bf16 v[112:115], v[214:217], v[222:225], v[112:115]
	v_mfma_f32_16x16x32_bf16 v[100:103], v[192:195], v[230:233], v[100:103]
	v_mfma_f32_16x16x32_bf16 v[96:99], v[214:217], v[230:233], v[96:99]
	v_mfma_f32_16x16x32_bf16 v[84:87], v[192:195], v[238:241], v[84:87]
	v_mfma_f32_16x16x32_bf16 v[80:83], v[214:217], v[238:241], v[80:83]
	v_mfma_f32_16x16x32_bf16 v[68:71], v[192:195], v[246:249], v[68:71]
	v_mfma_f32_16x16x32_bf16 v[64:67], v[214:217], v[246:249], v[64:67]
	s_setprio 0
	s_barrier
; #define PG8_STAGE(bufoff, gbase, voff) do { _Pragma("unroll") for (int _i = 0; _i < 2; ++_i) \
;         __builtin_amdgcn_global_load_lds((const unsigned*)((const char*)(gbase) + (voff)[_i]), (PG8_LAS unsigned*)(lds + (bufoff) + ldsw + _i * 8192), 16, 0, 0); } while (0)
; #define PG8_LDA(dst, b, h) do { _Pragma("unroll") for (int m = 0; m < 4; ++m) _Pragma("unroll") for (int k = 0; k < 2; ++k) dst[m][k] = *(const PG8_LAS bf16x8*)(lds + PG8_SA(b, h) + aoff + m * 2048 + k * 1024); } while (0)
; #define PG8_WAIT_V(n) asm volatile("s_waitcnt vmcnt(" #n ")" ::: "memory")
; #define PG8_WAIT_L(n) asm volatile("s_waitcnt lgkmcnt(" #n ")" ::: "memory")
; #define PG8_BAR __builtin_amdgcn_s_barrier()
; template <class Epi, class Sched, bool ALIGN_EPI = false, bool SP2 = false>
; __device__ __forceinline__ void gemm_phase(PG8_LAS unsigned char* lds, const Gemm g, const Sched& S, const Epi& E, const int tid) {
;     ...
;         for (int t = 0; t < nt; t += 2) {
;             const bool last = (t == nt - 2);
;             const char* a1 = cA + (size_t)(t + 1) * kstep;
;             const char* a2 = last ? nA : cA + (size_t)(t + 2) * kstep; const char* b2 = last ? nB : cB + (size_t)(t + 2) * kstep;
;             const char* a3 = a2 + kstep; const char* b3 = b2 + kstep;
;             if (last && has_next) S.a_ready(nxt);
;             if constexpr (SP2) {
;             PG8_LDB(B0, 0, 0); PG8_LDB(B1, 0, 1); PG8_SCHED; PG8_LDA(At, 0, 0); PG8_STAGE(PG8_SA(1, 1), a1 + hstep, voffA);
;             PG8_WAIT_V(8); PG8_WAIT_L(0); PG8_BAR; PG8_MMA(0, 0, At, B0); PG8_MMA(0, 1, At, B1); PG8_BAR; PG8_SCHED;
;             PG8_LDA(At, 0, 1); PG8_STAGE(PG8_SB(0, 0), b2, voffB); PG8_STAGE(PG8_SB(0, 1), b2 + hstep, voffB); PG8_STAGE(PG8_SA(0, 0), a2, voffA);
;             PG8_WAIT_V(8); PG8_WAIT_L(0); PG8_BAR; PG8_MMA(1, 0, At, B0); PG8_MMA(1, 1, At, B1); PG8_BAR; PG8_SCHED;
;             PG8_LDB(B0, 1, 0); PG8_LDB(B1, 1, 1); PG8_SCHED; PG8_LDA(At, 1, 0); PG8_STAGE(PG8_SA(0, 1), a2 + hstep, voffA);
;             PG8_WAIT_V(8); PG8_WAIT_L(0); PG8_BAR; PG8_MMA(0, 0, At, B0); PG8_MMA(0, 1, At, B1); PG8_BAR; PG8_SCHED;
;             PG8_LDA(At, 1, 1); PG8_STAGE(PG8_SB(1, 0), b3, voffB); PG8_STAGE(PG8_SB(1, 1), b3 + hstep, voffB); PG8_STAGE(PG8_SA(1, 0), a3, voffA);
;             PG8_WAIT_V(8); PG8_WAIT_L(0); PG8_BAR; PG8_MMA(1, 0, At, B0); PG8_MMA(1, 1, At, B1); PG8_BAR; PG8_SCHED;
	s_add_i32 s48, s90, s65
	v_lshl_add_u64 v[156:157], v[156:157], 0, s[28:29]
	s_mov_b32 m0, s48
	ds_read_b128 v[218:221], v175 offset:49152
	ds_read_b128 v[222:225], v175 offset:50176
	ds_read_b128 v[226:229], v175 offset:51200
	ds_read_b128 v[230:233], v175 offset:52224
	ds_read_b128 v[234:237], v175 offset:53248
	ds_read_b128 v[238:241], v175 offset:54272
	ds_read_b128 v[242:245], v175 offset:55296
	ds_read_b128 v[246:249], v175 offset:56320
	global_load_lds_dwordx4 v[156:157], off
	v_lshl_add_u64 v[156:157], v[250:251], 0, s[28:29]
	s_add_i32 m0, s48, 0x2000
	s_add_i32 s48, s91, s65
	global_load_lds_dwordx4 v[156:157], off
	v_lshl_add_u64 v[156:157], v[178:179], 0, s[28:29]
	s_mov_b32 m0, s48
	s_nop 0
	global_load_lds_dwordx4 v[156:157], off
	v_lshl_add_u64 v[156:157], v[180:181], 0, s[28:29]
	s_add_i32 m0, s48, 0x2000
	s_nop 0
	global_load_lds_dwordx4 v[156:157], off
	v_lshl_add_u64 v[156:157], v[204:205], 0, s[28:29]
	s_mov_b32 m0, s70
	s_nop 0
	global_load_lds_dwordx4 v[156:157], off
	v_lshl_add_u64 v[156:157], v[196:197], 0, s[28:29]
	s_mov_b32 m0, s71
	s_nop 0
	global_load_lds_dwordx4 v[156:157], off
	s_waitcnt vmcnt(8)
	s_waitcnt lgkmcnt(0)
	s_barrier
	s_setprio 1
	s_waitcnt lgkmcnt(0)
	v_mfma_f32_16x16x32_bf16 v[60:63], v[144:147], v[218:221], v[60:63]
	v_mfma_f32_16x16x32_bf16 v[56:59], v[152:155], v[218:221], v[56:59]
	v_mfma_f32_16x16x32_bf16 v[44:47], v[144:147], v[226:229], v[44:47]
	v_mfma_f32_16x16x32_bf16 v[40:43], v[152:155], v[226:229], v[40:43]
	v_mfma_f32_16x16x32_bf16 v[28:31], v[144:147], v[234:237], v[28:31]
	v_mfma_f32_16x16x32_bf16 v[24:27], v[152:155], v[234:237], v[24:27]
	v_mfma_f32_16x16x32_bf16 v[12:15], v[144:147], v[242:245], v[12:15]
	v_mfma_f32_16x16x32_bf16 v[8:11], v[152:155], v[242:245], v[8:11]
	v_mfma_f32_16x16x32_bf16 v[60:63], v[148:151], v[222:225], v[60:63]
	v_mfma_f32_16x16x32_bf16 v[56:59], v[184:187], v[222:225], v[56:59]
	v_mfma_f32_16x16x32_bf16 v[44:47], v[148:151], v[230:233], v[44:47]
	v_mfma_f32_16x16x32_bf16 v[40:43], v[184:187], v[230:233], v[40:43]
	v_mfma_f32_16x16x32_bf16 v[28:31], v[148:151], v[238:241], v[28:31]
	v_mfma_f32_16x16x32_bf16 v[24:27], v[184:187], v[238:241], v[24:27]
	v_mfma_f32_16x16x32_bf16 v[12:15], v[148:151], v[246:249], v[12:15]
	v_mfma_f32_16x16x32_bf16 v[8:11], v[184:187], v[246:249], v[8:11]
	s_setprio 0
	s_setprio 1
	v_mfma_f32_16x16x32_bf16 v[52:55], v[188:191], v[218:221], v[52:55]
	s_add_u32 s44, s44, 0x100
	v_mfma_f32_16x16x32_bf16 v[48:51], v[208:211], v[218:221], v[48:51]
	s_addc_u32 s45, s45, 0
	v_mfma_f32_16x16x32_bf16 v[36:39], v[188:191], v[226:229], v[36:39]
	s_add_u32 s37, s37, 0x100
	v_mfma_f32_16x16x32_bf16 v[32:35], v[208:211], v[226:229], v[32:35]
	s_addc_u32 s50, s50, 0
	v_mfma_f32_16x16x32_bf16 v[20:23], v[188:191], v[234:237], v[20:23]
	s_cmp_ge_u32 s51, s80
	v_mfma_f32_16x16x32_bf16 v[16:19], v[208:211], v[234:237], v[16:19]
	s_mov_b32 s48, s51
	v_mfma_f32_16x16x32_bf16 v[4:7], v[188:191], v[242:245], v[4:7]
	v_mfma_f32_16x16x32_bf16 v[0:3], v[208:211], v[242:245], v[0:3]
	v_mfma_f32_16x16x32_bf16 v[52:55], v[192:195], v[222:225], v[52:55]
	v_mfma_f32_16x16x32_bf16 v[48:51], v[214:217], v[222:225], v[48:51]
	v_mfma_f32_16x16x32_bf16 v[36:39], v[192:195], v[230:233], v[36:39]
	v_mfma_f32_16x16x32_bf16 v[32:35], v[214:217], v[230:233], v[32:35]
	v_mfma_f32_16x16x32_bf16 v[20:23], v[192:195], v[238:241], v[20:23]
	v_mfma_f32_16x16x32_bf16 v[16:19], v[214:217], v[238:241], v[16:19]
	v_mfma_f32_16x16x32_bf16 v[4:7], v[192:195], v[246:249], v[4:7]
	v_mfma_f32_16x16x32_bf16 v[0:3], v[214:217], v[246:249], v[0:3]
	s_setprio 0
	s_barrier
	s_cbranch_scc1 .Lmy_kdone_3
.LBB0_621:
	s_add_i32 s51, s48, 2
	s_add_u32 vcc_lo, s44, 0x80
	s_addc_u32 s49, s45, 0
	s_cmp_eq_u32 s82, s48
	s_cselect_b32 s49, s35, s49
	s_cselect_b32 s48, s34, vcc_lo
	v_add_u32_e32 v156, s59, v174
	s_cselect_b32 vcc_hi, s47, s50
	s_cselect_b32 vcc_lo, s46, s37
	s_add_i32 s90, 0, 0x14000
	s_waitcnt lgkmcnt(0)
	ds_read_b128 v[144:147], v156
	ds_read_b128 v[148:151], v156 offset:1024
	ds_read_b128 v[152:155], v156 offset:2048
	ds_read_b128 v[184:187], v156 offset:3072
	v_add_u32_e32 v156, s90, v174
	ds_read_b128 v[188:191], v156
	ds_read_b128 v[192:195], v156 offset:1024
	ds_read_b128 v[214:217], v156 offset:2048
	ds_read_b128 v[218:221], v156 offset:3072
	v_lshl_add_u64 v[156:157], s[44:45], 0, v[140:141]
	s_add_i32 m0, s66, 0xc000
	ds_read_b128 v[222:225], v175
	ds_read_b128 v[226:229], v175 offset:1024
	ds_read_b128 v[230:233], v175 offset:2048
	ds_read_b128 v[234:237], v175 offset:3072
	ds_read_b128 v[238:241], v175 offset:4096
	ds_read_b128 v[242:245], v175 offset:5120
	ds_read_b128 v[246:249], v175 offset:6144
	ds_read_b128 v[208:211], v175 offset:7168
	global_load_lds_dwordx4 v[156:157], off
	v_lshl_add_u64 v[156:157], s[44:45], 0, v[142:143]
	s_add_i32 m0, s66, 0xe000
	s_nop 0
	global_load_lds_dwordx4 v[156:157], off
	s_waitcnt vmcnt(8)
	s_waitcnt lgkmcnt(0)
	s_barrier
; #define PG8_STAGE(bufoff, gbase, voff) do { _Pragma("unroll") for (int _i = 0; _i < 2; ++_i) \
;         __builtin_amdgcn_global_load_lds((const unsigned*)((const char*)(gbase) + (voff)[_i]), (PG8_LAS unsigned*)(lds + (bufoff) + ldsw + _i * 8192), 16, 0, 0); } while (0)
; #define PG8_LDA(dst, b, h) do { _Pragma("unroll") for (int m = 0; m < 4; ++m) _Pragma("unroll") for (int k = 0; k < 2; ++k) dst[m][k] = *(const PG8_LAS bf16x8*)(lds + PG8_SA(b, h) + aoff + m * 2048 + k * 1024); } while (0)
; #define PG8_MMA(ai, bj, At, Bt) do { __builtin_amdgcn_s_setprio(1); _Pragma("unroll") for (int m = 0; m < 4; ++m) _Pragma("unroll") for (int n = 0; n < 2; ++n) _Pragma("unroll") for (int k = 0; k < 2; ++k) \
;         acc[ai][bj][m][n] = __builtin_amdgcn_mfma_f32_16x16x32_bf16(Bt[n][k], At[m][k], acc[ai][bj][m][n], 0, 0, 0); __builtin_amdgcn_s_setprio(0); } while (0)
; #define PG8_WAIT_V(n) asm volatile("s_waitcnt vmcnt(" #n ")" ::: "memory")
; #define PG8_WAIT_L(n) asm volatile("s_waitcnt lgkmcnt(" #n ")" ::: "memory")
; #define PG8_BAR __builtin_amdgcn_s_barrier()
; #define PG8_SCHED __builtin_amdgcn_sched_barrier(0)
; template <class Epi, class Sched, bool ALIGN_EPI = false, bool SP2 = false>
; __device__ __forceinline__ void gemm_phase(PG8_LAS unsigned char* lds, const Gemm g, const Sched& S, const Epi& E, const int tid) {
;     ...
;             PG8_WAIT_V(8); PG8_WAIT_L(0); PG8_BAR; PG8_MMA(0, 0, At, B0); PG8_MMA(0, 1, At, B1); PG8_BAR; PG8_SCHED;
;             PG8_LDA(At, 0, 1); PG8_STAGE(PG8_SB(0, 0), b2, voffB); PG8_STAGE(PG8_SB(0, 1), b2 + hstep, voffB); PG8_STAGE(PG8_SA(0, 0), a2, voffA);
;             PG8_WAIT_V(8); PG8_WAIT_L(0); PG8_BAR; PG8_MMA(1, 0, At, B0); PG8_MMA(1, 1, At, B1); PG8_BAR; PG8_SCHED;
	s_setprio 1
	s_waitcnt lgkmcnt(0)
	v_mfma_f32_16x16x32_bf16 v[124:127], v[144:147], v[222:225], v[124:127]
	v_mfma_f32_16x16x32_bf16 v[120:123], v[152:155], v[222:225], v[120:123]
	v_mfma_f32_16x16x32_bf16 v[108:111], v[144:147], v[230:233], v[108:111]
	v_mfma_f32_16x16x32_bf16 v[104:107], v[152:155], v[230:233], v[104:107]
	v_mfma_f32_16x16x32_bf16 v[92:95], v[144:147], v[238:241], v[92:95]
	v_mfma_f32_16x16x32_bf16 v[88:91], v[152:155], v[238:241], v[88:91]
	v_mfma_f32_16x16x32_bf16 v[76:79], v[144:147], v[246:249], v[76:79]
	v_mfma_f32_16x16x32_bf16 v[72:75], v[152:155], v[246:249], v[72:75]
	v_mfma_f32_16x16x32_bf16 v[124:127], v[148:151], v[226:229], v[124:127]
	v_mfma_f32_16x16x32_bf16 v[120:123], v[184:187], v[226:229], v[120:123]
	v_mfma_f32_16x16x32_bf16 v[108:111], v[148:151], v[234:237], v[108:111]
	v_mfma_f32_16x16x32_bf16 v[104:107], v[184:187], v[234:237], v[104:107]
	v_mfma_f32_16x16x32_bf16 v[92:95], v[148:151], v[242:245], v[92:95]
	v_mfma_f32_16x16x32_bf16 v[88:91], v[184:187], v[242:245], v[88:91]
	v_mfma_f32_16x16x32_bf16 v[76:79], v[148:151], v[208:211], v[76:79]
	v_mfma_f32_16x16x32_bf16 v[72:75], v[184:187], v[208:211], v[72:75]
	s_setprio 0
	s_setprio 1
	v_mfma_f32_16x16x32_bf16 v[116:119], v[188:191], v[222:225], v[116:119]
	v_mfma_f32_16x16x32_bf16 v[112:115], v[214:217], v[222:225], v[112:115]
	v_mfma_f32_16x16x32_bf16 v[100:103], v[188:191], v[230:233], v[100:103]
	v_mfma_f32_16x16x32_bf16 v[96:99], v[214:217], v[230:233], v[96:99]
	v_mfma_f32_16x16x32_bf16 v[84:87], v[188:191], v[238:241], v[84:87]
	v_mfma_f32_16x16x32_bf16 v[80:83], v[214:217], v[238:241], v[80:83]
	v_mfma_f32_16x16x32_bf16 v[68:71], v[188:191], v[246:249], v[68:71]
	v_mfma_f32_16x16x32_bf16 v[64:67], v[214:217], v[246:249], v[64:67]
	v_mfma_f32_16x16x32_bf16 v[116:119], v[192:195], v[226:229], v[116:119]
	v_mfma_f32_16x16x32_bf16 v[112:115], v[218:221], v[226:229], v[112:115]
	v_mfma_f32_16x16x32_bf16 v[100:103], v[192:195], v[234:237], v[100:103]
	v_mfma_f32_16x16x32_bf16 v[96:99], v[218:221], v[234:237], v[96:99]
	v_mfma_f32_16x16x32_bf16 v[84:87], v[192:195], v[242:245], v[84:87]
	v_mfma_f32_16x16x32_bf16 v[80:83], v[218:221], v[242:245], v[80:83]
	v_mfma_f32_16x16x32_bf16 v[68:71], v[192:195], v[208:211], v[68:71]
	v_mfma_f32_16x16x32_bf16 v[64:67], v[218:221], v[208:211], v[64:67]
	s_setprio 0
	s_barrier
	s_add_i32 s91, s59, s65
	v_lshl_add_u64 v[156:157], vcc, 0, v[160:161]
	s_mov_b32 m0, s91
	ds_read_b128 v[208:211], v175 offset:16384
	ds_read_b128 v[222:225], v175 offset:17408
	ds_read_b128 v[226:229], v175 offset:18432
	ds_read_b128 v[230:233], v175 offset:19456
	ds_read_b128 v[234:237], v175 offset:20480
	ds_read_b128 v[238:241], v175 offset:21504
	ds_read_b128 v[242:245], v175 offset:22528
	ds_read_b128 v[246:249], v175 offset:23552
	global_load_lds_dwordx4 v[156:157], off
	s_add_i32 m0, s91, 0x2000
	v_lshl_add_u64 v[250:251], vcc, 0, v[136:137]
	s_add_u32 vcc_lo, vcc_lo, s94
	s_addc_u32 vcc_hi, vcc_hi, 0
	s_add_i32 s90, s90, s65
	global_load_lds_dwordx4 v[250:251], off
	v_lshl_add_u64 v[178:179], vcc, 0, v[160:161]
	s_mov_b32 m0, s90
	v_lshl_add_u64 v[180:181], vcc, 0, v[136:137]
	global_load_lds_dwordx4 v[178:179], off
	s_add_i32 m0, s90, 0x2000
	v_lshl_add_u64 v[204:205], s[48:49], 0, v[132:133]
	global_load_lds_dwordx4 v[180:181], off
	s_mov_b32 m0, s66
	v_lshl_add_u64 v[196:197], s[48:49], 0, v[134:135]
	global_load_lds_dwordx4 v[204:205], off
	s_mov_b32 m0, s67
	s_nop 0
	global_load_lds_dwordx4 v[196:197], off
	s_waitcnt vmcnt(8)
	s_waitcnt lgkmcnt(0)
	s_barrier
	s_setprio 1
	s_waitcnt lgkmcnt(0)
	v_mfma_f32_16x16x32_bf16 v[60:63], v[144:147], v[208:211], v[60:63]
	v_mfma_f32_16x16x32_bf16 v[56:59], v[152:155], v[208:211], v[56:59]
	v_mfma_f32_16x16x32_bf16 v[44:47], v[144:147], v[226:229], v[44:47]
	v_mfma_f32_16x16x32_bf16 v[40:43], v[152:155], v[226:229], v[40:43]
	v_mfma_f32_16x16x32_bf16 v[28:31], v[144:147], v[234:237], v[28:31]
	v_mfma_f32_16x16x32_bf16 v[24:27], v[152:155], v[234:237], v[24:27]
	v_mfma_f32_16x16x32_bf16 v[12:15], v[144:147], v[242:245], v[12:15]
	v_mfma_f32_16x16x32_bf16 v[8:11], v[152:155], v[242:245], v[8:11]
	v_mfma_f32_16x16x32_bf16 v[60:63], v[148:151], v[222:225], v[60:63]
	v_mfma_f32_16x16x32_bf16 v[56:59], v[184:187], v[222:225], v[56:59]
	v_mfma_f32_16x16x32_bf16 v[44:47], v[148:151], v[230:233], v[44:47]
	v_mfma_f32_16x16x32_bf16 v[40:43], v[184:187], v[230:233], v[40:43]
	v_mfma_f32_16x16x32_bf16 v[28:31], v[148:151], v[238:241], v[28:31]
	v_mfma_f32_16x16x32_bf16 v[24:27], v[184:187], v[238:241], v[24:27]
	v_mfma_f32_16x16x32_bf16 v[12:15], v[148:151], v[246:249], v[12:15]
	v_mfma_f32_16x16x32_bf16 v[8:11], v[184:187], v[246:249], v[8:11]
	s_setprio 0
	s_setprio 1
	v_mfma_f32_16x16x32_bf16 v[52:55], v[188:191], v[208:211], v[52:55]
	v_mfma_f32_16x16x32_bf16 v[48:51], v[214:217], v[208:211], v[48:51]
	v_mfma_f32_16x16x32_bf16 v[36:39], v[188:191], v[226:229], v[36:39]
	v_mfma_f32_16x16x32_bf16 v[32:35], v[214:217], v[226:229], v[32:35]
	v_mfma_f32_16x16x32_bf16 v[20:23], v[188:191], v[234:237], v[20:23]
	v_mfma_f32_16x16x32_bf16 v[16:19], v[214:217], v[234:237], v[16:19]
	v_mfma_f32_16x16x32_bf16 v[4:7], v[188:191], v[242:245], v[4:7]
	v_mfma_f32_16x16x32_bf16 v[0:3], v[214:217], v[242:245], v[0:3]
	v_mfma_f32_16x16x32_bf16 v[52:55], v[192:195], v[222:225], v[52:55]
	v_mfma_f32_16x16x32_bf16 v[48:51], v[218:221], v[222:225], v[48:51]
	v_mfma_f32_16x16x32_bf16 v[36:39], v[192:195], v[230:233], v[36:39]
	v_mfma_f32_16x16x32_bf16 v[32:35], v[218:221], v[230:233], v[32:35]
	v_mfma_f32_16x16x32_bf16 v[20:23], v[192:195], v[238:241], v[20:23]
	v_mfma_f32_16x16x32_bf16 v[16:19], v[218:221], v[238:241], v[16:19]
	v_mfma_f32_16x16x32_bf16 v[4:7], v[192:195], v[246:249], v[4:7]
	v_mfma_f32_16x16x32_bf16 v[0:3], v[218:221], v[246:249], v[0:3]
	s_setprio 0
	s_barrier
; #define PG8_STAGE(bufoff, gbase, voff) do { _Pragma("unroll") for (int _i = 0; _i < 2; ++_i) \
;         __builtin_amdgcn_global_load_lds((const unsigned*)((const char*)(gbase) + (voff)[_i]), (PG8_LAS unsigned*)(lds + (bufoff) + ldsw + _i * 8192), 16, 0, 0); } while (0)
; #define PG8_LDA(dst, b, h) do { _Pragma("unroll") for (int m = 0; m < 4; ++m) _Pragma("unroll") for (int k = 0; k < 2; ++k) dst[m][k] = *(const PG8_LAS bf16x8*)(lds + PG8_SA(b, h) + aoff + m * 2048 + k * 1024); } while (0)
; #define PG8_LDB(dst, b, h) do { _Pragma("unroll") for (int n = 0; n < 2; ++n) _Pragma("unroll") for (int k = 0; k < 2; ++k) dst[n][k] = *(const PG8_LAS bf16x8*)(lds + PG8_SB(b, h) + boff + n * 2048 + k * 1024); } while (0)
; #define PG8_MMA(ai, bj, At, Bt) do { __builtin_amdgcn_s_setprio(1); _Pragma("unroll") for (int m = 0; m < 4; ++m) _Pragma("unroll") for (int n = 0; n < 2; ++n) _Pragma("unroll") for (int k = 0; k < 2; ++k) \
;         acc[ai][bj][m][n] = __builtin_amdgcn_mfma_f32_16x16x32_bf16(Bt[n][k], At[m][k], acc[ai][bj][m][n], 0, 0, 0); __builtin_amdgcn_s_setprio(0); } while (0)
; #define PG8_WAIT_V(n) asm volatile("s_waitcnt vmcnt(" #n ")" ::: "memory")
; #define PG8_WAIT_L(n) asm volatile("s_waitcnt lgkmcnt(" #n ")" ::: "memory")
; #define PG8_BAR __builtin_amdgcn_s_barrier()
; #define PG8_SCHED __builtin_amdgcn_sched_barrier(0)
; template <class Epi, class Sched, bool ALIGN_EPI = false, bool SP2 = false>
; __device__ __forceinline__ void gemm_phase(PG8_LAS unsigned char* lds, const Gemm g, const Sched& S, const Epi& E, const int tid) {
;     ...
;             PG8_LDB(B0, 1, 0); PG8_LDB(B1, 1, 1); PG8_SCHED; PG8_LDA(At, 1, 0); PG8_STAGE(PG8_SA(0, 1), a2 + hstep, voffA);
;             PG8_WAIT_V(8); PG8_WAIT_L(0); PG8_BAR; PG8_MMA(0, 0, At, B0); PG8_MMA(0, 1, At, B1); PG8_BAR; PG8_SCHED;
	s_add_i32 s90, 0, 0x18000
	v_add_u32_e32 v183, s90, v174
	s_add_i32 s91, 0, 0x1c000
	ds_read_b128 v[144:147], v183
	ds_read_b128 v[148:151], v183 offset:1024
	ds_read_b128 v[152:155], v183 offset:2048
	ds_read_b128 v[184:187], v183 offset:3072
	v_add_u32_e32 v183, s91, v174
	ds_read_b128 v[188:191], v183
	ds_read_b128 v[192:195], v183 offset:1024
	ds_read_b128 v[208:211], v183 offset:2048
	ds_read_b128 v[214:217], v183 offset:3072
	s_add_u32 s48, s48, s94
	s_addc_u32 s49, s49, 0
	s_mov_b32 m0, s68
	v_lshl_add_u64 v[198:199], s[48:49], 0, v[132:133]
	ds_read_b128 v[218:221], v175 offset:32768
	ds_read_b128 v[222:225], v175 offset:33792
	ds_read_b128 v[226:229], v175 offset:34816
	ds_read_b128 v[230:233], v175 offset:35840
	ds_read_b128 v[234:237], v175 offset:36864
	ds_read_b128 v[238:241], v175 offset:37888
	ds_read_b128 v[242:245], v175 offset:38912
	ds_read_b128 v[246:249], v175 offset:39936
	global_load_lds_dwordx4 v[198:199], off
	v_lshl_add_u64 v[198:199], s[48:49], 0, v[134:135]
	s_mov_b32 m0, s69
	s_nop 0
	global_load_lds_dwordx4 v[198:199], off
	s_waitcnt vmcnt(8)
	s_waitcnt lgkmcnt(0)
	s_barrier
	s_setprio 1
	s_waitcnt lgkmcnt(0)
	v_mfma_f32_16x16x32_bf16 v[124:127], v[144:147], v[218:221], v[124:127]
	v_mfma_f32_16x16x32_bf16 v[120:123], v[152:155], v[218:221], v[120:123]
	v_mfma_f32_16x16x32_bf16 v[108:111], v[144:147], v[226:229], v[108:111]
	v_mfma_f32_16x16x32_bf16 v[104:107], v[152:155], v[226:229], v[104:107]
	v_mfma_f32_16x16x32_bf16 v[92:95], v[144:147], v[234:237], v[92:95]
	v_mfma_f32_16x16x32_bf16 v[88:91], v[152:155], v[234:237], v[88:91]
	v_mfma_f32_16x16x32_bf16 v[76:79], v[144:147], v[242:245], v[76:79]
	v_mfma_f32_16x16x32_bf16 v[72:75], v[152:155], v[242:245], v[72:75]
	v_mfma_f32_16x16x32_bf16 v[124:127], v[148:151], v[222:225], v[124:127]
	v_mfma_f32_16x16x32_bf16 v[120:123], v[184:187], v[222:225], v[120:123]
	v_mfma_f32_16x16x32_bf16 v[108:111], v[148:151], v[230:233], v[108:111]
	v_mfma_f32_16x16x32_bf16 v[104:107], v[184:187], v[230:233], v[104:107]
	v_mfma_f32_16x16x32_bf16 v[92:95], v[148:151], v[238:241], v[92:95]
	v_mfma_f32_16x16x32_bf16 v[88:91], v[184:187], v[238:241], v[88:91]
	v_mfma_f32_16x16x32_bf16 v[76:79], v[148:151], v[246:249], v[76:79]
	v_mfma_f32_16x16x32_bf16 v[72:75], v[184:187], v[246:249], v[72:75]
	s_setprio 0
	s_setprio 1
	v_mfma_f32_16x16x32_bf16 v[116:119], v[188:191], v[218:221], v[116:119]
	v_mfma_f32_16x16x32_bf16 v[112:115], v[208:211], v[218:221], v[112:115]
	v_mfma_f32_16x16x32_bf16 v[100:103], v[188:191], v[226:229], v[100:103]
	v_mfma_f32_16x16x32_bf16 v[96:99], v[208:211], v[226:229], v[96:99]
	v_mfma_f32_16x16x32_bf16 v[84:87], v[188:191], v[234:237], v[84:87]
	v_mfma_f32_16x16x32_bf16 v[80:83], v[208:211], v[234:237], v[80:83]
	v_mfma_f32_16x16x32_bf16 v[68:71], v[188:191], v[242:245], v[68:71]
	v_mfma_f32_16x16x32_bf16 v[64:67], v[208:211], v[242:245], v[64:67]
	v_mfma_f32_16x16x32_bf16 v[116:119], v[192:195], v[222:225], v[116:119]
	v_mfma_f32_16x16x32_bf16 v[112:115], v[214:217], v[222:225], v[112:115]
	v_mfma_f32_16x16x32_bf16 v[100:103], v[192:195], v[230:233], v[100:103]
	v_mfma_f32_16x16x32_bf16 v[96:99], v[214:217], v[230:233], v[96:99]
	v_mfma_f32_16x16x32_bf16 v[84:87], v[192:195], v[238:241], v[84:87]
	v_mfma_f32_16x16x32_bf16 v[80:83], v[214:217], v[238:241], v[80:83]
	v_mfma_f32_16x16x32_bf16 v[68:71], v[192:195], v[246:249], v[68:71]
	v_mfma_f32_16x16x32_bf16 v[64:67], v[214:217], v[246:249], v[64:67]
	s_setprio 0
	s_barrier
; #define PG8_STAGE(bufoff, gbase, voff) do { _Pragma("unroll") for (int _i = 0; _i < 2; ++_i) \
;         __builtin_amdgcn_global_load_lds((const unsigned*)((const char*)(gbase) + (voff)[_i]), (PG8_LAS unsigned*)(lds + (bufoff) + ldsw + _i * 8192), 16, 0, 0); } while (0)
; #define PG8_LDA(dst, b, h) do { _Pragma("unroll") for (int m = 0; m < 4; ++m) _Pragma("unroll") for (int k = 0; k < 2; ++k) dst[m][k] = *(const PG8_LAS bf16x8*)(lds + PG8_SA(b, h) + aoff + m * 2048 + k * 1024); } while (0)
; #define PG8_MMA(ai, bj, At, Bt) do { __builtin_amdgcn_s_setprio(1); _Pragma("unroll") for (int m = 0; m < 4; ++m) _Pragma("unroll") for (int n = 0; n < 2; ++n) _Pragma("unroll") for (int k = 0; k < 2; ++k) \
;         acc[ai][bj][m][n] = __builtin_amdgcn_mfma_f32_16x16x32_bf16(Bt[n][k], At[m][k], acc[ai][bj][m][n], 0, 0, 0); __builtin_amdgcn_s_setprio(0); } while (0)
; #define PG8_WAIT_V(n) asm volatile("s_waitcnt vmcnt(" #n ")" ::: "memory")
; #define PG8_WAIT_L(n) asm volatile("s_waitcnt lgkmcnt(" #n ")" ::: "memory")
; #define PG8_BAR __builtin_amdgcn_s_barrier()
; #define PG8_SCHED __builtin_amdgcn_sched_barrier(0)
; template <class Epi, class Sched, bool ALIGN_EPI = false, bool SP2 = false>
; __device__ __forceinline__ void gemm_phase(PG8_LAS unsigned char* lds, const Gemm g, const Sched& S, const Epi& E, const int tid) {
;     ...
;             PG8_LDA(At, 1, 1); PG8_STAGE(PG8_SB(1, 0), b3, voffB); PG8_STAGE(PG8_SB(1, 1), b3 + hstep, voffB); PG8_STAGE(PG8_SA(1, 0), a3, voffA);
;             PG8_WAIT_V(8); PG8_WAIT_L(0); PG8_BAR; PG8_MMA(1, 0, At, B0); PG8_MMA(1, 1, At, B1); PG8_BAR; PG8_SCHED;
	s_add_i32 s48, s90, s65
	v_lshl_add_u64 v[156:157], v[156:157], 0, s[28:29]
	s_mov_b32 m0, s48
	ds_read_b128 v[218:221], v175 offset:49152
	ds_read_b128 v[222:225], v175 offset:50176
	ds_read_b128 v[226:229], v175 offset:51200
	ds_read_b128 v[230:233], v175 offset:52224
	ds_read_b128 v[234:237], v175 offset:53248
	ds_read_b128 v[238:241], v175 offset:54272
	ds_read_b128 v[242:245], v175 offset:55296
	ds_read_b128 v[246:249], v175 offset:56320
	global_load_lds_dwordx4 v[156:157], off
	v_lshl_add_u64 v[156:157], v[250:251], 0, s[28:29]
	s_add_i32 m0, s48, 0x2000
	s_add_i32 s48, s91, s65
	global_load_lds_dwordx4 v[156:157], off
	v_lshl_add_u64 v[156:157], v[178:179], 0, s[28:29]
	s_mov_b32 m0, s48
	s_nop 0
	global_load_lds_dwordx4 v[156:157], off
	v_lshl_add_u64 v[156:157], v[180:181], 0, s[28:29]
	s_add_i32 m0, s48, 0x2000
	s_nop 0
	global_load_lds_dwordx4 v[156:157], off
	v_lshl_add_u64 v[156:157], v[204:205], 0, s[28:29]
	s_mov_b32 m0, s70
	s_nop 0
	global_load_lds_dwordx4 v[156:157], off
	v_lshl_add_u64 v[156:157], v[196:197], 0, s[28:29]
	s_mov_b32 m0, s71
	s_nop 0
	global_load_lds_dwordx4 v[156:157], off
	s_waitcnt vmcnt(8)
	s_waitcnt lgkmcnt(0)
	s_barrier
	s_setprio 1
	s_waitcnt lgkmcnt(0)
	v_mfma_f32_16x16x32_bf16 v[60:63], v[144:147], v[218:221], v[60:63]
	v_mfma_f32_16x16x32_bf16 v[56:59], v[152:155], v[218:221], v[56:59]
	v_mfma_f32_16x16x32_bf16 v[44:47], v[144:147], v[226:229], v[44:47]
	v_mfma_f32_16x16x32_bf16 v[40:43], v[152:155], v[226:229], v[40:43]
	v_mfma_f32_16x16x32_bf16 v[28:31], v[144:147], v[234:237], v[28:31]
	v_mfma_f32_16x16x32_bf16 v[24:27], v[152:155], v[234:237], v[24:27]
	v_mfma_f32_16x16x32_bf16 v[12:15], v[144:147], v[242:245], v[12:15]
	v_mfma_f32_16x16x32_bf16 v[8:11], v[152:155], v[242:245], v[8:11]
	v_mfma_f32_16x16x32_bf16 v[60:63], v[148:151], v[222:225], v[60:63]
	v_mfma_f32_16x16x32_bf16 v[56:59], v[184:187], v[222:225], v[56:59]
	v_mfma_f32_16x16x32_bf16 v[44:47], v[148:151], v[230:233], v[44:47]
	v_mfma_f32_16x16x32_bf16 v[40:43], v[184:187], v[230:233], v[40:43]
	v_mfma_f32_16x16x32_bf16 v[28:31], v[148:151], v[238:241], v[28:31]
	v_mfma_f32_16x16x32_bf16 v[24:27], v[184:187], v[238:241], v[24:27]
	v_mfma_f32_16x16x32_bf16 v[12:15], v[148:151], v[246:249], v[12:15]
	v_mfma_f32_16x16x32_bf16 v[8:11], v[184:187], v[246:249], v[8:11]
	s_setprio 0
	s_setprio 1
	v_mfma_f32_16x16x32_bf16 v[52:55], v[188:191], v[218:221], v[52:55]
	s_add_u32 s44, s44, 0x100
	v_mfma_f32_16x16x32_bf16 v[48:51], v[208:211], v[218:221], v[48:51]
	s_addc_u32 s45, s45, 0
	v_mfma_f32_16x16x32_bf16 v[36:39], v[188:191], v[226:229], v[36:39]
	s_add_u32 s37, s37, 0x100
	v_mfma_f32_16x16x32_bf16 v[32:35], v[208:211], v[226:229], v[32:35]
	s_addc_u32 s50, s50, 0
	v_mfma_f32_16x16x32_bf16 v[20:23], v[188:191], v[234:237], v[20:23]
	s_cmp_ge_u32 s51, s80
	v_mfma_f32_16x16x32_bf16 v[16:19], v[208:211], v[234:237], v[16:19]
	s_mov_b32 s48, s51
	v_mfma_f32_16x16x32_bf16 v[4:7], v[188:191], v[242:245], v[4:7]
	v_mfma_f32_16x16x32_bf16 v[0:3], v[208:211], v[242:245], v[0:3]
	v_mfma_f32_16x16x32_bf16 v[52:55], v[192:195], v[222:225], v[52:55]
	v_mfma_f32_16x16x32_bf16 v[48:51], v[214:217], v[222:225], v[48:51]
	v_mfma_f32_16x16x32_bf16 v[36:39], v[192:195], v[230:233], v[36:39]
	v_mfma_f32_16x16x32_bf16 v[32:35], v[214:217], v[230:233], v[32:35]
	v_mfma_f32_16x16x32_bf16 v[20:23], v[192:195], v[238:241], v[20:23]
	v_mfma_f32_16x16x32_bf16 v[16:19], v[214:217], v[238:241], v[16:19]
	v_mfma_f32_16x16x32_bf16 v[4:7], v[192:195], v[246:249], v[4:7]
	v_mfma_f32_16x16x32_bf16 v[0:3], v[214:217], v[246:249], v[0:3]
	s_setprio 0
	s_barrier
	s_cbranch_scc0 .LBB0_621
